# packed f32 VALU ops (v_pk_mul/add/fma_f32) in the FFN-up conv/SiLU epilogue and the attention loops split into plain f32 ops (same arithmetic; packed ops issue slowly beside the partner wave's MFMAs)
# speedup vs baseline: 1.0089x; 1.0083x over previous
; #define GAS __attribute__((address_space(1)))
; DI unsigned pk2(float a, float b) { f32x2 v = {a, b}; bf2_t r = __builtin_convertvector(v, bf2_t); return __builtin_bit_cast(unsigned, r); }
; DI float bflo(unsigned w) { return __uint_as_float(w << 16); }
; DI float bfhi(unsigned w) { return __uint_as_float(w & 0xffff0000u); }
; __global__ void __launch_bounds__(256, 2) fwd_kernel(Params p) {
;     ...
;           ss += __shfl_xor(ss, 32);
;           const float rinv = rsqrtf(ss * (1.f / 128.f) + 1e-6f) * 0.8f;
;           const float* subg = pp->in[18];
; #pragma unroll
;           for (int t = 0; t < 4; ++t)
; #pragma unroll
;             for (int g = 0; g < 4; ++g) {
;               bf16_t* a = outp + 32 * t + 8 * g + 4 * h;
;               const u32x2 w = *(const GAS u32x2*)a;
;               const f32x4 g4 = *(const GAS f32x4*)(subg + 32 * t + 8 * g + 4 * h);
;               u32x2 o; o.x = pk2(bflo(w.x) * rinv * g4[0], bfhi(w.x) * rinv * g4[1]); o.y = pk2(bflo(w.y) * rinv * g4[2], bfhi(w.y) * rinv * g4[3]);
;               *(GAS u32x2*)a = o;
;             }
.LBB0_28:
	ds_bpermute_b32 v0, v115, v98
	s_mov_b32 s10, 0x800000
	s_load_dwordx2 s[12:13], s[8:9], 0x90
	s_waitcnt lgkmcnt(0)
	v_add_f32_e32 v0, v98, v0
	v_fmamk_f32 v0, v0, 0x3c000000, v186
	v_cmp_gt_f32_e32 vcc, s10, v0
	v_mul_f32_e32 v2, 0x4b800000, v0
	v_readlane_b32 s10, v252, 12
	v_cndmask_b32_e32 v0, v0, v2, vcc
	v_rsq_f32_e32 v0, v0
	s_add_i32 s22, s22, s10
	v_readlane_b32 s10, v252, 14
	s_cmp_ge_i32 s22, s10
	v_mul_f32_e32 v2, 0x45800000, v0
	v_cndmask_b32_e32 v0, v0, v2, vcc
	v_lshlrev_b32_e32 v2, 2, v112
	global_load_dwordx2 v[8:9], v[146:147], off
	global_load_dwordx4 v[4:7], v2, s[12:13]
	v_mul_f32_e32 v0, 0x3f4ccccd, v0
	s_waitcnt vmcnt(1)
	v_lshlrev_b32_e32 v10, 16, v8
	v_and_b32_e32 v11, 0xffff0000, v8
	v_lshlrev_b32_e32 v8, 16, v9
	v_and_b32_e32 v9, 0xffff0000, v9
	v_mul_f32_e32 v10, v0, v10
	v_mul_f32_e32 v11, v0, v11
	v_mul_f32_e32 v8, v0, v8
	v_mul_f32_e32 v9, v0, v9
	s_waitcnt vmcnt(0)
	v_mul_f32_e32 v4, v4, v10
	v_mul_f32_e32 v5, v5, v11
	v_mul_f32_e32 v6, v6, v8
	v_mul_f32_e32 v7, v7, v9
	v_cvt_pk_bf16_f32 v4, v4, v5
	v_cvt_pk_bf16_f32 v5, v6, v7
	global_store_dwordx2 v[146:147], v[4:5], off
	global_load_dwordx2 v[8:9], v[146:147], off offset:16
	s_nop 0
	global_load_dwordx4 v[4:7], v2, s[12:13] offset:32
	s_waitcnt vmcnt(1)
	v_lshlrev_b32_e32 v10, 16, v8
	v_and_b32_e32 v11, 0xffff0000, v8
	v_lshlrev_b32_e32 v8, 16, v9
	v_and_b32_e32 v9, 0xffff0000, v9
	v_mul_f32_e32 v10, v0, v10
	v_mul_f32_e32 v11, v0, v11
	v_mul_f32_e32 v8, v0, v8
	v_mul_f32_e32 v9, v0, v9
	s_waitcnt vmcnt(0)
	v_mul_f32_e32 v4, v4, v10
	v_mul_f32_e32 v5, v5, v11
	v_mul_f32_e32 v6, v6, v8
	v_mul_f32_e32 v7, v7, v9
	v_cvt_pk_bf16_f32 v4, v4, v5
	v_cvt_pk_bf16_f32 v5, v6, v7
	global_store_dwordx2 v[146:147], v[4:5], off offset:16
	global_load_dwordx2 v[8:9], v[146:147], off offset:32
	s_nop 0
	global_load_dwordx4 v[4:7], v2, s[12:13] offset:64
	s_waitcnt vmcnt(1)
	v_lshlrev_b32_e32 v10, 16, v8
	v_and_b32_e32 v11, 0xffff0000, v8
	v_lshlrev_b32_e32 v8, 16, v9
	v_and_b32_e32 v9, 0xffff0000, v9
	v_mul_f32_e32 v10, v0, v10
	v_mul_f32_e32 v11, v0, v11
	v_mul_f32_e32 v8, v0, v8
	v_mul_f32_e32 v9, v0, v9
	s_waitcnt vmcnt(0)
	v_mul_f32_e32 v4, v4, v10
	v_mul_f32_e32 v5, v5, v11
	v_mul_f32_e32 v6, v6, v8
	v_mul_f32_e32 v7, v7, v9
	v_cvt_pk_bf16_f32 v4, v4, v5
	v_cvt_pk_bf16_f32 v5, v6, v7
	global_store_dwordx2 v[146:147], v[4:5], off offset:32
	global_load_dwordx2 v[8:9], v[146:147], off offset:48
	s_nop 0
	global_load_dwordx4 v[4:7], v2, s[12:13] offset:96
	s_waitcnt vmcnt(1)
	v_lshlrev_b32_e32 v10, 16, v8
	v_and_b32_e32 v11, 0xffff0000, v8
	v_lshlrev_b32_e32 v8, 16, v9
	v_and_b32_e32 v9, 0xffff0000, v9
	v_mul_f32_e32 v10, v0, v10
	v_mul_f32_e32 v11, v0, v11
	v_mul_f32_e32 v8, v0, v8
	v_mul_f32_e32 v9, v0, v9
	s_waitcnt vmcnt(0)
	v_mul_f32_e32 v4, v4, v10
	v_mul_f32_e32 v5, v5, v11
	v_mul_f32_e32 v6, v6, v8
	v_mul_f32_e32 v7, v7, v9
	v_cvt_pk_bf16_f32 v4, v4, v5
	v_cvt_pk_bf16_f32 v5, v6, v7
	global_store_dwordx2 v[146:147], v[4:5], off offset:48
	global_load_dwordx2 v[8:9], v[146:147], off offset:64
	s_nop 0
	global_load_dwordx4 v[4:7], v2, s[12:13] offset:128
	s_waitcnt vmcnt(1)
	v_lshlrev_b32_e32 v10, 16, v8
	v_and_b32_e32 v11, 0xffff0000, v8
	v_lshlrev_b32_e32 v8, 16, v9
	v_and_b32_e32 v9, 0xffff0000, v9
	v_mul_f32_e32 v10, v0, v10
	v_mul_f32_e32 v11, v0, v11
	v_mul_f32_e32 v8, v0, v8
	v_mul_f32_e32 v9, v0, v9
	s_waitcnt vmcnt(0)
	v_mul_f32_e32 v4, v4, v10
	v_mul_f32_e32 v5, v5, v11
	v_mul_f32_e32 v6, v6, v8
	v_mul_f32_e32 v7, v7, v9
	v_cvt_pk_bf16_f32 v4, v4, v5
	v_cvt_pk_bf16_f32 v5, v6, v7
	global_store_dwordx2 v[146:147], v[4:5], off offset:64
	global_load_dwordx2 v[8:9], v[146:147], off offset:80
	s_nop 0
	global_load_dwordx4 v[4:7], v2, s[12:13] offset:160
	s_waitcnt vmcnt(1)
	v_lshlrev_b32_e32 v10, 16, v8
	v_and_b32_e32 v11, 0xffff0000, v8
	v_lshlrev_b32_e32 v8, 16, v9
	v_and_b32_e32 v9, 0xffff0000, v9
	v_mul_f32_e32 v10, v0, v10
	v_mul_f32_e32 v11, v0, v11
	v_mul_f32_e32 v8, v0, v8
	v_mul_f32_e32 v9, v0, v9
	s_waitcnt vmcnt(0)
	v_mul_f32_e32 v4, v4, v10
	v_mul_f32_e32 v5, v5, v11
	v_mul_f32_e32 v6, v6, v8
	v_mul_f32_e32 v7, v7, v9
	v_cvt_pk_bf16_f32 v4, v4, v5
	v_cvt_pk_bf16_f32 v5, v6, v7
	global_store_dwordx2 v[146:147], v[4:5], off offset:80
	global_load_dwordx2 v[8:9], v[146:147], off offset:96
	s_nop 0
	global_load_dwordx4 v[4:7], v2, s[12:13] offset:192
	s_waitcnt vmcnt(1)
	v_lshlrev_b32_e32 v10, 16, v8
	v_and_b32_e32 v11, 0xffff0000, v8
	v_lshlrev_b32_e32 v8, 16, v9
	v_and_b32_e32 v9, 0xffff0000, v9
	v_mul_f32_e32 v10, v0, v10
	v_mul_f32_e32 v11, v0, v11
	v_mul_f32_e32 v8, v0, v8
	v_mul_f32_e32 v9, v0, v9
	s_waitcnt vmcnt(0)
	v_mul_f32_e32 v4, v4, v10
	v_mul_f32_e32 v5, v5, v11
	v_mul_f32_e32 v6, v6, v8
	v_mul_f32_e32 v7, v7, v9
	v_cvt_pk_bf16_f32 v4, v4, v5
	v_cvt_pk_bf16_f32 v5, v6, v7
	global_store_dwordx2 v[146:147], v[4:5], off offset:96
	global_load_dwordx2 v[8:9], v[146:147], off offset:112
	s_nop 0
	global_load_dwordx4 v[4:7], v2, s[12:13] offset:224
	s_waitcnt vmcnt(1)
	v_lshlrev_b32_e32 v10, 16, v8
	v_and_b32_e32 v11, 0xffff0000, v8
	v_lshlrev_b32_e32 v8, 16, v9
	v_and_b32_e32 v9, 0xffff0000, v9
	v_mul_f32_e32 v10, v0, v10
	v_mul_f32_e32 v11, v0, v11
	v_mul_f32_e32 v8, v0, v8
	v_mul_f32_e32 v9, v0, v9
	s_waitcnt vmcnt(0)
; #define GAS __attribute__((address_space(1)))
; DI unsigned pk2(float a, float b) { f32x2 v = {a, b}; bf2_t r = __builtin_convertvector(v, bf2_t); return __builtin_bit_cast(unsigned, r); }
; DI float bflo(unsigned w) { return __uint_as_float(w << 16); }
; DI float bfhi(unsigned w) { return __uint_as_float(w & 0xffff0000u); }
; __global__ void __launch_bounds__(256, 2) fwd_kernel(Params p) {
;     ...
; #pragma unroll
;           for (int t = 0; t < 4; ++t)
; #pragma unroll
;             for (int g = 0; g < 4; ++g) {
;               bf16_t* a = outp + 32 * t + 8 * g + 4 * h;
;               const u32x2 w = *(const GAS u32x2*)a;
;               const f32x4 g4 = *(const GAS f32x4*)(subg + 32 * t + 8 * g + 4 * h);
;               u32x2 o; o.x = pk2(bflo(w.x) * rinv * g4[0], bfhi(w.x) * rinv * g4[1]); o.y = pk2(bflo(w.y) * rinv * g4[2], bfhi(w.y) * rinv * g4[3]);
;               *(GAS u32x2*)a = o;
;             }
	v_mul_f32_e32 v4, v4, v10
	v_mul_f32_e32 v5, v5, v11
	v_mul_f32_e32 v6, v6, v8
	v_mul_f32_e32 v7, v7, v9
	v_cvt_pk_bf16_f32 v4, v4, v5
	v_cvt_pk_bf16_f32 v5, v6, v7
	global_store_dwordx2 v[146:147], v[4:5], off offset:112
	global_load_dwordx2 v[8:9], v[146:147], off offset:128
	s_nop 0
	global_load_dwordx4 v[4:7], v2, s[12:13] offset:256
	s_waitcnt vmcnt(1)
	v_lshlrev_b32_e32 v10, 16, v8
	v_and_b32_e32 v11, 0xffff0000, v8
	v_lshlrev_b32_e32 v8, 16, v9
	v_and_b32_e32 v9, 0xffff0000, v9
	v_mul_f32_e32 v10, v0, v10
	v_mul_f32_e32 v11, v0, v11
	v_mul_f32_e32 v8, v0, v8
	v_mul_f32_e32 v9, v0, v9
	s_waitcnt vmcnt(0)
	v_mul_f32_e32 v4, v4, v10
	v_mul_f32_e32 v5, v5, v11
	v_mul_f32_e32 v6, v6, v8
	v_mul_f32_e32 v7, v7, v9
	v_cvt_pk_bf16_f32 v4, v4, v5
	v_cvt_pk_bf16_f32 v5, v6, v7
	global_store_dwordx2 v[146:147], v[4:5], off offset:128
	global_load_dwordx2 v[8:9], v[146:147], off offset:144
	s_nop 0
	global_load_dwordx4 v[4:7], v2, s[12:13] offset:288
	s_waitcnt vmcnt(1)
	v_lshlrev_b32_e32 v10, 16, v8
	v_and_b32_e32 v11, 0xffff0000, v8
	v_lshlrev_b32_e32 v8, 16, v9
	v_and_b32_e32 v9, 0xffff0000, v9
	v_mul_f32_e32 v10, v0, v10
	v_mul_f32_e32 v11, v0, v11
	v_mul_f32_e32 v8, v0, v8
	v_mul_f32_e32 v9, v0, v9
	s_waitcnt vmcnt(0)
	v_mul_f32_e32 v4, v4, v10
	v_mul_f32_e32 v5, v5, v11
	v_mul_f32_e32 v6, v6, v8
	v_mul_f32_e32 v7, v7, v9
	v_cvt_pk_bf16_f32 v4, v4, v5
	v_cvt_pk_bf16_f32 v5, v6, v7
	global_store_dwordx2 v[146:147], v[4:5], off offset:144
	global_load_dwordx2 v[8:9], v[146:147], off offset:160
	s_nop 0
	global_load_dwordx4 v[4:7], v2, s[12:13] offset:320
	s_waitcnt vmcnt(1)
	v_lshlrev_b32_e32 v10, 16, v8
	v_and_b32_e32 v11, 0xffff0000, v8
	v_lshlrev_b32_e32 v8, 16, v9
	v_and_b32_e32 v9, 0xffff0000, v9
	v_mul_f32_e32 v10, v0, v10
	v_mul_f32_e32 v11, v0, v11
	v_mul_f32_e32 v8, v0, v8
	v_mul_f32_e32 v9, v0, v9
	s_waitcnt vmcnt(0)
	v_mul_f32_e32 v4, v4, v10
	v_mul_f32_e32 v5, v5, v11
	v_mul_f32_e32 v6, v6, v8
	v_mul_f32_e32 v7, v7, v9
	v_cvt_pk_bf16_f32 v4, v4, v5
	v_cvt_pk_bf16_f32 v5, v6, v7
	global_store_dwordx2 v[146:147], v[4:5], off offset:160
	global_load_dwordx2 v[8:9], v[146:147], off offset:176
	s_nop 0
	global_load_dwordx4 v[4:7], v2, s[12:13] offset:352
	s_waitcnt vmcnt(1)
	v_lshlrev_b32_e32 v10, 16, v8
	v_and_b32_e32 v11, 0xffff0000, v8
	v_lshlrev_b32_e32 v8, 16, v9
	v_and_b32_e32 v9, 0xffff0000, v9
	v_mul_f32_e32 v10, v0, v10
	v_mul_f32_e32 v11, v0, v11
	v_mul_f32_e32 v8, v0, v8
	v_mul_f32_e32 v9, v0, v9
	s_waitcnt vmcnt(0)
	v_mul_f32_e32 v4, v4, v10
	v_mul_f32_e32 v5, v5, v11
	v_mul_f32_e32 v6, v6, v8
	v_mul_f32_e32 v7, v7, v9
	v_cvt_pk_bf16_f32 v4, v4, v5
	v_cvt_pk_bf16_f32 v5, v6, v7
	global_store_dwordx2 v[146:147], v[4:5], off offset:176
	global_load_dwordx2 v[8:9], v[146:147], off offset:192
	s_nop 0
	global_load_dwordx4 v[4:7], v2, s[12:13] offset:384
	s_waitcnt vmcnt(1)
	v_lshlrev_b32_e32 v10, 16, v8
	v_and_b32_e32 v11, 0xffff0000, v8
	v_lshlrev_b32_e32 v8, 16, v9
	v_and_b32_e32 v9, 0xffff0000, v9
	v_mul_f32_e32 v10, v0, v10
	v_mul_f32_e32 v11, v0, v11
	v_mul_f32_e32 v8, v0, v8
	v_mul_f32_e32 v9, v0, v9
	s_waitcnt vmcnt(0)
	v_mul_f32_e32 v4, v4, v10
	v_mul_f32_e32 v5, v5, v11
	v_mul_f32_e32 v6, v6, v8
	v_mul_f32_e32 v7, v7, v9
	v_cvt_pk_bf16_f32 v4, v4, v5
	v_cvt_pk_bf16_f32 v5, v6, v7
	global_store_dwordx2 v[146:147], v[4:5], off offset:192
	global_load_dwordx2 v[8:9], v[146:147], off offset:208
	s_nop 0
	global_load_dwordx4 v[4:7], v2, s[12:13] offset:416
	s_waitcnt vmcnt(1)
	v_lshlrev_b32_e32 v10, 16, v8
	v_and_b32_e32 v11, 0xffff0000, v8
	v_lshlrev_b32_e32 v8, 16, v9
	v_and_b32_e32 v9, 0xffff0000, v9
	v_mul_f32_e32 v10, v0, v10
	v_mul_f32_e32 v11, v0, v11
	v_mul_f32_e32 v8, v0, v8
	v_mul_f32_e32 v9, v0, v9
	s_waitcnt vmcnt(0)
	v_mul_f32_e32 v4, v4, v10
	v_mul_f32_e32 v5, v5, v11
	v_mul_f32_e32 v6, v6, v8
	v_mul_f32_e32 v7, v7, v9
	v_cvt_pk_bf16_f32 v4, v4, v5
	v_cvt_pk_bf16_f32 v5, v6, v7
	global_store_dwordx2 v[146:147], v[4:5], off offset:208
	global_load_dwordx2 v[8:9], v[146:147], off offset:224
	s_nop 0
	global_load_dwordx4 v[4:7], v2, s[12:13] offset:448
	s_waitcnt vmcnt(1)
	v_lshlrev_b32_e32 v10, 16, v8
	v_and_b32_e32 v11, 0xffff0000, v8
	v_lshlrev_b32_e32 v8, 16, v9
	v_and_b32_e32 v9, 0xffff0000, v9
	v_mul_f32_e32 v10, v0, v10
	v_mul_f32_e32 v11, v0, v11
	v_mul_f32_e32 v8, v0, v8
	v_mul_f32_e32 v9, v0, v9
	s_waitcnt vmcnt(0)
	v_mul_f32_e32 v4, v4, v10
	v_mul_f32_e32 v5, v5, v11
	v_mul_f32_e32 v6, v6, v8
	v_mul_f32_e32 v7, v7, v9
	v_cvt_pk_bf16_f32 v4, v4, v5
	v_cvt_pk_bf16_f32 v5, v6, v7
	global_store_dwordx2 v[146:147], v[4:5], off offset:224
	global_load_dwordx2 v[6:7], v[146:147], off offset:240
	s_nop 0
	global_load_dwordx4 v[2:5], v2, s[12:13] offset:480
	s_waitcnt vmcnt(1)
	v_lshlrev_b32_e32 v8, 16, v6
	v_and_b32_e32 v9, 0xffff0000, v6
	v_lshlrev_b32_e32 v6, 16, v7
	v_and_b32_e32 v7, 0xffff0000, v7
	v_mul_f32_e32 v8, v0, v8
	v_mul_f32_e32 v9, v0, v9
	v_mul_f32_e32 v6, v0, v6
	v_mul_f32_e32 v7, v0, v7
	s_waitcnt vmcnt(0)
	v_mul_f32_e32 v2, v2, v8
	v_mul_f32_e32 v3, v3, v9
	v_mul_f32_e32 v4, v4, v6
	v_mul_f32_e32 v5, v5, v7
	v_cvt_pk_bf16_f32 v2, v2, v3
	v_cvt_pk_bf16_f32 v3, v4, v5
	global_store_dwordx2 v[146:147], v[2:3], off offset:240
	s_cbranch_scc1 .LBB0_53

; #define GAS __attribute__((address_space(1)))
; DI unsigned pk2(float a, float b) { f32x2 v = {a, b}; bf2_t r = __builtin_convertvector(v, bf2_t); return __builtin_bit_cast(unsigned, r); }
; DI float bf2f(unsigned short v) { return __uint_as_float(((unsigned)v) << 16); }
; template <int DQK, int ROFF, int RDIM>
; DI void load_q(bf16x8 (&qf)[DQK / 16], const bf16_t* __restrict__ qrowp, int h, bool rope, const f32x2* __restrict__ cs  ) {
; #pragma unroll
;   for (int kk = 0; kk < DQK / 16; ++kk) qf[kk] = *(const GAS bf16x8*)(qrowp + kk * 16 + h * 8);
;   if (rope) {
;     constexpr int NP = RDIM / 32;
; #pragma unroll
;     for (int p = 0; p < NP; ++p) {
;       const int ka = ROFF / 16 + p, kb = ka + NP;
;       bf16x8 xa = qf[ka], xb = qf[kb];
;       u32x4 oa, ob;
; #pragma unroll
;       for (int j2 = 0; j2 < 4; ++j2) {
;         float o1[2], o2[2];
; #pragma unroll
;         for (int q = 0; q < 2; ++q) {
;           const int j = 2 * j2 + q;
;           const f32x2 csv = cs[16 * p + 8 * h + j];
;           const float x1 = bf2f((unsigned short)xa[j]), x2 = bf2f((unsigned short)xb[j]);
;           o1[q] = x1 * csv.x - x2 * csv.y; o2[q] = x1 * csv.y + x2 * csv.x;
;         }
;         oa[j2] = pk2(o1[0], o1[1]); ob[j2] = pk2(o2[0], o2[1]);
;       }
;       qf[ka] = __builtin_bit_cast(bf16x8, oa); qf[kb] = __builtin_bit_cast(bf16x8, ob);
;     }
;   }
.LBB0_38:
	v_lshl_add_u64 v[2:3], s[16:17], 1, v[150:151]
	global_load_dwordx4 v[14:17], v[2:3], off
	global_load_dwordx4 v[6:9], v[2:3], off offset:32
	global_load_dwordx4 v[10:13], v[2:3], off offset:64
	s_nop 0
	global_load_dwordx4 v[2:5], v[2:3], off offset:96
	s_andn2_b64 vcc, exec, s[12:13]
	s_cbranch_vccnz .LBB0_40
	flat_load_dwordx4 v[18:21], v[148:149]
	s_waitcnt vmcnt(0)
	v_and_b32_e32 v25, 0xffff0000, v10
	v_lshlrev_b32_e32 v24, 16, v10
	v_and_b32_e32 v23, 0xffff0000, v14
	v_lshlrev_b32_e32 v22, 16, v14
	s_waitcnt lgkmcnt(0)
	v_mov_b32_e32 v26, v19
	v_mov_b32_e32 v27, v21
	v_mov_b32_e32 v19, v20
	v_mul_f32_e32 v20, v18, v24
	v_mul_f32_e32 v21, v19, v25
	v_mul_f32_e32 v24, v26, v24
	v_mul_f32_e32 v25, v27, v25
	v_fma_f32 v20, v26, v22, v20
	v_fma_f32 v21, v27, v23, v21
	v_fma_f32 v18, v18, v22, -v24
	v_fma_f32 v19, v19, v23, -v25
	v_cvt_pk_bf16_f32 v10, v20, v21
	v_cvt_pk_bf16_f32 v14, v18, v19
	flat_load_dwordx4 v[18:21], v[148:149] offset:16
	v_and_b32_e32 v25, 0xffff0000, v11
	v_lshlrev_b32_e32 v24, 16, v11
	v_and_b32_e32 v23, 0xffff0000, v15
	v_lshlrev_b32_e32 v22, 16, v15
	s_waitcnt vmcnt(0) lgkmcnt(0)
	v_mov_b32_e32 v26, v19
	v_mov_b32_e32 v27, v21
	v_mov_b32_e32 v19, v20
	v_mul_f32_e32 v20, v18, v24
	v_mul_f32_e32 v21, v19, v25
	v_mul_f32_e32 v24, v26, v24
	v_mul_f32_e32 v25, v27, v25
	v_fma_f32 v20, v26, v22, v20
	v_fma_f32 v21, v27, v23, v21
	v_fma_f32 v18, v18, v22, -v24
	v_fma_f32 v19, v19, v23, -v25
	v_cvt_pk_bf16_f32 v11, v20, v21
	v_cvt_pk_bf16_f32 v15, v18, v19
	flat_load_dwordx4 v[18:21], v[148:149] offset:32
	v_and_b32_e32 v25, 0xffff0000, v12
	v_lshlrev_b32_e32 v24, 16, v12
	v_and_b32_e32 v23, 0xffff0000, v16
	v_lshlrev_b32_e32 v22, 16, v16
	s_waitcnt vmcnt(0) lgkmcnt(0)
	v_mov_b32_e32 v26, v19
	v_mov_b32_e32 v27, v21
	v_mov_b32_e32 v19, v20
	v_mul_f32_e32 v20, v18, v24
	v_mul_f32_e32 v21, v19, v25
	v_mul_f32_e32 v24, v26, v24
	v_mul_f32_e32 v25, v27, v25
	v_fma_f32 v20, v26, v22, v20
	v_fma_f32 v21, v27, v23, v21
	v_fma_f32 v18, v18, v22, -v24
	v_fma_f32 v19, v19, v23, -v25
	v_cvt_pk_bf16_f32 v12, v20, v21
	v_cvt_pk_bf16_f32 v16, v18, v19
	flat_load_dwordx4 v[18:21], v[148:149] offset:48
	v_and_b32_e32 v25, 0xffff0000, v13
	v_lshlrev_b32_e32 v24, 16, v13
	v_and_b32_e32 v23, 0xffff0000, v17
	v_lshlrev_b32_e32 v22, 16, v17
	s_waitcnt vmcnt(0) lgkmcnt(0)
	v_mov_b32_e32 v26, v19
	v_mov_b32_e32 v27, v21
	v_mov_b32_e32 v19, v20
	v_mul_f32_e32 v20, v18, v24
	v_mul_f32_e32 v21, v19, v25
	v_mul_f32_e32 v24, v26, v24
	v_mul_f32_e32 v25, v27, v25
	v_fma_f32 v20, v26, v22, v20
	v_fma_f32 v21, v27, v23, v21
	v_fma_f32 v18, v18, v22, -v24
	v_fma_f32 v19, v19, v23, -v25
	v_cvt_pk_bf16_f32 v13, v20, v21
	v_cvt_pk_bf16_f32 v17, v18, v19
	flat_load_dwordx4 v[18:21], v[148:149] offset:128
	v_and_b32_e32 v25, 0xffff0000, v2
	v_lshlrev_b32_e32 v24, 16, v2
	v_and_b32_e32 v23, 0xffff0000, v6
	v_lshlrev_b32_e32 v22, 16, v6
	s_waitcnt vmcnt(0) lgkmcnt(0)
	v_mov_b32_e32 v26, v19
	v_mov_b32_e32 v27, v21
	v_mov_b32_e32 v19, v20
	v_mul_f32_e32 v20, v18, v24
	v_mul_f32_e32 v21, v19, v25
	v_mul_f32_e32 v24, v26, v24
	v_mul_f32_e32 v25, v27, v25
	v_fma_f32 v20, v26, v22, v20
	v_fma_f32 v21, v27, v23, v21
	v_fma_f32 v18, v18, v22, -v24
	v_fma_f32 v19, v19, v23, -v25
	v_cvt_pk_bf16_f32 v2, v20, v21
	v_cvt_pk_bf16_f32 v6, v18, v19
	flat_load_dwordx4 v[18:21], v[148:149] offset:144
	v_and_b32_e32 v25, 0xffff0000, v3
	v_lshlrev_b32_e32 v24, 16, v3
	v_and_b32_e32 v23, 0xffff0000, v7
	v_lshlrev_b32_e32 v22, 16, v7
	s_waitcnt vmcnt(0) lgkmcnt(0)
	v_mov_b32_e32 v26, v19
	v_mov_b32_e32 v27, v21
	v_mov_b32_e32 v19, v20
	v_mul_f32_e32 v20, v18, v24
	v_mul_f32_e32 v21, v19, v25
	v_mul_f32_e32 v24, v26, v24
	v_mul_f32_e32 v25, v27, v25
	v_fma_f32 v20, v26, v22, v20
	v_fma_f32 v21, v27, v23, v21
	v_fma_f32 v18, v18, v22, -v24
	v_fma_f32 v19, v19, v23, -v25
	v_cvt_pk_bf16_f32 v3, v20, v21
	v_cvt_pk_bf16_f32 v7, v18, v19
	flat_load_dwordx4 v[18:21], v[148:149] offset:160
	v_and_b32_e32 v25, 0xffff0000, v4
	v_lshlrev_b32_e32 v24, 16, v4
	v_and_b32_e32 v23, 0xffff0000, v8
	v_lshlrev_b32_e32 v22, 16, v8
	s_waitcnt vmcnt(0) lgkmcnt(0)
	v_mov_b32_e32 v26, v19
	v_mov_b32_e32 v27, v21
	v_mov_b32_e32 v19, v20
	v_mul_f32_e32 v20, v18, v24
	v_mul_f32_e32 v21, v19, v25
	v_mul_f32_e32 v24, v26, v24
	v_mul_f32_e32 v25, v27, v25
	v_fma_f32 v20, v26, v22, v20
	v_fma_f32 v21, v27, v23, v21
	v_fma_f32 v18, v18, v22, -v24
	v_fma_f32 v19, v19, v23, -v25
	v_cvt_pk_bf16_f32 v4, v20, v21
	v_cvt_pk_bf16_f32 v8, v18, v19
	flat_load_dwordx4 v[18:21], v[148:149] offset:176
	v_and_b32_e32 v25, 0xffff0000, v5
	v_lshlrev_b32_e32 v24, 16, v5
	v_and_b32_e32 v23, 0xffff0000, v9
	v_lshlrev_b32_e32 v22, 16, v9
	s_waitcnt vmcnt(0) lgkmcnt(0)
	v_mov_b32_e32 v26, v19
	v_mov_b32_e32 v27, v21
	v_mov_b32_e32 v19, v20
	v_mul_f32_e32 v20, v18, v24
	v_mul_f32_e32 v21, v19, v25
	v_mul_f32_e32 v24, v26, v24
	v_mul_f32_e32 v25, v27, v25
	v_fma_f32 v20, v26, v22, v20
	v_fma_f32 v21, v27, v23, v21
	v_fma_f32 v18, v18, v22, -v24
	v_fma_f32 v19, v19, v23, -v25
	v_cvt_pk_bf16_f32 v5, v20, v21
	v_cvt_pk_bf16_f32 v9, v18, v19

; DI f32x16 mfma32(bf16x8 a, bf16x8 b, f32x16 c) { return __builtin_amdgcn_mfma_f32_32x32x16_bf16(a, b, c, 0, 0, 0); }
; DI int crow(int reg, int h) { return (reg & 3) + 8 * (reg >> 2) + 4 * h; }
; template <int DQK, int DV, int KW0, int MODE> ...
;     ...
;         kfa[kk] = *(const bf16x8*)(cur + r * (KS * 2) + kk * 32 + h * 16);
;         kfb[kk] = *(const bf16x8*)(cur + (32 + r) * (KS * 2) + kk * 32 + h * 16);
;         qv[kk] = QLDS ? *(const bf16x8*)(qbase + kk * 1024) : qf[kk];
;       }
; #pragma unroll
;       for (int kk = 0; kk < DQK / 16; ++kk) {
;         S0 = mfma32(kfa[kk], qv[kk], S0);
;         S1 = mfma32(kfb[kk], qv[kk], S1);
;       }
;       __builtin_amdgcn_sched_group_barrier(0x100, (QLDS ? 3 : 2) * (DQK / 16), 0);
;       __builtin_amdgcn_sched_group_barrier(0x008, 2 * (DQK / 16), 0);
;     }
;     if (MODE == 2) {
;       if (it >= 4) {
;         const int w = wlo + it - 4;
;         if (w < 2 || w > 3) {
;           const int kpos0 = (qn - 1) * 128 + 64 * w, qpos = qn * 128 + wid * 32 + r;
; #pragma unroll
;           for (int e = 0; e < 16; ++e) {
;             const int d0 = qpos - (kpos0 + crow(e, h)), d1 = d0 - 32;
;             if (d0 > 128 || d0 < -128) S0[e] = -1e30f;
;             if (d1 > 128 || d1 < -128) S1[e] = -1e30f;
;           }
;         }
;       }
;     }
;     float mx = S0[0];
; #pragma unroll
;     for (int e = 1; e < 16; ++e) mx = fmaxf(mx, S0[e]);
; #pragma unroll
;     for (int e = 0; e < 16; ++e) mx = fmaxf(mx, S1[e]);
;     mx = fmaxf(mx, __shfl_xor(mx, 32));
;     const float mn = fmaxf(m, mx);
;     const bool grow = __builtin_amdgcn_ballot_w64(mx > m) != 0ull;
;     const float alpha = __builtin_amdgcn_exp2f((m - mn) * c);
;     m = mn;
;     const float mc = mn * c;
;     float ps = 0.f;
; #pragma unroll
;     for (int e = 0; e < 16; ++e) { S0[e] = __builtin_amdgcn_exp2f(S0[e] * c - mc); ps += S0[e]; }
; #pragma unroll
;     for (int e = 0; e < 16; ++e) { S1[e] = __builtin_amdgcn_exp2f(S1[e] * c - mc); ps += S1[e]; }
;     if (grow) {
;       l *= alpha;
; #pragma unroll
;       for (int t = 0; t < DV / 32; ++t)
; #pragma unroll
;         for (int e = 0; e < 16; ++e) O[t][e] *= alpha;
;     }
;     ...
;         PV_TILE_(0); PV_TILE_(1); PV_TILE_(2); PV_TILE_(3);
.LBB0_41:
	s_bitcmp1_b32 s41, 0
	s_cselect_b32 s10, 0x7400, 0
	s_add_i32 s47, s10, 16
	v_add3_u32 v0, s47, v176, v177
	ds_read_b128 v[10:13], v0
	ds_read_b128 v[6:9], v182 offset:59392
	ds_read_b128 v[192:195], v0 offset:32
	ds_read_b128 v[2:5], v0 offset:4608
	ds_read_b128 v[218:221], v0 offset:4640
	ds_read_b128 v[222:225], v182 offset:60416
	ds_read_b128 v[226:229], v0 offset:64
	ds_read_b128 v[230:233], v0 offset:4672
	ds_read_b128 v[234:237], v182 offset:61440
	ds_read_b128 v[238:241], v0 offset:96
	ds_read_b128 v[242:245], v0 offset:4704
	ds_read_b128 v[246:249], v182 offset:62464
	s_setprio 1
	s_waitcnt lgkmcnt(10)
	v_mfma_f32_32x32x16_bf16 v[96:111], v[10:13], v[6:9], 0
	s_waitcnt lgkmcnt(6)
	v_mfma_f32_32x32x16_bf16 v[96:111], v[192:195], v[222:225], v[96:111]
	v_mfma_f32_32x32x16_bf16 v[80:95], v[2:5], v[6:9], 0
	v_max_f32_e32 v3, v183, v183
	s_waitcnt lgkmcnt(3)
	v_mfma_f32_32x32x16_bf16 v[96:111], v[226:229], v[234:237], v[96:111]
	v_mfma_f32_32x32x16_bf16 v[80:95], v[218:221], v[222:225], v[80:95]
	s_waitcnt lgkmcnt(0)
	v_mfma_f32_32x32x16_bf16 v[96:111], v[238:241], v[246:249], v[96:111]
	v_mfma_f32_32x32x16_bf16 v[80:95], v[230:233], v[234:237], v[80:95]
	s_nop 10
	v_max_f32_e32 v0, v97, v97
	v_max_f32_e32 v2, v96, v96
	v_max_f32_e32 v0, v2, v0
	v_max3_f32 v0, v0, v98, v99
	v_max3_f32 v0, v0, v100, v101
	v_max3_f32 v0, v0, v102, v103
	v_max3_f32 v0, v0, v104, v105
	v_mfma_f32_32x32x16_bf16 v[80:95], v[242:245], v[246:249], v[80:95]
	s_setprio 0
	v_max3_f32 v0, v0, v106, v107
	v_max3_f32 v0, v0, v108, v109
	v_max3_f32 v0, v0, v110, v111
	s_nop 8
	v_max3_f32 v0, v0, v80, v81
	v_max3_f32 v0, v0, v82, v83
	v_max3_f32 v0, v0, v84, v85
	v_max3_f32 v0, v0, v86, v87
	v_max3_f32 v0, v0, v88, v89
	v_max3_f32 v0, v0, v90, v91
	v_max3_f32 v0, v0, v92, v93
	v_max3_f32 v0, v0, v94, v95
	ds_bpermute_b32 v2, v115, v0
	s_waitcnt lgkmcnt(0)
	v_max_f32_e32 v2, v2, v2
	v_max_f32_e32 v0, v0, v2
	v_max_f32_e32 v3, v3, v0
	v_cmp_gt_f32_e32 vcc, v0, v183
	s_cbranch_vccz .LBB0_43
	v_sub_f32_e32 v0, v183, v3
	v_mul_f32_e32 v0, 0x3e38aa3b, v0
	v_exp_f32_e32 v0, v0
	s_nop 0
	v_mul_f32_e32 v78, v0, v78
	v_mul_f32_e32 v79, v0, v79
	v_mul_f32_e32 v76, v0, v76
	v_mul_f32_e32 v77, v0, v77
	v_mul_f32_e32 v74, v0, v74
	v_mul_f32_e32 v75, v0, v75
	v_mul_f32_e32 v72, v0, v72
	v_mul_f32_e32 v73, v0, v73
	v_mul_f32_e32 v70, v0, v70
	v_mul_f32_e32 v71, v0, v71
	v_mul_f32_e32 v68, v0, v68
	v_mul_f32_e32 v69, v0, v69
	v_mul_f32_e32 v66, v0, v66
	v_mul_f32_e32 v67, v0, v67
	v_mul_f32_e32 v64, v0, v64
	v_mul_f32_e32 v65, v0, v65
	v_mul_f32_e32 v62, v0, v62
	v_mul_f32_e32 v63, v0, v63
	v_mul_f32_e32 v60, v0, v60
	v_mul_f32_e32 v61, v0, v61
	v_mul_f32_e32 v58, v0, v58
	v_mul_f32_e32 v59, v0, v59
	v_mul_f32_e32 v56, v0, v56
	v_mul_f32_e32 v57, v0, v57
	v_mul_f32_e32 v54, v0, v54
	v_mul_f32_e32 v55, v0, v55
	v_mul_f32_e32 v52, v0, v52
	v_mul_f32_e32 v53, v0, v53
	v_mul_f32_e32 v50, v0, v50
	v_mul_f32_e32 v51, v0, v51
	v_mul_f32_e32 v48, v0, v48
	v_mul_f32_e32 v49, v0, v49
	v_mul_f32_e32 v46, v0, v46
	v_mul_f32_e32 v47, v0, v47
	v_mul_f32_e32 v44, v0, v44
	v_mul_f32_e32 v45, v0, v45
	v_mul_f32_e32 v42, v0, v42
	v_mul_f32_e32 v43, v0, v43
	v_mul_f32_e32 v40, v0, v40
	v_mul_f32_e32 v41, v0, v41
	v_mul_f32_e32 v38, v0, v38
	v_mul_f32_e32 v39, v0, v39
	v_mul_f32_e32 v36, v0, v36
	v_mul_f32_e32 v37, v0, v37
	v_mul_f32_e32 v34, v0, v34
	v_mul_f32_e32 v35, v0, v35
	v_mul_f32_e32 v32, v0, v32
	v_mul_f32_e32 v33, v0, v33
	v_mul_f32_e32 v30, v0, v30
	v_mul_f32_e32 v31, v0, v31
	v_mul_f32_e32 v28, v0, v28
	v_mul_f32_e32 v29, v0, v29
	v_mul_f32_e32 v26, v0, v26
	v_mul_f32_e32 v27, v0, v27
	v_mul_f32_e32 v24, v0, v24
	v_mul_f32_e32 v25, v0, v25
	v_mul_f32_e32 v22, v0, v22
	v_mul_f32_e32 v23, v0, v23
	v_mul_f32_e32 v20, v0, v20
	v_mul_f32_e32 v21, v0, v21
	v_mul_f32_e32 v18, v0, v18
	v_mul_f32_e32 v19, v0, v19
	v_mul_f32_e32 v16, v0, v16
	v_mul_f32_e32 v17, v0, v17
	v_mul_f32_e32 v145, v145, v0
.LBB0_43:
	v_mov_b32_e32 v2, v111
	v_mul_f32_e64 v184, v2, s88
	v_mul_f32_e64 v185, v3, s88
	s_addk_i32 s47, 0x2400
	v_fma_f32 v4, v98, s88, -v185
	v_exp_f32_e32 v111, v4
	v_fma_f32 v4, v99, s88, -v185
	v_exp_f32_e32 v183, v4
	v_fma_f32 v4, v100, s88, -v185
	v_exp_f32_e32 v100, v4
	v_fma_f32 v4, v101, s88, -v185
	v_exp_f32_e32 v101, v4
	v_fma_f32 v4, v102, s88, -v185
	v_exp_f32_e32 v102, v4
	v_fma_f32 v4, v103, s88, -v185
	v_exp_f32_e32 v103, v4
	v_fma_f32 v4, v104, s88, -v185
	v_exp_f32_e32 v104, v4
	v_fma_f32 v4, v105, s88, -v185
	v_exp_f32_e32 v105, v4
	v_fma_f32 v4, v106, s88, -v185
	v_exp_f32_e32 v106, v4
	v_fma_f32 v4, v107, s88, -v185
	v_exp_f32_e32 v107, v4
	v_fma_f32 v4, v108, s88, -v185
	v_exp_f32_e32 v108, v4
	v_fma_f32 v4, v109, s88, -v185
	v_exp_f32_e32 v109, v4
	v_fma_f32 v4, v110, s88, -v185
	v_exp_f32_e32 v110, v4
	v_sub_f32_e32 v4, v184, v185
	v_exp_f32_e32 v184, v4
	v_fma_f32 v4, v80, s88, -v185
	v_exp_f32_e32 v189, v4
	v_fma_f32 v4, v81, s88, -v185
	v_exp_f32_e32 v192, v4
	v_fma_f32 v4, v82, s88, -v185
	v_exp_f32_e32 v193, v4
	v_fma_f32 v4, v83, s88, -v185
	v_exp_f32_e32 v194, v4
	v_fma_f32 v4, v84, s88, -v185
	v_exp_f32_e32 v195, v4
	v_fma_f32 v4, v85, s88, -v185
	v_fma_f32 v0, v96, s88, -v185
	v_fma_f32 v2, v97, s88, -v185
	v_exp_f32_e32 v196, v4
	v_fma_f32 v4, v86, s88, -v185
	v_exp_f32_e32 v0, v0
	v_exp_f32_e32 v2, v2
	v_exp_f32_e32 v197, v4
	v_fma_f32 v4, v87, s88, -v185
	v_exp_f32_e32 v218, v4
	v_fma_f32 v4, v88, s88, -v185
	v_exp_f32_e32 v219, v4
	v_fma_f32 v4, v89, s88, -v185
	v_exp_f32_e32 v220, v4
	v_fma_f32 v4, v90, s88, -v185
	v_exp_f32_e32 v221, v4
	v_cvt_pk_bf16_f32 v4, v0, v2
	v_cvt_pk_bf16_f32 v5, v111, v183
	v_cvt_pk_bf16_f32 v6, v100, v101
	v_cvt_pk_bf16_f32 v7, v102, v103
	v_add_u32_e32 v222, s47, v178
	s_setprio 1
	ds_read_b64_tr_b16 v[84:85], v222 offset:0
	ds_read_b64_tr_b16 v[86:87], v222 offset:2560
	ds_read_b64_tr_b16 v[80:81], v222 offset:5120
	ds_read_b64_tr_b16 v[82:83], v222 offset:7680
	ds_read_b64_tr_b16 v[12:13], v222 offset:10240
	ds_read_b64_tr_b16 v[14:15], v222 offset:12800
	ds_read_b64_tr_b16 v[8:9], v222 offset:15360
	ds_read_b64_tr_b16 v[10:11], v222 offset:17920
	s_waitcnt lgkmcnt(0)
; DI unsigned pk2(float a, float b) { f32x2 v = {a, b}; bf2_t r = __builtin_convertvector(v, bf2_t); return __builtin_bit_cast(unsigned, r); }
; #define PV_TILE64_(T) do { TRV8_192_T##T(R, vaddr); \
;           _Pragma("unroll") for (int st = 0; st < 2; ++st) _Pragma("unroll") for (int s = 0; s < 2; ++s) { const int ix = (st * 2 + s) * 2; \
;             const bf16x8 va = __builtin_shufflevector(R[ix], R[ix + 1], 0, 1, 2, 3, 4, 5, 6, 7); O[T] = mfma32(va, pf[st][s], O[T]); } } while (0)
; template <int DQK, int DV, int KW0, int MODE> ...
;     ...
;     for (int e = 0; e < 16; ++e) { S0[e] = __builtin_amdgcn_exp2f(S0[e] * c - mc); ps += S0[e]; }
; #pragma unroll
;     for (int e = 0; e < 16; ++e) { S1[e] = __builtin_amdgcn_exp2f(S1[e] * c - mc); ps += S1[e]; }
;     if (grow) {
;       l *= alpha;
; #pragma unroll
;       for (int t = 0; t < DV / 32; ++t)
; #pragma unroll
;         for (int e = 0; e < 16; ++e) O[t][e] *= alpha;
;     }
;     l += ps;
;     bf16x8 pf[2][2];
; #pragma unroll
;     for (int s = 0; s < 2; ++s) {
;       u32x4 w0, w1;
;       w0.x = pk2(S0[8 * s + 0], S0[8 * s + 1]); w0.y = pk2(S0[8 * s + 2], S0[8 * s + 3]); w0.z = pk2(S0[8 * s + 4], S0[8 * s + 5]); w0.w = pk2(S0[8 * s + 6], S0[8 * s + 7]);
;       w1.x = pk2(S1[8 * s + 0], S1[8 * s + 1]); w1.y = pk2(S1[8 * s + 2], S1[8 * s + 3]); w1.z = pk2(S1[8 * s + 4], S1[8 * s + 5]); w1.w = pk2(S1[8 * s + 6], S1[8 * s + 7]);
;       pf[0][s] = __builtin_bit_cast(bf16x8, w0); pf[1][s] = __builtin_bit_cast(bf16x8, w1);
;     }
;     {
;       const unsigned vaddr = (unsigned)(size_t)(cur + KB) + (unsigned)((4 * h + ((lane & 15) >> 2)) * VSB + ((lane >> 4) & 1) * 32 + (lane & 3) * 8);
;       if (DV == 64) {
;         s16x4 R[8];
;     ...
;         PV_TILE64_(0); PV_TILE64_(1);
;     ...
;       } else {
;         s16x4 R[8];
;     ...
;         PV_TILE_(0); PV_TILE_(1); PV_TILE_(2); PV_TILE_(3);
;     ...
;       }
;     }
;     if (DV > 64) { __builtin_amdgcn_sched_barrier(0); if (more) attn_gload<DQK, DV, KW0, 3>(kreg, vreg, k0p, ldk0, k1p, ldk1, vp, ldv, key_tile_row<MODE>(it + 1, b, qn, wlo), tid); }
;     if (more) attn_sstore<DQK, DV>(kreg, vreg, smem + ((it + 1) & 1) * STG, tid);
;     __syncthreads();
;   }
	v_fma_f32 v88, v91, s88, -v185
	v_mfma_f32_32x32x16_bf16 v[64:79], v[84:87], v[4:7], v[64:79]
	v_fma_f32 v84, v92, s88, -v185
	v_exp_f32_e32 v224, v84
	v_cvt_pk_bf16_f32 v84, v104, v105
	v_cvt_pk_bf16_f32 v85, v106, v107
	v_cvt_pk_bf16_f32 v86, v108, v109
	v_cvt_pk_bf16_f32 v87, v110, v184
	v_exp_f32_e32 v223, v88
	v_fma_f32 v88, v94, s88, -v185
	v_mfma_f32_32x32x16_bf16 v[64:79], v[80:83], v[84:87], v[64:79]
	v_fma_f32 v80, v93, s88, -v185
	v_exp_f32_e32 v225, v80
	v_cvt_pk_bf16_f32 v80, v189, v192
	v_cvt_pk_bf16_f32 v81, v193, v194
	v_cvt_pk_bf16_f32 v82, v195, v196
	v_cvt_pk_bf16_f32 v83, v197, v218
	v_exp_f32_e32 v226, v88
	v_add_f32_e32 v0, 0, v0
	v_mfma_f32_32x32x16_bf16 v[64:79], v[12:15], v[80:83], v[64:79]
	v_fma_f32 v12, v95, s88, -v185
	v_exp_f32_e32 v185, v12
	v_cvt_pk_bf16_f32 v12, v219, v220
	v_cvt_pk_bf16_f32 v13, v221, v223
	v_cvt_pk_bf16_f32 v14, v224, v225
	v_cvt_pk_bf16_f32 v15, v226, v185
	v_add_f32_e32 v0, v2, v0
	v_add_f32_e32 v0, v111, v0
	v_mfma_f32_32x32x16_bf16 v[64:79], v[8:11], v[12:15], v[64:79]
	ds_read_b64_tr_b16 v[96:97], v222 offset:64
	ds_read_b64_tr_b16 v[98:99], v222 offset:2624
	ds_read_b64_tr_b16 v[92:93], v222 offset:5184
	ds_read_b64_tr_b16 v[94:95], v222 offset:7744
	ds_read_b64_tr_b16 v[88:89], v222 offset:10304
	ds_read_b64_tr_b16 v[90:91], v222 offset:12864
	ds_read_b64_tr_b16 v[8:9], v222 offset:15424
	ds_read_b64_tr_b16 v[10:11], v222 offset:17984
	s_waitcnt lgkmcnt(0)
	v_add_f32_e32 v0, v183, v0
	v_add_f32_e32 v0, v100, v0
	v_add_f32_e32 v0, v101, v0
	v_add_f32_e32 v0, v102, v0
	v_add_f32_e32 v0, v103, v0
	v_add_f32_e32 v0, v104, v0
	v_mfma_f32_32x32x16_bf16 v[48:63], v[96:99], v[4:7], v[48:63]
	v_add_f32_e32 v0, v105, v0
	v_add_f32_e32 v0, v106, v0
	v_add_f32_e32 v0, v107, v0
	v_add_f32_e32 v0, v108, v0
	v_add_f32_e32 v0, v109, v0
	v_add_f32_e32 v0, v110, v0
	v_add_f32_e32 v0, v184, v0
	v_mfma_f32_32x32x16_bf16 v[48:63], v[92:95], v[84:87], v[48:63]
	v_add_f32_e32 v0, v189, v0
	v_add_f32_e32 v0, v192, v0
	v_add_f32_e32 v0, v193, v0
	v_add_f32_e32 v0, v194, v0
	v_add_f32_e32 v0, v195, v0
	v_add_f32_e32 v0, v196, v0
	v_add_f32_e32 v0, v197, v0
	v_mfma_f32_32x32x16_bf16 v[48:63], v[88:91], v[80:83], v[48:63]
	v_add_f32_e32 v0, v218, v0
	v_add_f32_e32 v0, v219, v0
	v_add_f32_e32 v0, v220, v0
	v_add_f32_e32 v0, v221, v0
	v_add_f32_e32 v0, v223, v0
	v_add_f32_e32 v0, v224, v0
	v_add_f32_e32 v0, v225, v0
	v_mfma_f32_32x32x16_bf16 v[48:63], v[8:11], v[12:15], v[48:63]
	ds_read_b64_tr_b16 v[96:97], v222 offset:128
	ds_read_b64_tr_b16 v[98:99], v222 offset:2688
	ds_read_b64_tr_b16 v[92:93], v222 offset:5248
	ds_read_b64_tr_b16 v[94:95], v222 offset:7808
	ds_read_b64_tr_b16 v[88:89], v222 offset:10368
	ds_read_b64_tr_b16 v[90:91], v222 offset:12928
	ds_read_b64_tr_b16 v[8:9], v222 offset:15488
	ds_read_b64_tr_b16 v[10:11], v222 offset:18048
	s_waitcnt lgkmcnt(0)
	v_add_f32_e32 v0, v226, v0
	v_add_f32_e32 v0, v185, v0
	s_add_i32 s47, s41, 1
	v_add_f32_e32 v145, v0, v145
	v_mfma_f32_32x32x16_bf16 v[32:47], v[96:99], v[4:7], v[32:47]
	v_mfma_f32_32x32x16_bf16 v[32:47], v[92:95], v[84:87], v[32:47]
	v_mfma_f32_32x32x16_bf16 v[32:47], v[88:91], v[80:83], v[32:47]
	v_mfma_f32_32x32x16_bf16 v[32:47], v[8:11], v[12:15], v[32:47]
	ds_read_b64_tr_b16 v[96:97], v222 offset:192
	ds_read_b64_tr_b16 v[98:99], v222 offset:2752
	ds_read_b64_tr_b16 v[92:93], v222 offset:5312
	ds_read_b64_tr_b16 v[94:95], v222 offset:7872
	ds_read_b64_tr_b16 v[88:89], v222 offset:10432
	ds_read_b64_tr_b16 v[90:91], v222 offset:12992
	ds_read_b64_tr_b16 v[8:9], v222 offset:15552
	ds_read_b64_tr_b16 v[10:11], v222 offset:18112
	s_waitcnt lgkmcnt(0)
	s_nop 0
	v_mfma_f32_32x32x16_bf16 v[16:31], v[96:99], v[4:7], v[16:31]
	v_mfma_f32_32x32x16_bf16 v[16:31], v[92:95], v[84:87], v[16:31]
	v_mfma_f32_32x32x16_bf16 v[16:31], v[88:91], v[80:83], v[16:31]
	v_mfma_f32_32x32x16_bf16 v[16:31], v[8:11], v[12:15], v[16:31]
	s_setprio 0
	s_cmp_lt_u32 s41, 3
	s_cselect_b32 s10, 8, 11
	s_mov_b32 s11, 0x10000
	s_cselect_b32 s11, s11, 0xffffff00
	s_lshl_b32 s10, s23, s10
	s_add_i32 s11, s11, s10
	s_add_i32 s10, s40, s11
	s_mul_hi_i32 s11, s10, 0x1200
	s_mulk_i32 s10, 0x1200
	s_add_u32 s56, s16, s10
	s_addc_u32 s57, s17, s11
	v_lshl_add_u64 v[4:5], s[56:57], 0, v[120:121]
	v_lshl_add_u64 v[8:9], s[56:57], 0, v[122:123]
	s_add_u32 s56, s44, s10
	global_load_dwordx4 v[4:7], v[4:5], off
	s_addc_u32 s57, s45, s11
	global_load_dwordx4 v[8:11], v[8:9], off
	v_lshl_add_u64 v[12:13], s[56:57], 0, v[124:125]
	global_load_dwordx4 v[12:15], v[12:13], off
	v_lshl_add_u64 v[80:81], s[56:57], 0, v[126:127]
	v_lshl_add_u64 v[84:85], s[56:57], 0, v[128:129]
	global_load_dwordx4 v[80:83], v[80:81], off
	v_lshl_add_u64 v[88:89], s[56:57], 0, v[138:139]
	global_load_dwordx4 v[84:87], v[84:85], off
	s_bitcmp1_b32 s47, 0
	global_load_dwordx4 v[88:91], v[88:89], off
	s_cselect_b32 s10, 0x7400, 0
	s_add_i32 s41, s10, 16
	v_add3_u32 v0, s41, v168, v169
	s_add_i32 s40, s40, 64
	s_cmp_eq_u32 s46, s47
	s_waitcnt vmcnt(5)
	ds_write_b128 v0, v[4:7]
	v_add3_u32 v0, s41, v170, v171
	s_waitcnt vmcnt(4)
	ds_write_b128 v0, v[8:11]
	v_add3_u32 v0, s41, v172, v173
	s_waitcnt vmcnt(3)
	ds_write_b128 v0, v[12:15] offset:9216
	s_waitcnt vmcnt(2)
	ds_write_b128 v0, v[80:83] offset:9536
	v_add3_u32 v0, s41, v174, v175
	s_waitcnt vmcnt(1)
	ds_write_b128 v0, v[84:87] offset:9216
	s_waitcnt vmcnt(0)
	ds_write_b128 v0, v[88:91] offset:9536
	s_waitcnt lgkmcnt(0)
	s_barrier
	s_cbranch_scc1 .LBB0_45
	v_mov_b32_e32 v183, v3
	s_mov_b32 s41, s47
	s_branch .LBB0_41
; DI f32x16 mfma32(bf16x8 a, bf16x8 b, f32x16 c) { return __builtin_amdgcn_mfma_f32_32x32x16_bf16(a, b, c, 0, 0, 0); }
; DI int crow(int reg, int h) { return (reg & 3) + 8 * (reg >> 2) + 4 * h; }
; template <int DQK, int DV, int KW0, int MODE> ...
;     ...
;       for (int kk = 0; kk < DQK / 16; ++kk) {
;         kfa[kk] = *(const bf16x8*)(cur + r * (KS * 2) + kk * 32 + h * 16);
;         kfb[kk] = *(const bf16x8*)(cur + (32 + r) * (KS * 2) + kk * 32 + h * 16);
;         qv[kk] = QLDS ? *(const bf16x8*)(qbase + kk * 1024) : qf[kk];
;       }
; #pragma unroll
;       for (int kk = 0; kk < DQK / 16; ++kk) {
;         S0 = mfma32(kfa[kk], qv[kk], S0);
;         S1 = mfma32(kfb[kk], qv[kk], S1);
;       }
;       __builtin_amdgcn_sched_group_barrier(0x100, (QLDS ? 3 : 2) * (DQK / 16), 0);
;       __builtin_amdgcn_sched_group_barrier(0x008, 2 * (DQK / 16), 0);
;     }
;     if (MODE == 2) {
;       if (it >= 4) {
;         const int w = wlo + it - 4;
;         if (w < 2 || w > 3) {
;           const int kpos0 = (qn - 1) * 128 + 64 * w, qpos = qn * 128 + wid * 32 + r;
; #pragma unroll
;           for (int e = 0; e < 16; ++e) {
;             const int d0 = qpos - (kpos0 + crow(e, h)), d1 = d0 - 32;
;             if (d0 > 128 || d0 < -128) S0[e] = -1e30f;
;             if (d1 > 128 || d1 < -128) S1[e] = -1e30f;
;           }
;         }
;       }
;     }
;     float mx = S0[0];
; #pragma unroll
;     for (int e = 1; e < 16; ++e) mx = fmaxf(mx, S0[e]);
; #pragma unroll
;     for (int e = 0; e < 16; ++e) mx = fmaxf(mx, S1[e]);
;     mx = fmaxf(mx, __shfl_xor(mx, 32));
;     const float mn = fmaxf(m, mx);
;     const bool grow = __builtin_amdgcn_ballot_w64(mx > m) != 0ull;
;     const float alpha = __builtin_amdgcn_exp2f((m - mn) * c);
;     m = mn;
;     const float mc = mn * c;
;     float ps = 0.f;
; #pragma unroll
;     for (int e = 0; e < 16; ++e) { S0[e] = __builtin_amdgcn_exp2f(S0[e] * c - mc); ps += S0[e]; }
; #pragma unroll
;     for (int e = 0; e < 16; ++e) { S1[e] = __builtin_amdgcn_exp2f(S1[e] * c - mc); ps += S1[e]; }
;     if (grow) {
;       l *= alpha;
; #pragma unroll
;       for (int t = 0; t < DV / 32; ++t)
; #pragma unroll
;         for (int e = 0; e < 16; ++e) O[t][e] *= alpha;
;     }
;     l += ps;
.LBB0_45:
	v_add3_u32 v0, s41, v176, v177
	ds_read_b128 v[12:15], v0
	ds_read_b128 v[8:11], v182 offset:59392
	ds_read_b128 v[192:195], v0 offset:32
	ds_read_b128 v[4:7], v0 offset:4608
	ds_read_b128 v[218:221], v0 offset:4640
	ds_read_b128 v[222:225], v182 offset:60416
	ds_read_b128 v[226:229], v0 offset:64
	ds_read_b128 v[230:233], v0 offset:4672
	ds_read_b128 v[234:237], v182 offset:61440
	ds_read_b128 v[238:241], v0 offset:96
	ds_read_b128 v[242:245], v0 offset:4704
	ds_read_b128 v[246:249], v182 offset:62464
	s_waitcnt lgkmcnt(10)
	v_mfma_f32_32x32x16_bf16 v[96:111], v[12:15], v[8:11], 0
	s_waitcnt lgkmcnt(6)
	v_mfma_f32_32x32x16_bf16 v[96:111], v[192:195], v[222:225], v[96:111]
	v_mfma_f32_32x32x16_bf16 v[80:95], v[4:7], v[8:11], 0
	v_max_f32_e32 v4, v3, v3
	s_waitcnt lgkmcnt(3)
	v_mfma_f32_32x32x16_bf16 v[96:111], v[226:229], v[234:237], v[96:111]
	v_mfma_f32_32x32x16_bf16 v[80:95], v[218:221], v[222:225], v[80:95]
	s_waitcnt lgkmcnt(0)
	v_mfma_f32_32x32x16_bf16 v[96:111], v[238:241], v[246:249], v[96:111]
	v_mfma_f32_32x32x16_bf16 v[80:95], v[230:233], v[234:237], v[80:95]
	s_nop 10
	v_max_f32_e32 v0, v97, v97
	v_max_f32_e32 v2, v96, v96
	v_max_f32_e32 v0, v2, v0
	v_max3_f32 v0, v0, v98, v99
	v_max3_f32 v0, v0, v100, v101
	v_max3_f32 v0, v0, v102, v103
	v_max3_f32 v0, v0, v104, v105
	v_mfma_f32_32x32x16_bf16 v[80:95], v[242:245], v[246:249], v[80:95]
	v_max3_f32 v0, v0, v106, v107
	v_max3_f32 v0, v0, v108, v109
	v_max3_f32 v0, v0, v110, v111
	s_nop 8
	v_max3_f32 v0, v0, v80, v81
	v_max3_f32 v0, v0, v82, v83
	v_max3_f32 v0, v0, v84, v85
	v_max3_f32 v0, v0, v86, v87
	v_max3_f32 v0, v0, v88, v89
	v_max3_f32 v0, v0, v90, v91
	v_max3_f32 v0, v0, v92, v93
	v_max3_f32 v0, v0, v94, v95
	ds_bpermute_b32 v2, v115, v0
	s_waitcnt lgkmcnt(0)
	v_max_f32_e32 v2, v2, v2
	v_max_f32_e32 v2, v0, v2
	v_max_f32_e32 v0, v4, v2
	v_cmp_gt_f32_e32 vcc, v2, v3
	s_cbranch_vccz .LBB0_47
	v_sub_f32_e32 v2, v3, v0
	v_mul_f32_e32 v2, 0x3e38aa3b, v2
	v_exp_f32_e32 v2, v2
	s_nop 0
	v_mul_f32_e32 v78, v2, v78
	v_mul_f32_e32 v79, v2, v79
	v_mul_f32_e32 v76, v2, v76
	v_mul_f32_e32 v77, v2, v77
	v_mul_f32_e32 v74, v2, v74
	v_mul_f32_e32 v75, v2, v75
	v_mul_f32_e32 v72, v2, v72
	v_mul_f32_e32 v73, v2, v73
	v_mul_f32_e32 v70, v2, v70
	v_mul_f32_e32 v71, v2, v71
	v_mul_f32_e32 v68, v2, v68
	v_mul_f32_e32 v69, v2, v69
	v_mul_f32_e32 v66, v2, v66
	v_mul_f32_e32 v67, v2, v67
	v_mul_f32_e32 v64, v2, v64
	v_mul_f32_e32 v65, v2, v65
	v_mul_f32_e32 v62, v2, v62
	v_mul_f32_e32 v63, v2, v63
	v_mul_f32_e32 v60, v2, v60
	v_mul_f32_e32 v61, v2, v61
	v_mul_f32_e32 v58, v2, v58
	v_mul_f32_e32 v59, v2, v59
	v_mul_f32_e32 v56, v2, v56
	v_mul_f32_e32 v57, v2, v57
	v_mul_f32_e32 v54, v2, v54
	v_mul_f32_e32 v55, v2, v55
	v_mul_f32_e32 v52, v2, v52
	v_mul_f32_e32 v53, v2, v53
	v_mul_f32_e32 v50, v2, v50
	v_mul_f32_e32 v51, v2, v51
	v_mul_f32_e32 v48, v2, v48
	v_mul_f32_e32 v49, v2, v49
	v_mul_f32_e32 v46, v2, v46
	v_mul_f32_e32 v47, v2, v47
	v_mul_f32_e32 v44, v2, v44
	v_mul_f32_e32 v45, v2, v45
	v_mul_f32_e32 v42, v2, v42
	v_mul_f32_e32 v43, v2, v43
	v_mul_f32_e32 v40, v2, v40
	v_mul_f32_e32 v41, v2, v41
	v_mul_f32_e32 v38, v2, v38
	v_mul_f32_e32 v39, v2, v39
	v_mul_f32_e32 v36, v2, v36
	v_mul_f32_e32 v37, v2, v37
	v_mul_f32_e32 v34, v2, v34
	v_mul_f32_e32 v35, v2, v35
	v_mul_f32_e32 v32, v2, v32
	v_mul_f32_e32 v33, v2, v33
	v_mul_f32_e32 v30, v2, v30
	v_mul_f32_e32 v31, v2, v31
	v_mul_f32_e32 v28, v2, v28
	v_mul_f32_e32 v29, v2, v29
	v_mul_f32_e32 v26, v2, v26
	v_mul_f32_e32 v27, v2, v27
	v_mul_f32_e32 v24, v2, v24
	v_mul_f32_e32 v25, v2, v25
	v_mul_f32_e32 v22, v2, v22
	v_mul_f32_e32 v23, v2, v23
	v_mul_f32_e32 v20, v2, v20
	v_mul_f32_e32 v21, v2, v21
	v_mul_f32_e32 v18, v2, v18
	v_mul_f32_e32 v19, v2, v19
	v_mul_f32_e32 v16, v2, v16
	v_mul_f32_e32 v17, v2, v17
	v_mul_f32_e32 v145, v145, v2
.LBB0_47:
	v_mul_f32_e32 v0, 0x3e38aa3b, v0
	v_fma_f32 v2, v96, s88, -v0
	v_exp_f32_e32 v14, v2
	v_fma_f32 v2, v97, s88, -v0
	v_exp_f32_e32 v15, v2
	v_fma_f32 v2, v98, s88, -v0
	v_exp_f32_e32 v183, v2
	v_fma_f32 v2, v99, s88, -v0
	v_exp_f32_e32 v184, v2
	v_fma_f32 v2, v100, s88, -v0
	v_exp_f32_e32 v100, v2
	v_fma_f32 v2, v101, s88, -v0
	v_exp_f32_e32 v101, v2
	v_fma_f32 v2, v102, s88, -v0
	v_exp_f32_e32 v102, v2
	v_fma_f32 v2, v103, s88, -v0
	v_exp_f32_e32 v103, v2
	v_fma_f32 v2, v104, s88, -v0
	v_exp_f32_e32 v104, v2
	v_fma_f32 v2, v105, s88, -v0
	v_exp_f32_e32 v105, v2
	v_fma_f32 v2, v106, s88, -v0
	v_exp_f32_e32 v106, v2
	v_fma_f32 v2, v107, s88, -v0
	v_exp_f32_e32 v107, v2
	v_fma_f32 v2, v108, s88, -v0
	v_exp_f32_e32 v108, v2
	v_fma_f32 v2, v109, s88, -v0
	v_exp_f32_e32 v109, v2
	v_fma_f32 v2, v110, s88, -v0
	v_exp_f32_e32 v110, v2
	v_fma_f32 v2, v111, s88, -v0
	v_exp_f32_e32 v111, v2
	v_fma_f32 v2, v80, s88, -v0
	v_exp_f32_e32 v185, v2
	v_fma_f32 v2, v81, s88, -v0
	v_exp_f32_e32 v189, v2
	v_fma_f32 v2, v82, s88, -v0
	v_exp_f32_e32 v192, v2
	v_fma_f32 v2, v83, s88, -v0
	v_exp_f32_e32 v193, v2
	v_fma_f32 v2, v84, s88, -v0
	v_exp_f32_e32 v194, v2
	v_fma_f32 v2, v85, s88, -v0
	v_exp_f32_e32 v195, v2
	v_fma_f32 v2, v86, s88, -v0
	v_exp_f32_e32 v196, v2
	v_fma_f32 v2, v87, s88, -v0
	v_exp_f32_e32 v197, v2
	v_fma_f32 v2, v88, s88, -v0
	v_exp_f32_e32 v218, v2
	v_fma_f32 v2, v89, s88, -v0
	v_exp_f32_e32 v219, v2
	v_fma_f32 v2, v90, s88, -v0
	v_exp_f32_e32 v220, v2
	v_fma_f32 v2, v91, s88, -v0
	v_exp_f32_e32 v221, v2
	v_fma_f32 v2, v92, s88, -v0
	v_exp_f32_e32 v222, v2
	v_fma_f32 v2, v93, s88, -v0
	v_cvt_pk_bf16_f32 v10, v14, v15
	v_cvt_pk_bf16_f32 v11, v183, v184
	v_cvt_pk_bf16_f32 v12, v100, v101
	v_cvt_pk_bf16_f32 v13, v102, v103
	s_addk_i32 s41, 0x2400
	v_exp_f32_e32 v223, v2
	v_fma_f32 v2, v94, s88, -v0
	v_fma_f32 v0, v95, s88, -v0
	v_add_u32_e32 v225, s41, v178
	ds_read_b64_tr_b16 v[96:97], v225 offset:0
	ds_read_b64_tr_b16 v[98:99], v225 offset:2560
	ds_read_b64_tr_b16 v[92:93], v225 offset:5120
	ds_read_b64_tr_b16 v[94:95], v225 offset:7680
	ds_read_b64_tr_b16 v[88:89], v225 offset:10240
	ds_read_b64_tr_b16 v[90:91], v225 offset:12800
	ds_read_b64_tr_b16 v[84:85], v225 offset:15360
	ds_read_b64_tr_b16 v[86:87], v225 offset:17920
	s_waitcnt lgkmcnt(0)
; #define GAS __attribute__((address_space(1)))
; DI float bflo(unsigned w) { return __uint_as_float(w << 16); }
; DI float bfhi(unsigned w) { return __uint_as_float(w & 0xffff0000u); }
; #define PV_TILE_(T) do { TRV8_320_T##T(R, vaddr); \
;           _Pragma("unroll") for (int st = 0; st < 2; ++st) _Pragma("unroll") for (int s = 0; s < 2; ++s) { const int ix = (st * 2 + s) * 2; \
;             const bf16x8 va = __builtin_shufflevector(R[ix], R[ix + 1], 0, 1, 2, 3, 4, 5, 6, 7); O[(DV > 64) ? T : 0] = mfma32(va, pf[st][s], O[(DV > 64) ? T : 0]); } } while (0)
; template <int DQK, int DV, int KW0, int MODE> ...
;     ...
;         PV_TILE_(0); PV_TILE_(1); PV_TILE_(2); PV_TILE_(3);
;     ...
;       }
;     }
;     if (DV > 64) { __builtin_amdgcn_sched_barrier(0); if (more) attn_gload<DQK, DV, KW0, 3>(kreg, vreg, k0p, ldk0, k1p, ldk1, vp, ldv, key_tile_row<MODE>(it + 1, b, qn, wlo), tid); }
;     if (more) attn_sstore<DQK, DV>(kreg, vreg, smem + ((it + 1) & 1) * STG, tid);
;     __syncthreads();
;   }
; __global__ void __launch_bounds__(256, 2) fwd_kernel(Params p) {
;     ...
;             l += __shfl_xor(l, 32);
;             const float inv = 1.f / l;
;             if (sm == 0) {
;               attn_store<4>(O, inv, outp, h);
;             } else {
; #pragma unroll
;               for (int t = 0; t < 4; ++t)
; #pragma unroll
;                 for (int g = 0; g < 4; ++g) {
;                   const u32x2 w = *(const GAS u32x2*)(outp + 32 * t + 8 * g + 4 * h);
;                   const float v0 = bflo(w.x) - lam * O[t][4 * g + 0] * inv, v1 = bfhi(w.x) - lam * O[t][4 * g + 1] * inv;
;                   const float v2 = bflo(w.y) - lam * O[t][4 * g + 2] * inv, v3 = bfhi(w.y) - lam * O[t][4 * g + 3] * inv;
;                   ss += v0 * v0 + v1 * v1 + v2 * v2 + v3 * v3;
;                   O[t][4 * g + 0] = v0; O[t][4 * g + 1] = v1; O[t][4 * g + 2] = v2; O[t][4 * g + 3] = v3;
;                 }
	v_cvt_pk_bf16_f32 v80, v104, v105
	v_mfma_f32_32x32x16_bf16 v[64:79], v[96:99], v[10:13], v[64:79]
	v_cvt_pk_bf16_f32 v81, v106, v107
	v_cvt_pk_bf16_f32 v82, v108, v109
	v_cvt_pk_bf16_f32 v83, v110, v111
	v_exp_f32_e32 v224, v2
	v_cvt_pk_bf16_f32 v2, v185, v189
	v_cvt_pk_bf16_f32 v3, v192, v193
	v_cvt_pk_bf16_f32 v4, v194, v195
	v_mfma_f32_32x32x16_bf16 v[64:79], v[92:95], v[80:83], v[64:79]
	v_cvt_pk_bf16_f32 v5, v196, v197
	v_exp_f32_e32 v0, v0
	v_cvt_pk_bf16_f32 v6, v218, v219
	v_cvt_pk_bf16_f32 v7, v220, v221
	v_cvt_pk_bf16_f32 v8, v222, v223
	v_cvt_pk_bf16_f32 v9, v224, v0
	v_mfma_f32_32x32x16_bf16 v[64:79], v[88:91], v[2:5], v[64:79]
	s_nop 0
	v_mfma_f32_32x32x16_bf16 v[64:79], v[84:87], v[6:9], v[64:79]
	ds_read_b64_tr_b16 v[96:97], v225 offset:64
	ds_read_b64_tr_b16 v[98:99], v225 offset:2624
	ds_read_b64_tr_b16 v[92:93], v225 offset:5184
	ds_read_b64_tr_b16 v[94:95], v225 offset:7744
	ds_read_b64_tr_b16 v[88:89], v225 offset:10304
	ds_read_b64_tr_b16 v[90:91], v225 offset:12864
	ds_read_b64_tr_b16 v[84:85], v225 offset:15424
	ds_read_b64_tr_b16 v[86:87], v225 offset:17984
	s_waitcnt lgkmcnt(0)
	s_nop 0
	v_mfma_f32_32x32x16_bf16 v[48:63], v[96:99], v[10:13], v[48:63]
	v_mfma_f32_32x32x16_bf16 v[48:63], v[92:95], v[80:83], v[48:63]
	v_mfma_f32_32x32x16_bf16 v[48:63], v[88:91], v[2:5], v[48:63]
	v_mfma_f32_32x32x16_bf16 v[48:63], v[84:87], v[6:9], v[48:63]
	ds_read_b64_tr_b16 v[96:97], v225 offset:128
	ds_read_b64_tr_b16 v[98:99], v225 offset:2688
	ds_read_b64_tr_b16 v[92:93], v225 offset:5248
	ds_read_b64_tr_b16 v[94:95], v225 offset:7808
	ds_read_b64_tr_b16 v[88:89], v225 offset:10368
	ds_read_b64_tr_b16 v[90:91], v225 offset:12928
	ds_read_b64_tr_b16 v[84:85], v225 offset:15488
	ds_read_b64_tr_b16 v[86:87], v225 offset:18048
	s_waitcnt lgkmcnt(0)
	s_nop 0
	v_mfma_f32_32x32x16_bf16 v[32:47], v[96:99], v[10:13], v[32:47]
	v_mfma_f32_32x32x16_bf16 v[32:47], v[92:95], v[80:83], v[32:47]
	v_mfma_f32_32x32x16_bf16 v[32:47], v[88:91], v[2:5], v[32:47]
	v_mfma_f32_32x32x16_bf16 v[32:47], v[84:87], v[6:9], v[32:47]
	ds_read_b64_tr_b16 v[96:97], v225 offset:192
	ds_read_b64_tr_b16 v[98:99], v225 offset:2752
	ds_read_b64_tr_b16 v[92:93], v225 offset:5312
	ds_read_b64_tr_b16 v[94:95], v225 offset:7872
	ds_read_b64_tr_b16 v[88:89], v225 offset:10432
	ds_read_b64_tr_b16 v[90:91], v225 offset:12992
	ds_read_b64_tr_b16 v[84:85], v225 offset:15552
	ds_read_b64_tr_b16 v[86:87], v225 offset:18112
	s_waitcnt lgkmcnt(0)
	s_nop 0
	v_mfma_f32_32x32x16_bf16 v[16:31], v[96:99], v[10:13], v[16:31]
	v_mfma_f32_32x32x16_bf16 v[16:31], v[92:95], v[80:83], v[16:31]
	v_mfma_f32_32x32x16_bf16 v[16:31], v[88:91], v[2:5], v[16:31]
	v_mfma_f32_32x32x16_bf16 v[16:31], v[84:87], v[6:9], v[16:31]
	v_add_f32_e32 v2, 0, v14
	v_add_f32_e32 v2, v15, v2
	v_add_f32_e32 v2, v183, v2
	v_add_f32_e32 v2, v184, v2
	v_add_f32_e32 v2, v100, v2
	v_add_f32_e32 v2, v101, v2
	v_add_f32_e32 v2, v102, v2
	v_add_f32_e32 v2, v103, v2
	v_add_f32_e32 v2, v104, v2
	v_add_f32_e32 v2, v105, v2
	v_add_f32_e32 v2, v106, v2
	v_add_f32_e32 v2, v107, v2
	v_add_f32_e32 v2, v108, v2
	v_add_f32_e32 v2, v109, v2
	v_add_f32_e32 v2, v110, v2
	v_add_f32_e32 v2, v111, v2
	v_add_f32_e32 v2, v185, v2
	v_add_f32_e32 v2, v189, v2
	v_add_f32_e32 v2, v192, v2
	v_add_f32_e32 v2, v193, v2
	v_add_f32_e32 v2, v194, v2
	v_add_f32_e32 v2, v195, v2
	v_add_f32_e32 v2, v196, v2
	v_add_f32_e32 v2, v197, v2
	v_add_f32_e32 v2, v218, v2
	v_add_f32_e32 v2, v219, v2
	v_add_f32_e32 v2, v220, v2
	v_add_f32_e32 v2, v221, v2
	v_add_f32_e32 v2, v222, v2
	v_add_f32_e32 v2, v223, v2
	v_add_f32_e32 v2, v224, v2
	v_add_f32_e32 v0, v0, v2
	v_add_f32_e32 v0, v0, v145
	ds_bpermute_b32 v2, v115, v0
	s_waitcnt lgkmcnt(0)
	s_barrier
	v_add_f32_e32 v0, v0, v2
	v_div_scale_f32 v2, s[16:17], v0, v0, 1.0
	v_rcp_f32_e32 v3, v2
	v_div_scale_f32 v4, vcc, 1.0, v0, 1.0
	s_mov_b64 s[16:17], -1
	v_fma_f32 v5, -v2, v3, 1.0
	v_fmac_f32_e32 v3, v5, v3
	v_mul_f32_e32 v5, v4, v3
	v_fma_f32 v6, -v2, v5, v4
	v_fmac_f32_e32 v5, v6, v3
	v_fma_f32 v2, -v2, v5, v4
	v_div_fmas_f32 v2, v2, v3, v5
	v_div_fixup_f32 v0, v2, v0, 1.0
	s_andn2_b64 vcc, exec, s[14:15]
	s_cbranch_vccnz .LBB0_49
	global_load_dwordx2 v[2:3], v[146:147], off
	global_load_dwordx2 v[4:5], v[146:147], off offset:16
	global_load_dwordx2 v[6:7], v[146:147], off offset:32
	global_load_dwordx2 v[8:9], v[146:147], off offset:48
	global_load_dwordx2 v[10:11], v[146:147], off offset:80
	global_load_dwordx2 v[96:97], v[146:147], off offset:96
	global_load_dwordx2 v[98:99], v[146:147], off offset:112
	global_load_dwordx2 v[12:13], v[146:147], off offset:64
	global_load_dwordx2 v[94:95], v[146:147], off offset:128
	global_load_dwordx2 v[108:109], v[146:147], off offset:144
	global_load_dwordx2 v[110:111], v[146:147], off offset:160
	global_load_dwordx2 v[184:185], v[146:147], off offset:176
	v_mov_b32_e32 v84, v48
	v_mov_b32_e32 v85, v52
	v_mul_f32_e32 v14, v160, v64
	v_mul_f32_e32 v15, v161, v65
	v_mul_f32_e32 v80, v160, v66
	v_mul_f32_e32 v81, v161, v67
	v_mul_f32_e32 v82, v160, v68
	v_mul_f32_e32 v83, v161, v69
	v_mul_f32_e32 v90, v160, v72
	v_mul_f32_e32 v91, v161, v73
	v_mov_b32_e32 v86, v49
	v_mov_b32_e32 v87, v53
	v_mul_f32_e32 v192, v160, v84
	v_mul_f32_e32 v193, v161, v85
	v_mul_f32_e32 v88, v160, v70
	v_mul_f32_e32 v89, v161, v71
	v_mul_f32_e32 v92, v160, v74
	v_mul_f32_e32 v93, v161, v75
	v_mul_f32_e32 v102, v160, v78
	v_mul_f32_e32 v103, v161, v79
	v_mov_b32_e32 v104, v50
	v_mov_b32_e32 v105, v54
	v_mul_f32_e32 v194, v160, v86
	v_mul_f32_e32 v195, v161, v87
	v_mul_f32_e32 v104, v160, v104
	v_mul_f32_e32 v105, v161, v105
	v_mul_f32_e32 v100, v160, v76
	v_mul_f32_e32 v101, v161, v77
	v_mov_b32_e32 v106, v51
	v_mov_b32_e32 v107, v55
	s_mov_b64 s[16:17], 0
	s_waitcnt vmcnt(11)
; #define GAS __attribute__((address_space(1)))
; DI float bflo(unsigned w) { return __uint_as_float(w << 16); }
; DI float bfhi(unsigned w) { return __uint_as_float(w & 0xffff0000u); }
; __global__ void __launch_bounds__(256, 2) fwd_kernel(Params p) {
;     ...
; #pragma unroll
;               for (int t = 0; t < 4; ++t)
; #pragma unroll
;                 for (int g = 0; g < 4; ++g) {
;                   const u32x2 w = *(const GAS u32x2*)(outp + 32 * t + 8 * g + 4 * h);
;                   const float v0 = bflo(w.x) - lam * O[t][4 * g + 0] * inv, v1 = bfhi(w.x) - lam * O[t][4 * g + 1] * inv;
;                   const float v2 = bflo(w.y) - lam * O[t][4 * g + 2] * inv, v3 = bfhi(w.y) - lam * O[t][4 * g + 3] * inv;
;                   ss += v0 * v0 + v1 * v1 + v2 * v2 + v3 * v3;
;                   O[t][4 * g + 0] = v0; O[t][4 * g + 1] = v1; O[t][4 * g + 2] = v2; O[t][4 * g + 3] = v3;
;                 }
;               attn_store<4>(O, 1.f, outp, h);
	v_lshlrev_b32_e32 v84, 16, v2
	v_and_b32_e32 v85, 0xffff0000, v2
	v_lshlrev_b32_e32 v2, 16, v3
	v_and_b32_e32 v3, 0xffff0000, v3
	s_waitcnt vmcnt(10)
	v_lshlrev_b32_e32 v196, 16, v4
	v_and_b32_e32 v197, 0xffff0000, v4
	s_waitcnt vmcnt(9)
	v_lshlrev_b32_e32 v218, 16, v6
	v_and_b32_e32 v219, 0xffff0000, v6
	v_lshlrev_b32_e32 v4, 16, v5
	v_and_b32_e32 v5, 0xffff0000, v5
	v_lshlrev_b32_e32 v6, 16, v7
	v_and_b32_e32 v7, 0xffff0000, v7
	s_waitcnt vmcnt(8)
	v_lshlrev_b32_e32 v222, 16, v9
	v_and_b32_e32 v223, 0xffff0000, v9
	s_waitcnt vmcnt(4)
	v_lshlrev_b32_e32 v224, 16, v12
	v_and_b32_e32 v226, 0xffff0000, v12
	v_lshlrev_b32_e32 v228, 16, v13
	v_and_b32_e32 v230, 0xffff0000, v13
	v_fma_f32 v84, -v0, v14, v84
	v_fma_f32 v85, -v0, v15, v85
	v_fma_f32 v86, -v0, v80, v2
	v_fma_f32 v87, -v0, v81, v3
	v_fma_f32 v80, -v0, v82, v196
	v_fma_f32 v81, -v0, v83, v197
	v_fma_f32 v12, -v0, v90, v218
	v_fma_f32 v13, -v0, v91, v219
	v_lshlrev_b32_e32 v225, 16, v10
	v_and_b32_e32 v227, 0xffff0000, v10
	v_lshlrev_b32_e32 v229, 16, v11
	v_and_b32_e32 v231, 0xffff0000, v11
	v_fma_f32 v82, -v0, v88, v4
	v_fma_f32 v83, -v0, v89, v5
	v_fma_f32 v14, -v0, v92, v6
	v_fma_f32 v15, -v0, v93, v7
	v_fma_f32 v10, -v0, v102, v222
	v_fma_f32 v11, -v0, v103, v223
	v_mul_f32_e32 v88, v84, v84
	v_mul_f32_e32 v89, v85, v85
	v_mul_f32_e32 v92, v80, v80
	v_mul_f32_e32 v93, v81, v81
	v_mul_f32_e32 v102, v12, v12
	v_mul_f32_e32 v103, v13, v13
	v_fma_f32 v6, -v0, v104, v228
	v_fma_f32 v7, -v0, v105, v229
	v_mul_f32_e32 v90, v86, v86
	v_mul_f32_e32 v91, v87, v87
	v_mul_f32_e32 v104, v14, v14
	v_mul_f32_e32 v105, v15, v15
	v_add_f32_e32 v88, v88, v89
	v_add_f32_e32 v89, v92, v93
	v_add_f32_e32 v92, v102, v103
	v_add_f32_e32 v88, v90, v88
	v_add_f32_e32 v90, v104, v92
	v_add_f32_e32 v90, v105, v90
	global_load_dwordx2 v[102:103], v[146:147], off offset:192
	global_load_dwordx2 v[104:105], v[146:147], off offset:208
	v_lshlrev_b32_e32 v220, 16, v8
	v_and_b32_e32 v221, 0xffff0000, v8
	v_fma_f32 v8, -v0, v100, v220
	v_fma_f32 v9, -v0, v101, v221
	v_fma_f32 v2, -v0, v192, v224
	v_fma_f32 v3, -v0, v193, v225
	v_mul_f32_e32 v192, v8, v8
	v_mul_f32_e32 v193, v9, v9
	v_fma_f32 v4, -v0, v194, v226
	v_fma_f32 v5, -v0, v195, v227
	v_mul_f32_e32 v194, v10, v10
	v_mul_f32_e32 v195, v11, v11
	v_add_f32_e32 v93, v192, v193
	v_add_f32_e32 v92, v194, v93
	v_add_f32_e32 v88, v91, v88
	v_add_f32_e32 v91, v195, v92
	global_load_dwordx2 v[194:195], v[146:147], off offset:224
	global_load_dwordx2 v[196:197], v[146:147], off offset:240
	v_mul_f32_e32 v100, v82, v82
	v_mul_f32_e32 v101, v83, v83
	v_add_f32_e32 v88, v143, v88
	v_add_f32_e32 v89, v100, v89
	v_add_f32_e32 v89, v101, v89
	v_add_f32_e32 v88, v88, v89
	v_add_f32_e32 v88, v88, v90
	v_add_f32_e32 v92, v88, v91
	v_mul_f32_e32 v90, v4, v4
	v_mul_f32_e32 v91, v5, v5
	v_mul_f32_e32 v88, v160, v106
	v_mul_f32_e32 v89, v161, v107
	v_fma_f32 v90, v2, v2, v90
	v_fma_f32 v91, v3, v3, v91
	v_fma_f32 v88, -v0, v88, v230
	v_fma_f32 v89, -v0, v89, v231
	v_fma_f32 v90, v6, v6, v90
	v_fma_f32 v91, v7, v7, v91
	v_mov_b32_e32 v93, v60
	v_fma_f32 v90, v88, v88, v90
	v_fma_f32 v91, v89, v89, v91
	v_mov_b32_e32 v100, v57
	v_add_f32_e32 v90, v92, v90
	v_mov_b32_e32 v92, v56
	v_add_f32_e32 v145, v90, v91
	v_lshlrev_b32_e32 v91, 16, v98
	v_lshlrev_b32_e32 v90, 16, v96
	v_mul_f32_e32 v92, v160, v92
	v_mul_f32_e32 v93, v161, v93
	v_mov_b32_e32 v101, v61
	v_fma_f32 v90, -v0, v92, v90
	v_fma_f32 v91, -v0, v93, v91
	v_and_b32_e32 v93, 0xffff0000, v98
	v_and_b32_e32 v92, 0xffff0000, v96
	v_mul_f32_e32 v100, v160, v100
	v_mul_f32_e32 v101, v161, v101
	v_mov_b32_e32 v106, v58
	v_fma_f32 v92, -v0, v100, v92
	v_fma_f32 v93, -v0, v101, v93
	v_lshlrev_b32_e32 v100, 16, v97
	v_mov_b32_e32 v107, v62
	v_and_b32_e32 v98, 0xffff0000, v97
	v_mov_b32_e32 v96, v59
	v_mov_b32_e32 v97, v63
	v_lshlrev_b32_e32 v101, 16, v99
	v_mul_f32_e32 v106, v160, v106
	v_mul_f32_e32 v107, v161, v107
	v_and_b32_e32 v99, 0xffff0000, v99
	v_mul_f32_e32 v96, v160, v96
	v_mul_f32_e32 v97, v161, v97
	v_fma_f32 v100, -v0, v106, v100
	v_fma_f32 v101, -v0, v107, v101
	v_fma_f32 v106, -v0, v96, v98
	v_fma_f32 v107, -v0, v97, v99
	v_mul_f32_e32 v96, v92, v92
	v_mul_f32_e32 v97, v93, v93
	v_mov_b32_e32 v98, v32
	v_fma_f32 v96, v90, v90, v96
	v_fma_f32 v97, v91, v91, v97
	v_mov_b32_e32 v99, v36
	v_fma_f32 v96, v100, v100, v96
	v_fma_f32 v97, v101, v101, v97
	v_mul_f32_e32 v98, v160, v98
	v_mul_f32_e32 v99, v161, v99
	v_fma_f32 v96, v106, v106, v96
	v_fma_f32 v97, v107, v107, v97
	v_cvt_pk_bf16_f32 v8, v8, v9
	v_add_f32_e32 v96, v145, v96
	v_add_f32_e32 v145, v96, v97
	s_waitcnt vmcnt(6)
	v_lshlrev_b32_e32 v97, 16, v108
	v_lshlrev_b32_e32 v96, 16, v94
	v_fma_f32 v192, -v0, v98, v96
	v_fma_f32 v193, -v0, v99, v97
	v_mov_b32_e32 v98, v33
	v_mov_b32_e32 v99, v37
	v_and_b32_e32 v97, 0xffff0000, v108
	v_and_b32_e32 v96, 0xffff0000, v94
	v_mul_f32_e32 v98, v160, v98
	v_mul_f32_e32 v99, v161, v99
	v_mov_b32_e32 v94, v35
	v_fma_f32 v218, -v0, v98, v96
	v_fma_f32 v219, -v0, v99, v97
	v_mov_b32_e32 v98, v34
	v_mov_b32_e32 v99, v38
	v_lshlrev_b32_e32 v97, 16, v109
	v_lshlrev_b32_e32 v96, 16, v95
	v_mul_f32_e32 v98, v160, v98
	v_mul_f32_e32 v99, v161, v99
	v_cvt_pk_bf16_f32 v9, v10, v11
	v_fma_f32 v220, -v0, v98, v96
	v_fma_f32 v221, -v0, v99, v97
	v_and_b32_e32 v96, 0xffff0000, v95
	v_mov_b32_e32 v95, v39
	v_and_b32_e32 v97, 0xffff0000, v109
	v_mul_f32_e32 v94, v160, v94
	v_mul_f32_e32 v95, v161, v95
	global_store_dwordx2 v[146:147], v[8:9], off offset:48
	v_fma_f32 v108, -v0, v94, v96
	v_fma_f32 v109, -v0, v95, v97
	v_mul_f32_e32 v94, v218, v218
	v_mul_f32_e32 v95, v219, v219
	v_mov_b32_e32 v96, v40
	v_fma_f32 v94, v192, v192, v94
	v_fma_f32 v95, v193, v193, v95
	v_mov_b32_e32 v97, v44
	v_fma_f32 v94, v220, v220, v94
	v_fma_f32 v95, v221, v221, v95
	v_mul_f32_e32 v96, v160, v96
	v_mul_f32_e32 v97, v161, v97
	v_fma_f32 v94, v108, v108, v94
	v_fma_f32 v95, v109, v109, v95
	v_cvt_pk_bf16_f32 v8, v2, v4
	v_add_f32_e32 v94, v145, v94
	v_add_f32_e32 v98, v94, v95
	s_waitcnt vmcnt(5)
; #define GAS __attribute__((address_space(1)))
; DI float bflo(unsigned w) { return __uint_as_float(w << 16); }
; DI float bfhi(unsigned w) { return __uint_as_float(w & 0xffff0000u); }
; __global__ void __launch_bounds__(256, 2) fwd_kernel(Params p) {
;     ...
; #pragma unroll
;               for (int t = 0; t < 4; ++t)
; #pragma unroll
;                 for (int g = 0; g < 4; ++g) {
;                   const u32x2 w = *(const GAS u32x2*)(outp + 32 * t + 8 * g + 4 * h);
;                   const float v0 = bflo(w.x) - lam * O[t][4 * g + 0] * inv, v1 = bfhi(w.x) - lam * O[t][4 * g + 1] * inv;
;                   const float v2 = bflo(w.y) - lam * O[t][4 * g + 2] * inv, v3 = bfhi(w.y) - lam * O[t][4 * g + 3] * inv;
;                   ss += v0 * v0 + v1 * v1 + v2 * v2 + v3 * v3;
;                   O[t][4 * g + 0] = v0; O[t][4 * g + 1] = v1; O[t][4 * g + 2] = v2; O[t][4 * g + 3] = v3;
;                 }
;               attn_store<4>(O, 1.f, outp, h);
	v_lshlrev_b32_e32 v95, 16, v184
	v_lshlrev_b32_e32 v94, 16, v110
	v_fma_f32 v222, -v0, v96, v94
	v_fma_f32 v223, -v0, v97, v95
	v_mov_b32_e32 v96, v41
	v_mov_b32_e32 v97, v45
	v_and_b32_e32 v95, 0xffff0000, v184
	v_and_b32_e32 v94, 0xffff0000, v110
	v_mul_f32_e32 v96, v160, v96
	v_mul_f32_e32 v97, v161, v97
	v_cvt_pk_bf16_f32 v2, v3, v5
	v_fma_f32 v224, -v0, v96, v94
	v_fma_f32 v225, -v0, v97, v95
	v_mov_b32_e32 v96, v42
	v_mov_b32_e32 v97, v46
	v_lshlrev_b32_e32 v95, 16, v185
	v_lshlrev_b32_e32 v94, 16, v111
	v_mul_f32_e32 v96, v160, v96
	v_mul_f32_e32 v97, v161, v97
	v_cvt_pk_bf16_f32 v3, v7, v89
	v_fma_f32 v226, -v0, v96, v94
	v_fma_f32 v227, -v0, v97, v95
	v_mov_b32_e32 v96, v43
	v_mov_b32_e32 v97, v47
	v_and_b32_e32 v95, 0xffff0000, v185
	v_and_b32_e32 v94, 0xffff0000, v111
	v_mul_f32_e32 v96, v160, v96
	v_mul_f32_e32 v97, v161, v97
	global_store_dwordx2 v[146:147], v[2:3], off offset:80
	v_fma_f32 v110, -v0, v96, v94
	v_fma_f32 v111, -v0, v97, v95
	v_mul_f32_e32 v94, v224, v224
	v_mul_f32_e32 v95, v225, v225
	v_mov_b32_e32 v96, v16
	v_fma_f32 v94, v222, v222, v94
	v_fma_f32 v95, v223, v223, v95
	v_mov_b32_e32 v97, v20
	v_fma_f32 v94, v226, v226, v94
	v_fma_f32 v95, v227, v227, v95
	v_mul_f32_e32 v96, v160, v96
	v_mul_f32_e32 v97, v161, v97
	v_fma_f32 v94, v110, v110, v94
	v_fma_f32 v95, v111, v111, v95
	v_cvt_pk_bf16_f32 v2, v90, v92
	v_add_f32_e32 v94, v98, v94
	v_add_f32_e32 v98, v94, v95
	s_waitcnt vmcnt(4)
	v_lshlrev_b32_e32 v95, 16, v104
	v_lshlrev_b32_e32 v94, 16, v102
	v_fma_f32 v184, -v0, v96, v94
	v_fma_f32 v185, -v0, v97, v95
	v_mov_b32_e32 v96, v17
	v_mov_b32_e32 v97, v21
	v_and_b32_e32 v95, 0xffff0000, v104
	v_and_b32_e32 v94, 0xffff0000, v102
	v_mul_f32_e32 v96, v160, v96
	v_mul_f32_e32 v97, v161, v97
	v_cvt_pk_bf16_f32 v3, v100, v106
	v_fma_f32 v228, -v0, v96, v94
	v_fma_f32 v229, -v0, v97, v95
	v_mov_b32_e32 v96, v18
	v_mov_b32_e32 v97, v22
	v_lshlrev_b32_e32 v95, 16, v105
	v_lshlrev_b32_e32 v94, 16, v103
	v_mul_f32_e32 v96, v160, v96
	v_mul_f32_e32 v97, v161, v97
	global_store_dwordx2 v[146:147], v[2:3], off offset:96
	v_fma_f32 v230, -v0, v96, v94
	v_fma_f32 v231, -v0, v97, v95
	v_mov_b32_e32 v96, v19
	v_mov_b32_e32 v97, v23
	v_and_b32_e32 v95, 0xffff0000, v105
	v_and_b32_e32 v94, 0xffff0000, v103
	v_mul_f32_e32 v96, v160, v96
	v_mul_f32_e32 v97, v161, v97
	v_cvt_pk_bf16_f32 v2, v91, v93
	v_fma_f32 v102, -v0, v96, v94
	v_fma_f32 v103, -v0, v97, v95
	v_mul_f32_e32 v94, v228, v228
	v_mul_f32_e32 v95, v229, v229
	v_mov_b32_e32 v96, v24
	v_fma_f32 v94, v184, v184, v94
	v_fma_f32 v95, v185, v185, v95
	v_mov_b32_e32 v97, v28
	v_fma_f32 v94, v230, v230, v94
	v_fma_f32 v95, v231, v231, v95
	v_mul_f32_e32 v96, v160, v96
	v_mul_f32_e32 v97, v161, v97
	v_fma_f32 v94, v102, v102, v94
	v_fma_f32 v95, v103, v103, v95
	v_cvt_pk_bf16_f32 v3, v101, v107
	v_add_f32_e32 v94, v98, v94
	v_add_f32_e32 v145, v94, v95
	s_waitcnt vmcnt(3)
	v_lshlrev_b32_e32 v95, 16, v196
	v_lshlrev_b32_e32 v94, 16, v194
	v_fma_f32 v104, -v0, v96, v94
	v_fma_f32 v105, -v0, v97, v95
	v_mov_b32_e32 v96, v25
	v_mov_b32_e32 v97, v29
	v_and_b32_e32 v95, 0xffff0000, v196
	v_and_b32_e32 v94, 0xffff0000, v194
	v_mul_f32_e32 v96, v160, v96
	v_mul_f32_e32 v97, v161, v97
	v_mov_b32_e32 v98, v27
	v_fma_f32 v232, -v0, v96, v94
	v_fma_f32 v233, -v0, v97, v95
	v_mov_b32_e32 v96, v26
	v_mov_b32_e32 v97, v30
	v_lshlrev_b32_e32 v95, 16, v197
	v_lshlrev_b32_e32 v94, 16, v195
	v_mul_f32_e32 v96, v160, v96
	v_mul_f32_e32 v97, v161, v97
	v_mov_b32_e32 v99, v31
	global_store_dwordx2 v[146:147], v[2:3], off offset:112
	v_cvt_pk_bf16_f32 v2, v192, v218
	v_cvt_pk_bf16_f32 v3, v220, v108
	v_fma_f32 v94, -v0, v96, v94
	v_fma_f32 v95, -v0, v97, v95
	v_and_b32_e32 v97, 0xffff0000, v197
	v_and_b32_e32 v96, 0xffff0000, v195
	v_mul_f32_e32 v98, v160, v98
	v_mul_f32_e32 v99, v161, v99
	global_store_dwordx2 v[146:147], v[2:3], off offset:128
	v_cvt_pk_bf16_f32 v2, v193, v219
	v_cvt_pk_bf16_f32 v3, v221, v109
	v_fma_f32 v96, -v0, v98, v96
	v_fma_f32 v97, -v0, v99, v97
	v_mul_f32_e32 v98, v232, v232
	v_mul_f32_e32 v99, v233, v233
	global_store_dwordx2 v[146:147], v[2:3], off offset:144
	v_cvt_pk_bf16_f32 v2, v222, v224
	v_cvt_pk_bf16_f32 v3, v226, v110
	v_fma_f32 v98, v104, v104, v98
	v_fma_f32 v99, v105, v105, v99
	global_store_dwordx2 v[146:147], v[2:3], off offset:160
	v_cvt_pk_bf16_f32 v2, v223, v225
	v_cvt_pk_bf16_f32 v3, v227, v111
	v_fma_f32 v98, v94, v94, v98
	v_fma_f32 v99, v95, v95, v99
	global_store_dwordx2 v[146:147], v[2:3], off offset:176
	v_cvt_pk_bf16_f32 v2, v184, v228
	v_cvt_pk_bf16_f32 v3, v230, v102
	v_fma_f32 v98, v96, v96, v98
	v_fma_f32 v99, v97, v97, v99
	global_store_dwordx2 v[146:147], v[2:3], off offset:192
	v_cvt_pk_bf16_f32 v2, v185, v229
	v_cvt_pk_bf16_f32 v3, v231, v103
	v_add_f32_e32 v98, v145, v98
	global_store_dwordx2 v[146:147], v[2:3], off offset:208
	v_cvt_pk_bf16_f32 v2, v104, v232
	v_cvt_pk_bf16_f32 v3, v94, v96
	v_add_f32_e32 v98, v98, v99
	v_cvt_pk_bf16_f32 v84, v84, v85
	v_cvt_pk_bf16_f32 v85, v86, v87
	v_cvt_pk_bf16_f32 v80, v80, v81
	v_cvt_pk_bf16_f32 v81, v82, v83
	v_cvt_pk_bf16_f32 v12, v12, v13
	v_cvt_pk_bf16_f32 v13, v14, v15
	v_cvt_pk_bf16_f32 v9, v6, v88
	global_store_dwordx2 v[146:147], v[2:3], off offset:224
	v_cvt_pk_bf16_f32 v2, v105, v233
	global_store_dwordx2 v[146:147], v[84:85], off
	global_store_dwordx2 v[146:147], v[80:81], off offset:16
	global_store_dwordx2 v[146:147], v[12:13], off offset:32
	global_store_dwordx2 v[146:147], v[8:9], off offset:64
; #define GAS __attribute__((address_space(1)))
; DI unsigned pk2(float a, float b) { f32x2 v = {a, b}; bf2_t r = __builtin_convertvector(v, bf2_t); return __builtin_bit_cast(unsigned, r); }
; template <int NTL> DI void attn_store(const f32x16 (&O)[NTL], float inv, bf16_t* __restrict__ outp, int h) {
; #pragma unroll
;   for (int t = 0; t < NTL; ++t)
; #pragma unroll
;     for (int g = 0; g < 4; ++g) {
;       u32x2 w; w.x = pk2(O[t][4 * g] * inv, O[t][4 * g + 1] * inv); w.y = pk2(O[t][4 * g + 2] * inv, O[t][4 * g + 3] * inv);
;       *(GAS u32x2*)(outp + 32 * t + 8 * g + 4 * h) = w;
;     }
; }
; __global__ void __launch_bounds__(256, 2) fwd_kernel(Params p) {
;     ...
;             if (sm == 0) {
;               attn_store<4>(O, inv, outp, h);
.LBB0_49:
	s_andn2_b64 vcc, exec, s[16:17]
	s_cbranch_vccnz .LBB0_51
	v_mul_f32_e32 v2, v0, v64
	v_mul_f32_e32 v3, v0, v65
	v_mul_f32_e32 v4, v0, v66
	v_mul_f32_e32 v5, v0, v67
	v_cvt_pk_bf16_f32 v2, v2, v3
	v_cvt_pk_bf16_f32 v3, v4, v5
	global_store_dwordx2 v[146:147], v[2:3], off
	v_mul_f32_e32 v2, v0, v68
	v_mul_f32_e32 v3, v0, v69
	v_mul_f32_e32 v4, v0, v70
	v_mul_f32_e32 v5, v0, v71
	v_cvt_pk_bf16_f32 v2, v2, v3
	v_cvt_pk_bf16_f32 v3, v4, v5
	global_store_dwordx2 v[146:147], v[2:3], off offset:16
	v_mul_f32_e32 v2, v0, v72
	v_mul_f32_e32 v3, v0, v73
	v_mul_f32_e32 v4, v0, v74
	v_mul_f32_e32 v5, v0, v75
	v_cvt_pk_bf16_f32 v2, v2, v3
	v_cvt_pk_bf16_f32 v3, v4, v5
	global_store_dwordx2 v[146:147], v[2:3], off offset:32
	v_mul_f32_e32 v2, v0, v76
	v_mul_f32_e32 v3, v0, v77
	v_mul_f32_e32 v4, v0, v78
	v_mul_f32_e32 v5, v0, v79
	v_cvt_pk_bf16_f32 v2, v2, v3
	v_cvt_pk_bf16_f32 v3, v4, v5
	global_store_dwordx2 v[146:147], v[2:3], off offset:48
	v_mul_f32_e32 v2, v0, v48
	v_mul_f32_e32 v3, v0, v49
	v_mul_f32_e32 v4, v0, v50
	v_mul_f32_e32 v5, v0, v51
	v_cvt_pk_bf16_f32 v2, v2, v3
	v_cvt_pk_bf16_f32 v3, v4, v5
	global_store_dwordx2 v[146:147], v[2:3], off offset:64
	v_mul_f32_e32 v2, v0, v52
	v_mul_f32_e32 v3, v0, v53
	v_mul_f32_e32 v4, v0, v54
	v_mul_f32_e32 v5, v0, v55
	v_cvt_pk_bf16_f32 v2, v2, v3
	v_cvt_pk_bf16_f32 v3, v4, v5
	global_store_dwordx2 v[146:147], v[2:3], off offset:80
	v_mul_f32_e32 v2, v0, v56
	v_mul_f32_e32 v3, v0, v57
	v_mul_f32_e32 v4, v0, v58
	v_mul_f32_e32 v5, v0, v59
	v_cvt_pk_bf16_f32 v2, v2, v3
	v_cvt_pk_bf16_f32 v3, v4, v5
	global_store_dwordx2 v[146:147], v[2:3], off offset:96
	v_mul_f32_e32 v2, v0, v60
	v_mul_f32_e32 v3, v0, v61
	v_mul_f32_e32 v4, v0, v62
	v_mul_f32_e32 v5, v0, v63
	v_cvt_pk_bf16_f32 v2, v2, v3
	v_cvt_pk_bf16_f32 v3, v4, v5
	global_store_dwordx2 v[146:147], v[2:3], off offset:112
	v_mul_f32_e32 v2, v0, v32
	v_mul_f32_e32 v3, v0, v33
	v_mul_f32_e32 v4, v0, v34
	v_mul_f32_e32 v5, v0, v35
	v_cvt_pk_bf16_f32 v2, v2, v3
	v_cvt_pk_bf16_f32 v3, v4, v5
	global_store_dwordx2 v[146:147], v[2:3], off offset:128
	v_mul_f32_e32 v2, v0, v36
	v_mul_f32_e32 v3, v0, v37
	v_mul_f32_e32 v4, v0, v38
	v_mul_f32_e32 v5, v0, v39
	v_cvt_pk_bf16_f32 v2, v2, v3
	v_cvt_pk_bf16_f32 v3, v4, v5
	global_store_dwordx2 v[146:147], v[2:3], off offset:144
	v_mul_f32_e32 v2, v0, v40
	v_mul_f32_e32 v3, v0, v41
	v_mul_f32_e32 v4, v0, v42
	v_mul_f32_e32 v5, v0, v43
	v_cvt_pk_bf16_f32 v2, v2, v3
	v_cvt_pk_bf16_f32 v3, v4, v5
	global_store_dwordx2 v[146:147], v[2:3], off offset:160
	v_mul_f32_e32 v2, v0, v44
	v_mul_f32_e32 v3, v0, v45
	v_mul_f32_e32 v4, v0, v46
	v_mul_f32_e32 v5, v0, v47
	v_cvt_pk_bf16_f32 v2, v2, v3
	v_cvt_pk_bf16_f32 v3, v4, v5
	global_store_dwordx2 v[146:147], v[2:3], off offset:176
	v_mul_f32_e32 v2, v0, v16
	v_mul_f32_e32 v3, v0, v17
	v_mul_f32_e32 v4, v0, v18
	v_mul_f32_e32 v5, v0, v19
	v_cvt_pk_bf16_f32 v2, v2, v3
	v_cvt_pk_bf16_f32 v3, v4, v5
	global_store_dwordx2 v[146:147], v[2:3], off offset:192
	v_mul_f32_e32 v2, v0, v20
	v_mul_f32_e32 v3, v0, v21
	v_mul_f32_e32 v4, v0, v22
	v_mul_f32_e32 v5, v0, v23
	v_cvt_pk_bf16_f32 v2, v2, v3
	v_cvt_pk_bf16_f32 v3, v4, v5
	global_store_dwordx2 v[146:147], v[2:3], off offset:208
	v_mul_f32_e32 v2, v0, v24
	v_mul_f32_e32 v3, v0, v25
	v_mul_f32_e32 v4, v0, v26
	v_mul_f32_e32 v5, v0, v27
	v_cvt_pk_bf16_f32 v2, v2, v3
	v_cvt_pk_bf16_f32 v3, v4, v5
	global_store_dwordx2 v[146:147], v[2:3], off offset:224
	v_mul_f32_e32 v2, v0, v28
	v_mul_f32_e32 v3, v0, v29
	v_mul_f32_e32 v96, v0, v30
	v_mul_f32_e32 v97, v0, v31
	v_cvt_pk_bf16_f32 v2, v2, v3
	v_mov_b32_e32 v98, v143
	v_mov_b32_e32 v95, v96

; #define GAS __attribute__((address_space(1)))
; DI unsigned pk2(float a, float b) { f32x2 v = {a, b}; bf2_t r = __builtin_convertvector(v, bf2_t); return __builtin_bit_cast(unsigned, r); }
; template <int NTL> DI void attn_store(const f32x16 (&O)[NTL], float inv, bf16_t* __restrict__ outp, int h) {
; #pragma unroll
;   for (int t = 0; t < NTL; ++t)
; #pragma unroll
;     for (int g = 0; g < 4; ++g) {
;       u32x2 w; w.x = pk2(O[t][4 * g] * inv, O[t][4 * g + 1] * inv); w.y = pk2(O[t][4 * g + 2] * inv, O[t][4 * g + 3] * inv);
;       *(GAS u32x2*)(outp + 32 * t + 8 * g + 4 * h) = w;
;     }
; }
; __global__ void __launch_bounds__(256, 2) fwd_kernel(Params p) {
;     ...
;           l += __shfl_xor(l, 32);
;           attn_store<2>(O, 1.f / l, MI + (size_t)qr * 1024 + hh * 64, h);
.LBB0_55:
	ds_bpermute_b32 v36, v166, v113
	v_lshlrev_b64 v[34:35], 11, v[114:115]
	s_lshl_b32 s70, s23, 7
	v_lshl_add_u64 v[34:35], s[58:59], 0, v[34:35]
	v_lshl_add_u64 v[34:35], v[34:35], 0, s[70:71]
	s_waitcnt lgkmcnt(0)
	v_add_f32_e32 v36, v113, v36
	v_div_scale_f32 v37, s[12:13], v36, v36, 1.0
	v_rcp_f32_e32 v38, v37
	v_div_scale_f32 v39, vcc, 1.0, v36, 1.0
	v_mov_b32_e32 v113, v1
	v_fma_f32 v40, -v37, v38, 1.0
	v_fmac_f32_e32 v38, v40, v38
	v_mul_f32_e32 v40, v39, v38
	v_fma_f32 v41, -v37, v40, v39
	v_fmac_f32_e32 v40, v41, v38
	v_fma_f32 v37, -v37, v40, v39
	v_div_fmas_f32 v37, v37, v38, v40
	v_div_fixup_f32 v36, v37, v36, 1.0
	v_mul_f32_e32 v2, v2, v36
	v_mul_f32_e32 v3, v3, v36
	v_mul_f32_e32 v4, v4, v36
	v_mul_f32_e32 v5, v5, v36
	v_lshl_add_u64 v[34:35], v[34:35], 0, v[112:113]
	v_cvt_pk_bf16_f32 v2, v2, v3
	v_cvt_pk_bf16_f32 v3, v4, v5
	global_store_dwordx2 v[34:35], v[2:3], off
	v_mul_f32_e32 v2, v6, v36
	v_mul_f32_e32 v3, v7, v36
	v_mul_f32_e32 v4, v8, v36
	v_mul_f32_e32 v5, v9, v36
	v_cvt_pk_bf16_f32 v2, v2, v3
	v_cvt_pk_bf16_f32 v3, v4, v5
	global_store_dwordx2 v[34:35], v[2:3], off offset:16
	v_mul_f32_e32 v2, v10, v36
	v_mul_f32_e32 v3, v11, v36
	v_mul_f32_e32 v4, v12, v36
	v_mul_f32_e32 v5, v13, v36
	v_cvt_pk_bf16_f32 v2, v2, v3
	v_cvt_pk_bf16_f32 v3, v4, v5
	global_store_dwordx2 v[34:35], v[2:3], off offset:32
	v_mul_f32_e32 v2, v14, v36
	v_mul_f32_e32 v3, v15, v36
	v_mul_f32_e32 v4, v16, v36
	v_mul_f32_e32 v5, v17, v36
	v_cvt_pk_bf16_f32 v2, v2, v3
	v_cvt_pk_bf16_f32 v3, v4, v5
	global_store_dwordx2 v[34:35], v[2:3], off offset:48
	v_mul_f32_e32 v2, v18, v36
	v_mul_f32_e32 v3, v19, v36
	v_mul_f32_e32 v4, v20, v36
	v_mul_f32_e32 v5, v21, v36
	v_cvt_pk_bf16_f32 v2, v2, v3
	v_cvt_pk_bf16_f32 v3, v4, v5
	global_store_dwordx2 v[34:35], v[2:3], off offset:64
	v_mul_f32_e32 v2, v22, v36
	v_mul_f32_e32 v3, v23, v36
	v_mul_f32_e32 v4, v24, v36
	v_mul_f32_e32 v5, v25, v36
	v_cvt_pk_bf16_f32 v2, v2, v3
	v_cvt_pk_bf16_f32 v3, v4, v5
	global_store_dwordx2 v[34:35], v[2:3], off offset:80
	v_mul_f32_e32 v2, v26, v36
	v_mul_f32_e32 v3, v27, v36
	v_mul_f32_e32 v4, v28, v36
	v_mul_f32_e32 v5, v29, v36
	v_cvt_pk_bf16_f32 v2, v2, v3
	v_cvt_pk_bf16_f32 v3, v4, v5
	v_readlane_b32 s10, v252, 12
	global_store_dwordx2 v[34:35], v[2:3], off offset:96
	v_mul_f32_e32 v2, v30, v36
	v_mul_f32_e32 v3, v31, v36
	v_mul_f32_e32 v4, v32, v36
	v_mul_f32_e32 v5, v33, v36
	s_add_i32 s22, s22, s10
	v_readlane_b32 s10, v252, 21
	v_cvt_pk_bf16_f32 v2, v2, v3
	v_cvt_pk_bf16_f32 v3, v4, v5
	s_cmp_ge_i32 s22, s10
	global_store_dwordx2 v[34:35], v[2:3], off offset:112
	s_cbranch_scc1 .LBB0_140

; #define GAS __attribute__((address_space(1)))
; DI unsigned pk2(float a, float b) { f32x2 v = {a, b}; bf2_t r = __builtin_convertvector(v, bf2_t); return __builtin_bit_cast(unsigned, r); }
; DI float bf2f(unsigned short v) { return __uint_as_float(((unsigned)v) << 16); }
; template <int DQK, int ROFF, int RDIM>
; DI void load_q(bf16x8 (&qf)[DQK / 16], const bf16_t* __restrict__ qrowp, int h, bool rope, const f32x2* __restrict__ cs  ) {
; #pragma unroll
;   for (int kk = 0; kk < DQK / 16; ++kk) qf[kk] = *(const GAS bf16x8*)(qrowp + kk * 16 + h * 8);
;   if (rope) {
;     constexpr int NP = RDIM / 32;
; #pragma unroll
;     for (int p = 0; p < NP; ++p) {
;       const int ka = ROFF / 16 + p, kb = ka + NP;
;       bf16x8 xa = qf[ka], xb = qf[kb];
;       u32x4 oa, ob;
; #pragma unroll
;       for (int j2 = 0; j2 < 4; ++j2) {
;         float o1[2], o2[2];
; #pragma unroll
;         for (int q = 0; q < 2; ++q) {
;           const int j = 2 * j2 + q;
;           const f32x2 csv = cs[16 * p + 8 * h + j];
;           const float x1 = bf2f((unsigned short)xa[j]), x2 = bf2f((unsigned short)xb[j]);
;           o1[q] = x1 * csv.x - x2 * csv.y; o2[q] = x1 * csv.y + x2 * csv.x;
;         }
;         oa[j2] = pk2(o1[0], o1[1]); ob[j2] = pk2(o2[0], o2[1]);
;       }
;       qf[ka] = __builtin_bit_cast(bf16x8, oa); qf[kb] = __builtin_bit_cast(bf16x8, ob);
;     }
;   }
.LBB0_64:
	s_lshl_b32 s10, s16, 7
	s_and_b32 s10, s10, s14
	s_or_b32 s10, s19, s10
	s_and_b32 s23, s17, 7
	v_add_u32_e32 v114, s10, v162
	v_mov_b64_e32 v[2:3], s[56:57]
	s_movk_i32 s10, 0x600
	v_mad_i64_i32 v[2:3], s[14:15], v114, s10, v[2:3]
	s_mul_i32 s70, s23, 0xc0
	v_lshl_add_u64 v[2:3], v[2:3], 0, s[70:71]
	v_lshl_add_u64 v[2:3], v[2:3], 0, v[0:1]
	global_load_dwordx4 v[22:25], v[2:3], off
	global_load_dwordx4 v[18:21], v[2:3], off offset:32
	global_load_dwordx4 v[14:17], v[2:3], off offset:64
	global_load_dwordx4 v[10:13], v[2:3], off offset:96
	global_load_dwordx4 v[6:9], v[2:3], off offset:128
	s_nop 0
	global_load_dwordx4 v[2:5], v[2:3], off offset:160
	s_andn2_b64 vcc, exec, s[12:13]
	v_ashrrev_i32_e32 v115, 31, v114
	s_cbranch_vccnz .LBB0_66
	v_lshlrev_b32_e32 v32, 7, v114
	v_and_b32_e32 v32, 0x3ff80, v32
	v_mov_b32_e32 v33, v1
	v_lshl_add_u64 v[36:37], v[110:111], 0, v[32:33]
	flat_load_dwordx4 v[32:35], v[36:37]
	s_waitcnt vmcnt(0)
	v_and_b32_e32 v41, 0xffff0000, v2
	v_lshlrev_b32_e32 v40, 16, v2
	v_and_b32_e32 v39, 0xffff0000, v6
	v_lshlrev_b32_e32 v38, 16, v6
	v_lshrrev_b32_e32 v26, 16, v13
	v_lshrrev_b32_e32 v27, 16, v12
	v_lshrrev_b32_e32 v28, 16, v11
	v_lshrrev_b32_e32 v29, 16, v10
	v_lshrrev_b32_e32 v30, 16, v17
	v_lshrrev_b32_e32 v31, 16, v16
	v_lshrrev_b32_e32 v44, 16, v15
	v_lshrrev_b32_e32 v45, 16, v14
	v_lshrrev_b32_e32 v46, 16, v21
	v_lshrrev_b32_e32 v47, 16, v20
	v_lshrrev_b32_e32 v48, 16, v19
	v_lshrrev_b32_e32 v49, 16, v18
	v_lshrrev_b32_e32 v50, 16, v25
	v_lshrrev_b32_e32 v51, 16, v24
	v_lshrrev_b32_e32 v52, 16, v23
	v_lshrrev_b32_e32 v53, 16, v22
	s_mov_b32 s10, 0x5040100
	v_perm_b32 v22, v53, v22, s10
	v_perm_b32 v23, v52, v23, s10
	v_perm_b32 v24, v51, v24, s10
	v_perm_b32 v25, v50, v25, s10
	v_perm_b32 v18, v49, v18, s10
	v_perm_b32 v19, v48, v19, s10
	v_perm_b32 v20, v47, v20, s10
	v_perm_b32 v21, v46, v21, s10
	v_perm_b32 v14, v45, v14, s10
	v_perm_b32 v15, v44, v15, s10
	v_perm_b32 v16, v31, v16, s10
	v_perm_b32 v17, v30, v17, s10
	v_perm_b32 v10, v29, v10, s10
	v_perm_b32 v11, v28, v11, s10
	v_perm_b32 v12, v27, v12, s10
	v_perm_b32 v13, v26, v13, s10
	s_mov_b32 s28, 36
	s_waitcnt lgkmcnt(0)
	v_mov_b32_e32 v42, v33
	v_mov_b32_e32 v43, v35
	v_mov_b32_e32 v33, v34
	v_mul_f32_e32 v34, v32, v40
	v_mul_f32_e32 v35, v33, v41
	v_mul_f32_e32 v40, v42, v40
	v_mul_f32_e32 v41, v43, v41
	v_fma_f32 v34, v42, v38, v34
	v_fma_f32 v35, v43, v39, v35
	v_fma_f32 v32, v32, v38, -v40
	v_fma_f32 v33, v33, v39, -v41
	v_cvt_pk_bf16_f32 v2, v34, v35
	v_cvt_pk_bf16_f32 v6, v32, v33
	flat_load_dwordx4 v[32:35], v[36:37] offset:16
	v_and_b32_e32 v41, 0xffff0000, v3
	v_lshlrev_b32_e32 v40, 16, v3
	v_and_b32_e32 v39, 0xffff0000, v7
	v_lshlrev_b32_e32 v38, 16, v7
	s_waitcnt vmcnt(0) lgkmcnt(0)
	v_mov_b32_e32 v42, v33
	v_mov_b32_e32 v43, v35
	v_mov_b32_e32 v33, v34
	v_mul_f32_e32 v34, v32, v40
	v_mul_f32_e32 v35, v33, v41
	v_mul_f32_e32 v40, v42, v40
	v_mul_f32_e32 v41, v43, v41
	v_fma_f32 v34, v42, v38, v34
	v_fma_f32 v35, v43, v39, v35
	v_fma_f32 v32, v32, v38, -v40
	v_fma_f32 v33, v33, v39, -v41
	v_cvt_pk_bf16_f32 v3, v34, v35
	v_cvt_pk_bf16_f32 v7, v32, v33
	flat_load_dwordx4 v[32:35], v[36:37] offset:32
	v_and_b32_e32 v41, 0xffff0000, v4
	v_lshlrev_b32_e32 v40, 16, v4
	v_and_b32_e32 v39, 0xffff0000, v8
	v_lshlrev_b32_e32 v38, 16, v8
	s_waitcnt vmcnt(0) lgkmcnt(0)
	v_mov_b32_e32 v42, v33
	v_mov_b32_e32 v43, v35
	v_mov_b32_e32 v33, v34
	v_mul_f32_e32 v34, v32, v40
	v_mul_f32_e32 v35, v33, v41
	v_mul_f32_e32 v40, v42, v40
	v_mul_f32_e32 v41, v43, v41
	v_fma_f32 v34, v42, v38, v34
	v_fma_f32 v35, v43, v39, v35
	v_fma_f32 v32, v32, v38, -v40
	v_fma_f32 v33, v33, v39, -v41
	v_cvt_pk_bf16_f32 v4, v34, v35
	v_cvt_pk_bf16_f32 v8, v32, v33
	flat_load_dwordx4 v[32:35], v[36:37] offset:48
	v_and_b32_e32 v39, 0xffff0000, v5
	v_lshlrev_b32_e32 v38, 16, v5
	v_and_b32_e32 v37, 0xffff0000, v9
	v_lshlrev_b32_e32 v36, 16, v9
	s_waitcnt vmcnt(0) lgkmcnt(0)
	v_mov_b32_e32 v40, v33
	v_mov_b32_e32 v41, v35
	v_mov_b32_e32 v33, v34
	v_mul_f32_e32 v34, v32, v38
	v_mul_f32_e32 v35, v33, v39
	v_mul_f32_e32 v38, v40, v38
	v_mul_f32_e32 v39, v41, v39
	v_fma_f32 v34, v40, v36, v34
	v_fma_f32 v35, v41, v37, v35
	v_fma_f32 v32, v32, v36, -v38
	v_fma_f32 v33, v33, v37, -v39
	v_cvt_pk_bf16_f32 v5, v34, v35
	v_cvt_pk_bf16_f32 v9, v32, v33
	s_branch .LBB0_67

; template <int DQK, int DV, int KW0, int MODE> ...
;     ...
;   __syncthreads();
;   if (QLDS) {
; #pragma unroll
;     for (int kk = 0; kk < DQK / 16; ++kk) *(bf16x8*)(qbase + kk * 1024) = qf[kk];
;   }
;   attn_gload<DQK, DV, KW0, 3>(kreg, vreg, k0p, ldk0, k1p, ldk1, vp, ldv, key_tile_row<MODE>(0, b, qn, wlo), tid);
;   attn_sstore<DQK, DV>(kreg, vreg, smem, tid);
;   __syncthreads();
;   for (int it = 0; it < nkt; ++it) {
;     const char* cur = smem + (it & 1) * STG;
;     const bool more = (it + 1 < nkt);
;     if (DV <= 64) { if (more) attn_gload<DQK, DV, KW0, 3>(kreg, vreg, k0p, ldk0, k1p, ldk1, vp, ldv, key_tile_row<MODE>(it + 1, b, qn, wlo), tid); __builtin_amdgcn_sched_barrier(0); }
;     f32x16 S0, S1;
; #pragma unroll
;     for (int e = 0; e < 16; ++e) { S0[e] = 0.f; S1[e] = 0.f; }
;     {
;       bf16x8 kfa[DQK / 16], kfb[DQK / 16], qv[DQK / 16];
; #pragma unroll
;       for (int kk = 0; kk < DQK / 16; ++kk) {
;         kfa[kk] = *(const bf16x8*)(cur + r * (KS * 2) + kk * 32 + h * 16);
;         kfb[kk] = *(const bf16x8*)(cur + (32 + r) * (KS * 2) + kk * 32 + h * 16);
;         qv[kk] = QLDS ? *(const bf16x8*)(qbase + kk * 1024) : qf[kk];
.LBB0_67:
	s_lshl_b32 s10, s23, 8
	s_add_u32 s12, s20, s10
	s_addc_u32 s13, s21, 0
	s_lshl_b32 s19, s18, 8
	s_add_i32 s14, s19, 0x10000
	v_add_u32_e32 v28, s14, v152
	v_ashrrev_i32_e32 v29, 31, v28
	s_barrier
	s_and_saveexec_b64 s[16:17], s[40:41]
	s_xor_b64 s[16:17], exec, s[16:17]
	s_movk_i32 s10, 0xff80
	v_mad_i64_i32 v[26:27], s[46:47], v28, s35, v[116:117]
	s_mov_b32 s11, -1
	v_lshl_add_u64 v[26:27], v[26:27], 0, s[10:11]
	s_andn2_saveexec_b64 s[16:17], s[16:17]
	v_lshlrev_b64 v[26:27], 11, v[28:29]
	v_lshl_add_u64 v[26:27], s[12:13], 0, v[26:27]
	v_lshl_add_u64 v[26:27], v[118:119], 1, v[26:27]
	s_or_b64 exec, exec, s[16:17]
	global_load_dwordx4 v[26:29], v[26:27], off
	v_add_u32_e32 v32, s14, v153
	v_ashrrev_i32_e32 v33, 31, v32
	s_and_saveexec_b64 s[16:17], s[42:43]
	s_xor_b64 s[16:17], exec, s[16:17]
	s_movk_i32 s10, 0xff80
	v_mad_i64_i32 v[30:31], s[46:47], v32, s35, v[120:121]
	s_mov_b32 s11, -1
	v_lshl_add_u64 v[30:31], v[30:31], 0, s[10:11]
	s_andn2_saveexec_b64 s[16:17], s[16:17]
	v_lshlrev_b64 v[30:31], 11, v[32:33]
	v_lshl_add_u64 v[30:31], s[12:13], 0, v[30:31]
	v_lshl_add_u64 v[30:31], v[122:123], 1, v[30:31]
	s_or_b64 exec, exec, s[16:17]
	global_load_dwordx4 v[30:33], v[30:31], off
	v_add_u32_e32 v38, s14, v154
	v_ashrrev_i32_e32 v39, 31, v38
	s_and_saveexec_b64 s[16:17], s[44:45]
	s_xor_b64 s[16:17], exec, s[16:17]
	s_movk_i32 s10, 0xff80
	v_mad_i64_i32 v[34:35], s[46:47], v38, s35, v[126:127]
	s_mov_b32 s11, -1
	v_lshl_add_u64 v[36:37], v[34:35], 0, s[10:11]
	s_or_saveexec_b64 s[16:17], s[16:17]
	v_mov_b64_e32 v[34:35], v[124:125]
	s_xor_b64 exec, exec, s[16:17]
	v_lshlrev_b64 v[34:35], 11, v[38:39]
	v_lshl_add_u64 v[34:35], s[12:13], 0, v[34:35]
	v_lshl_add_u64 v[36:37], v[128:129], 1, v[34:35]
	v_mov_b64_e32 v[34:35], v[128:129]
	s_or_b64 exec, exec, s[16:17]
	s_ashr_i32 s15, s14, 31
	s_lshl_b64 s[14:15], s[14:15], 11
	s_add_u32 s14, s12, s14
	s_addc_u32 s15, s13, s15
	v_lshl_add_u64 v[40:41], s[14:15], 0, v[138:139]
	v_lshl_add_u64 v[44:45], s[14:15], 0, v[140:141]
	global_load_dwordx4 v[36:39], v[36:37], off
	s_nop 0
	global_load_dwordx4 v[40:43], v[40:41], off offset:128
	s_nop 0
	global_load_dwordx4 v[44:47], v[44:45], off offset:128
	s_add_i32 s14, s19, 0x10040
	s_waitcnt vmcnt(0)
	ds_write_b128 v170, v[26:29]
	s_waitcnt vmcnt(3)
	ds_write_b128 v171, v[30:33]
	v_add_u32_e32 v26, s14, v152
	v_ashrrev_i32_e32 v27, 31, v26
	s_waitcnt vmcnt(2)
	ds_write_b128 v172, v[36:39]
	s_waitcnt vmcnt(1)
	ds_write_b128 v173, v[40:43] offset:13312
	s_waitcnt vmcnt(0)
	ds_write_b128 v173, v[44:47] offset:13504
	s_waitcnt lgkmcnt(0)
	s_barrier
	s_and_saveexec_b64 s[16:17], s[40:41]
	s_xor_b64 s[16:17], exec, s[16:17]
	s_movk_i32 s10, 0xff80
	v_mad_i64_i32 v[26:27], s[46:47], v26, s35, v[116:117]
	s_mov_b32 s11, -1
	v_lshl_add_u64 v[28:29], v[26:27], 0, s[10:11]
	s_or_saveexec_b64 s[16:17], s[16:17]
	v_lshl_add_u64 v[142:143], v[118:119], 1, s[12:13]
	s_xor_b64 exec, exec, s[16:17]
	v_lshlrev_b64 v[26:27], 11, v[26:27]
	v_lshl_add_u64 v[28:29], v[142:143], 0, v[26:27]
	s_or_b64 exec, exec, s[16:17]
	global_load_dwordx4 v[50:53], v[28:29], off
	v_add_u32_e32 v28, s14, v153
	v_ashrrev_i32_e32 v29, 31, v28
	s_and_saveexec_b64 s[16:17], s[42:43]
	s_xor_b64 s[16:17], exec, s[16:17]
	s_movk_i32 s10, 0xff80
	v_mad_i64_i32 v[26:27], s[46:47], v28, s35, v[120:121]
	s_mov_b32 s11, -1
	v_lshl_add_u64 v[26:27], v[26:27], 0, s[10:11]
	s_or_saveexec_b64 s[16:17], s[16:17]
	v_lshl_add_u64 v[144:145], v[122:123], 1, s[12:13]
	s_xor_b64 exec, exec, s[16:17]
	v_lshlrev_b64 v[26:27], 11, v[28:29]
	v_lshl_add_u64 v[26:27], v[144:145], 0, v[26:27]
	s_or_b64 exec, exec, s[16:17]
	global_load_dwordx4 v[54:57], v[26:27], off
	v_add_u32_e32 v28, s14, v154
	v_ashrrev_i32_e32 v29, 31, v28
	s_and_saveexec_b64 s[16:17], s[44:45]
	s_xor_b64 s[16:17], exec, s[16:17]
	s_movk_i32 s10, 0xff80
	v_mad_i64_i32 v[26:27], s[46:47], v28, s35, v[126:127]
	s_mov_b32 s11, -1
	v_lshl_add_u64 v[26:27], v[26:27], 0, s[10:11]
	s_or_saveexec_b64 s[16:17], s[16:17]
	v_lshl_add_u64 v[146:147], v[34:35], 1, s[12:13]
	s_xor_b64 exec, exec, s[16:17]
	v_lshlrev_b64 v[26:27], 11, v[28:29]
	v_lshl_add_u64 v[26:27], v[146:147], 0, v[26:27]
	s_or_b64 exec, exec, s[16:17]
	s_ashr_i32 s15, s14, 31
	s_lshl_b64 s[14:15], s[14:15], 11
	s_add_u32 s14, s12, s14
	s_addc_u32 s15, s13, s15
	global_load_dwordx4 v[58:61], v[26:27], off
	v_lshl_add_u64 v[26:27], s[14:15], 0, v[138:139]
	v_lshl_add_u64 v[28:29], s[14:15], 0, v[140:141]
	global_load_dwordx4 v[62:65], v[26:27], off offset:128
	global_load_dwordx4 v[90:93], v[28:29], off offset:128
	v_lshrrev_b32_e32 v113, 16, v5
	v_lshrrev_b32_e32 v175, 16, v4
	v_lshrrev_b32_e32 v176, 16, v3
	v_lshrrev_b32_e32 v177, 16, v2
	v_lshrrev_b32_e32 v178, 16, v9
	v_lshrrev_b32_e32 v179, 16, v8
	v_lshrrev_b32_e32 v180, 16, v7
	v_lshrrev_b32_e32 v181, 16, v6
	v_lshrrev_b32_e32 v182, 16, v13
	v_lshrrev_b32_e32 v183, 16, v12
	v_lshrrev_b32_e32 v184, 16, v11
	v_lshrrev_b32_e32 v185, 16, v10
	v_lshrrev_b32_e32 v77, 16, v17
	v_lshrrev_b32_e32 v76, 16, v16
	v_lshrrev_b32_e32 v75, 16, v15
	v_lshrrev_b32_e32 v74, 16, v14
	v_lshrrev_b32_e32 v73, 16, v21
	v_lshrrev_b32_e32 v72, 16, v20
	v_lshrrev_b32_e32 v71, 16, v19
	v_lshrrev_b32_e32 v70, 16, v18
	v_lshrrev_b32_e32 v26, 16, v25
	v_lshrrev_b32_e32 v27, 16, v24
	v_lshrrev_b32_e32 v28, 16, v23
	v_lshrrev_b32_e32 v29, 16, v22
	s_mov_b32 s10, 0x5040100
	v_perm_b32 v66, v29, v22, s10
	v_perm_b32 v67, v28, v23, s10
	v_perm_b32 v68, v27, v24, s10
	v_perm_b32 v69, v26, v25, s10
	ds_read_b128 v[22:25], v174
	ds_read_b128 v[42:45], v174 offset:32
	ds_read_b128 v[38:41], v174 offset:6656
	ds_read_b128 v[46:49], v174 offset:6688
	ds_read_b128 v[78:81], v174 offset:64
	ds_read_b128 v[94:97], v174 offset:6720
	ds_read_b128 v[82:85], v174 offset:96
	ds_read_b128 v[98:101], v174 offset:6752
	ds_read_b128 v[86:89], v174 offset:128
	ds_read_b128 v[102:105], v174 offset:6784
	ds_read_b128 v[106:109], v174 offset:160
	ds_read_b128 v[148:151], v174 offset:6816
	s_waitcnt lgkmcnt(11)
; DI int crow(int reg, int h) { return (reg & 3) + 8 * (reg >> 2) + 4 * h; }
; template <int DQK, int DV, int KW0, int MODE> ...
;     ...
; #pragma unroll
;       for (int kk = 0; kk < DQK / 16; ++kk) {
;         S0 = mfma32(kfa[kk], qv[kk], S0);
;         S1 = mfma32(kfb[kk], qv[kk], S1);
;       }
;       __builtin_amdgcn_sched_group_barrier(0x100, (QLDS ? 3 : 2) * (DQK / 16), 0);
;       __builtin_amdgcn_sched_group_barrier(0x008, 2 * (DQK / 16), 0);
;     }
;     if (MODE == 2) {
;       if (it >= 4) {
;         const int w = wlo + it - 4;
;         if (w < 2 || w > 3) {
;           const int kpos0 = (qn - 1) * 128 + 64 * w, qpos = qn * 128 + wid * 32 + r;
; #pragma unroll
;           for (int e = 0; e < 16; ++e) {
;             const int d0 = qpos - (kpos0 + crow(e, h)), d1 = d0 - 32;
;             if (d0 > 128 || d0 < -128) S0[e] = -1e30f;
;             if (d1 > 128 || d1 < -128) S1[e] = -1e30f;
;           }
;         }
;       }
;     }
;     float mx = S0[0];
; #pragma unroll
;     for (int e = 1; e < 16; ++e) mx = fmaxf(mx, S0[e]);
; #pragma unroll
;     for (int e = 0; e < 16; ++e) mx = fmaxf(mx, S1[e]);
;     mx = fmaxf(mx, __shfl_xor(mx, 32));
;     const float mn = fmaxf(m, mx);
;     const bool grow = __builtin_amdgcn_ballot_w64(mx > m) != 0ull;
;     const float alpha = __builtin_amdgcn_exp2f((m - mn) * c);
;     m = mn;
;     const float mc = mn * c;
;     float ps = 0.f;
; #pragma unroll
;     for (int e = 0; e < 16; ++e) { S0[e] = __builtin_amdgcn_exp2f(S0[e] * c - mc); ps += S0[e]; }
; #pragma unroll
;     for (int e = 0; e < 16; ++e) { S1[e] = __builtin_amdgcn_exp2f(S1[e] * c - mc); ps += S1[e]; }
;     if (grow) {
;       l *= alpha;
; #pragma unroll
;       for (int t = 0; t < DV / 32; ++t)
; #pragma unroll
;         for (int e = 0; e < 16; ++e) O[t][e] *= alpha;
;     }
;     l += ps;
;     bf16x8 pf[2][2];
; #pragma unroll
;     for (int s = 0; s < 2; ++s) {
;       u32x4 w0, w1;
;       w0.x = pk2(S0[8 * s + 0], S0[8 * s + 1]); w0.y = pk2(S0[8 * s + 2], S0[8 * s + 3]); w0.z = pk2(S0[8 * s + 4], S0[8 * s + 5]); w0.w = pk2(S0[8 * s + 6], S0[8 * s + 7]);
;       w1.x = pk2(S1[8 * s + 0], S1[8 * s + 1]); w1.y = pk2(S1[8 * s + 2], S1[8 * s + 3]); w1.z = pk2(S1[8 * s + 4], S1[8 * s + 5]); w1.w = pk2(S1[8 * s + 6], S1[8 * s + 7]);
;       pf[0][s] = __builtin_bit_cast(bf16x8, w0); pf[1][s] = __builtin_bit_cast(bf16x8, w1);
;     }
;     {
	v_mfma_f32_32x32x16_bf16 v[22:37], v[22:25], v[66:69], 0
	v_perm_b32 v70, v70, v18, s10
	v_perm_b32 v71, v71, v19, s10
	v_perm_b32 v72, v72, v20, s10
	v_perm_b32 v73, v73, v21, s10
	v_perm_b32 v74, v74, v14, s10
	v_perm_b32 v75, v75, v15, s10
	v_perm_b32 v76, v76, v16, s10
	s_waitcnt lgkmcnt(10)
	v_mfma_f32_32x32x16_bf16 v[22:37], v[42:45], v[70:73], v[22:37]
	v_perm_b32 v77, v77, v17, s10
	s_waitcnt lgkmcnt(7)
	s_nop 0
	v_mfma_f32_32x32x16_bf16 v[22:37], v[78:81], v[74:77], v[22:37]
	v_perm_b32 v78, v185, v10, s10
	v_perm_b32 v79, v184, v11, s10
	v_perm_b32 v80, v183, v12, s10
	v_perm_b32 v81, v182, v13, s10
	s_waitcnt lgkmcnt(5)
	s_nop 0
	v_mfma_f32_32x32x16_bf16 v[22:37], v[82:85], v[78:81], v[22:37]
	v_perm_b32 v82, v181, v6, s10
	v_perm_b32 v83, v180, v7, s10
	v_perm_b32 v84, v179, v8, s10
	v_perm_b32 v85, v178, v9, s10
	v_mfma_f32_32x32x16_bf16 v[6:21], v[38:41], v[66:69], 0
	v_mfma_f32_32x32x16_bf16 v[6:21], v[46:49], v[70:73], v[6:21]
	v_mfma_f32_32x32x16_bf16 v[6:21], v[94:97], v[74:77], v[6:21]
	s_waitcnt lgkmcnt(3)
	v_mfma_f32_32x32x16_bf16 v[22:37], v[86:89], v[82:85], v[22:37]
	v_perm_b32 v86, v177, v2, s10
	v_perm_b32 v87, v176, v3, s10
	v_perm_b32 v88, v175, v4, s10
	v_perm_b32 v89, v113, v5, s10
	s_mov_b32 s10, 0xf149f2ca
	v_mfma_f32_32x32x16_bf16 v[6:21], v[98:101], v[78:81], v[6:21]
	s_waitcnt lgkmcnt(1)
	v_mfma_f32_32x32x16_bf16 v[22:37], v[106:109], v[86:89], v[22:37]
	v_mfma_f32_32x32x16_bf16 v[6:21], v[102:105], v[82:85], v[6:21]
	s_nop 10
	v_max_f32_e32 v2, v23, v23
	v_max_f32_e32 v3, v22, v22
	v_max_f32_e32 v2, v3, v2
	v_max3_f32 v2, v2, v24, v25
	v_max3_f32 v2, v2, v26, v27
	v_max3_f32 v2, v2, v28, v29
	v_max3_f32 v2, v2, v30, v31
	s_waitcnt lgkmcnt(0)
	v_mfma_f32_32x32x16_bf16 v[6:21], v[148:151], v[86:89], v[6:21]
	v_max3_f32 v2, v2, v32, v33
	v_max3_f32 v2, v2, v34, v35
	v_max3_f32 v2, v2, v36, v37
	s_nop 8
	v_max3_f32 v2, v2, v6, v7
	v_max3_f32 v2, v2, v8, v9
	v_max3_f32 v2, v2, v10, v11
	v_max3_f32 v2, v2, v12, v13
	v_max3_f32 v2, v2, v14, v15
	v_max3_f32 v2, v2, v16, v17
	v_max3_f32 v2, v2, v18, v19
	v_max3_f32 v2, v2, v20, v21
	ds_bpermute_b32 v3, v166, v2
	v_mov_b32_e32 v148, v21
	s_waitcnt lgkmcnt(0)
	v_max_f32_e32 v3, v3, v3
	v_max_f32_e32 v2, v2, v3
	v_max_f32_e32 v149, 0xf149f2ca, v2
	v_mul_f32_e64 v196, v148, s30
	v_mul_f32_e64 v197, v149, s30
	v_cmp_lt_f32_e32 vcc, s10, v2
	v_fma_f32 v2, v22, s30, -v197
	v_exp_f32_e32 v98, v2
	v_fma_f32 v2, v23, s30, -v197
	v_exp_f32_e32 v99, v2
	v_fma_f32 v2, v24, s30, -v197
	v_exp_f32_e32 v100, v2
	v_fma_f32 v2, v25, s30, -v197
	v_exp_f32_e32 v101, v2
	v_fma_f32 v2, v26, s30, -v197
	v_exp_f32_e32 v102, v2
	v_fma_f32 v2, v27, s30, -v197
	v_exp_f32_e32 v103, v2
	v_fma_f32 v2, v28, s30, -v197
	v_exp_f32_e32 v104, v2
	v_fma_f32 v2, v29, s30, -v197
	v_exp_f32_e32 v105, v2
	v_fma_f32 v2, v30, s30, -v197
	v_exp_f32_e32 v106, v2
	v_fma_f32 v2, v31, s30, -v197
	v_exp_f32_e32 v107, v2
	v_fma_f32 v2, v32, s30, -v197
	v_exp_f32_e32 v108, v2
	v_fma_f32 v2, v33, s30, -v197
	v_exp_f32_e32 v109, v2
	v_fma_f32 v2, v34, s30, -v197
	v_exp_f32_e32 v113, v2
	v_fma_f32 v2, v35, s30, -v197
	v_exp_f32_e32 v148, v2
	v_fma_f32 v2, v36, s30, -v197
	v_exp_f32_e32 v150, v2
	v_fma_f32 v2, v37, s30, -v197
	v_exp_f32_e32 v151, v2
	v_fma_f32 v2, v6, s30, -v197
	v_exp_f32_e32 v175, v2
	v_fma_f32 v2, v7, s30, -v197
	v_exp_f32_e32 v176, v2
	v_fma_f32 v2, v8, s30, -v197
	v_exp_f32_e32 v177, v2
	v_fma_f32 v2, v9, s30, -v197
	v_exp_f32_e32 v178, v2
	v_fma_f32 v2, v10, s30, -v197
	v_exp_f32_e32 v179, v2
	v_fma_f32 v2, v11, s30, -v197
	v_exp_f32_e32 v180, v2
	v_fma_f32 v2, v12, s30, -v197
	v_exp_f32_e32 v181, v2
	v_fma_f32 v2, v13, s30, -v197
	v_exp_f32_e32 v182, v2
	v_fma_f32 v2, v14, s30, -v197
	v_exp_f32_e32 v183, v2
	v_fma_f32 v2, v15, s30, -v197
	v_exp_f32_e32 v184, v2
	v_sub_f32_e32 v2, 0xf149f2ca, v149
	v_mul_f32_e32 v2, 0x3e16c740, v2
	v_exp_f32_e32 v2, v2
	s_cmp_eq_u64 vcc, 0
	s_cselect_b64 s[14:15], -1, 0
	v_fma_f32 v3, v16, s30, -v197
	v_mul_f32_e32 v2, 0, v2
	v_cndmask_b32_e64 v34, v2, 0, s[14:15]
	v_cvt_pk_bf16_f32 v94, v98, v99
	v_cvt_pk_bf16_f32 v95, v100, v101
	v_cvt_pk_bf16_f32 v96, v102, v103
	v_cvt_pk_bf16_f32 v97, v104, v105
	v_mov_b32_e32 v35, v34
	v_mov_b32_e32 v36, v34
	v_mov_b32_e32 v37, v34
	v_mov_b32_e32 v38, v34
	v_mov_b32_e32 v39, v34
	v_mov_b32_e32 v40, v34
	v_mov_b32_e32 v41, v34
	v_mov_b32_e32 v42, v34
	v_mov_b32_e32 v43, v34
	v_mov_b32_e32 v44, v34
	v_mov_b32_e32 v45, v34
	v_mov_b32_e32 v46, v34
	v_mov_b32_e32 v47, v34
	v_mov_b32_e32 v48, v34
	v_mov_b32_e32 v49, v34
	v_exp_f32_e32 v185, v3
	v_fma_f32 v21, v17, s30, -v197
	ds_read_b64_tr_b16 v[192:193], v168 offset:0
	ds_read_b64_tr_b16 v[194:195], v168 offset:1536
	ds_read_b64_tr_b16 v[30:31], v168 offset:3072
	ds_read_b64_tr_b16 v[32:33], v168 offset:4608
	ds_read_b64_tr_b16 v[26:27], v168 offset:6144
	ds_read_b64_tr_b16 v[28:29], v168 offset:7680
	ds_read_b64_tr_b16 v[22:23], v168 offset:9216
	ds_read_b64_tr_b16 v[24:25], v168 offset:10752
	s_waitcnt lgkmcnt(0)
	v_cvt_pk_bf16_f32 v218, v106, v107
	v_mfma_f32_32x32x16_bf16 v[2:17], v[192:195], v[94:97], v[34:49]
	v_cvt_pk_bf16_f32 v219, v108, v109
	v_cvt_pk_bf16_f32 v220, v113, v148
	v_cvt_pk_bf16_f32 v221, v150, v151
	v_fma_f32 v18, v18, s30, -v197
	v_cvt_pk_bf16_f32 v222, v175, v176
	v_cvt_pk_bf16_f32 v223, v177, v178
	v_cvt_pk_bf16_f32 v224, v179, v180
	v_mfma_f32_32x32x16_bf16 v[2:17], v[30:33], v[218:221], v[2:17]
	v_cvt_pk_bf16_f32 v225, v181, v182
	v_exp_f32_e32 v192, v18
	v_fma_f32 v18, v19, s30, -v197
	v_exp_f32_e32 v193, v18
	v_fma_f32 v18, v20, s30, -v197
	v_exp_f32_e32 v194, v18
	v_sub_f32_e32 v18, v196, v197
	v_mfma_f32_32x32x16_bf16 v[2:17], v[26:29], v[222:225], v[2:17]
	v_exp_f32_e32 v189, v21
	v_exp_f32_e32 v195, v18
	v_cvt_pk_bf16_f32 v226, v183, v184
	v_cvt_pk_bf16_f32 v228, v192, v193
	v_cvt_pk_bf16_f32 v227, v185, v189
	v_cvt_pk_bf16_f32 v229, v194, v195
	ds_read_b64_tr_b16 v[242:243], v168 offset:64
	ds_read_b64_tr_b16 v[244:245], v168 offset:1600
	ds_read_b64_tr_b16 v[238:239], v168 offset:3136
	ds_read_b64_tr_b16 v[240:241], v168 offset:4672
	ds_read_b64_tr_b16 v[234:235], v168 offset:6208
	ds_read_b64_tr_b16 v[236:237], v168 offset:7744
	ds_read_b64_tr_b16 v[230:231], v168 offset:9280
	ds_read_b64_tr_b16 v[232:233], v168 offset:10816
	s_waitcnt lgkmcnt(0)
; DI unsigned pk2(float a, float b) { f32x2 v = {a, b}; bf2_t r = __builtin_convertvector(v, bf2_t); return __builtin_bit_cast(unsigned, r); }
; template <int DQK, int DV, int KW0, int MODE> ...
;     ...
;     float mx = S0[0];
; #pragma unroll
;     for (int e = 1; e < 16; ++e) mx = fmaxf(mx, S0[e]);
; #pragma unroll
;     for (int e = 0; e < 16; ++e) mx = fmaxf(mx, S1[e]);
;     mx = fmaxf(mx, __shfl_xor(mx, 32));
;     const float mn = fmaxf(m, mx);
;     const bool grow = __builtin_amdgcn_ballot_w64(mx > m) != 0ull;
;     const float alpha = __builtin_amdgcn_exp2f((m - mn) * c);
;     m = mn;
;     const float mc = mn * c;
;     float ps = 0.f;
; #pragma unroll
;     for (int e = 0; e < 16; ++e) { S0[e] = __builtin_amdgcn_exp2f(S0[e] * c - mc); ps += S0[e]; }
; #pragma unroll
;     for (int e = 0; e < 16; ++e) { S1[e] = __builtin_amdgcn_exp2f(S1[e] * c - mc); ps += S1[e]; }
;     if (grow) {
;       l *= alpha;
; #pragma unroll
;       for (int t = 0; t < DV / 32; ++t)
; #pragma unroll
;         for (int e = 0; e < 16; ++e) O[t][e] *= alpha;
;     }
;     l += ps;
;     bf16x8 pf[2][2];
; #pragma unroll
;     for (int s = 0; s < 2; ++s) {
;       u32x4 w0, w1;
;       w0.x = pk2(S0[8 * s + 0], S0[8 * s + 1]); w0.y = pk2(S0[8 * s + 2], S0[8 * s + 3]); w0.z = pk2(S0[8 * s + 4], S0[8 * s + 5]); w0.w = pk2(S0[8 * s + 6], S0[8 * s + 7]);
;       w1.x = pk2(S1[8 * s + 0], S1[8 * s + 1]); w1.y = pk2(S1[8 * s + 2], S1[8 * s + 3]); w1.z = pk2(S1[8 * s + 4], S1[8 * s + 5]); w1.w = pk2(S1[8 * s + 6], S1[8 * s + 7]);
;       pf[0][s] = __builtin_bit_cast(bf16x8, w0); pf[1][s] = __builtin_bit_cast(bf16x8, w1);
;     }
;     {
;       const unsigned vaddr = (unsigned)(size_t)(cur + KB) + (unsigned)((4 * h + ((lane & 15) >> 2)) * VSB + ((lane >> 4) & 1) * 32 + (lane & 3) * 8);
;       if (DV == 64) {
;         s16x4 R[8];
;     ...
;         PV_TILE64_(0); PV_TILE64_(1);
;     ...
;       } else {
;         s16x4 R[8];
;     ...
;         PV_TILE_(0); PV_TILE_(1); PV_TILE_(2); PV_TILE_(3);
;     ...
;       }
;     }
;     if (DV > 64) { __builtin_amdgcn_sched_barrier(0); if (more) attn_gload<DQK, DV, KW0, 3>(kreg, vreg, k0p, ldk0, k1p, ldk1, vp, ldv, key_tile_row<MODE>(it + 1, b, qn, wlo), tid); }
;     if (more) attn_sstore<DQK, DV>(kreg, vreg, smem + ((it + 1) & 1) * STG, tid);
	s_add_i32 s14, s19, 0x10080
	s_waitcnt vmcnt(4)
	ds_write_b128 v170, v[50:53] offset:25600
	v_mfma_f32_32x32x16_bf16 v[2:17], v[22:25], v[226:229], v[2:17]
	v_mov_b64_e32 v[18:19], v[34:35]
	v_mov_b64_e32 v[20:21], v[36:37]
	v_mov_b64_e32 v[22:23], v[38:39]
	v_mov_b64_e32 v[24:25], v[40:41]
	v_mov_b64_e32 v[26:27], v[42:43]
	v_mov_b64_e32 v[28:29], v[44:45]
	v_mov_b64_e32 v[30:31], v[46:47]
	v_mov_b64_e32 v[32:33], v[48:49]
	v_add_u32_e32 v38, s14, v152
	v_ashrrev_i32_e32 v39, 31, v38
	v_mfma_f32_32x32x16_bf16 v[18:33], v[242:245], v[94:97], v[18:33]
	s_waitcnt vmcnt(3)
	ds_write_b128 v171, v[54:57] offset:25600
	s_waitcnt vmcnt(2)
	ds_write_b128 v172, v[58:61] offset:25600
	s_waitcnt vmcnt(1)
	ds_write_b128 v173, v[62:65] offset:38912
	s_waitcnt vmcnt(0)
	ds_write_b128 v173, v[90:93] offset:39104
	s_waitcnt lgkmcnt(0)
	s_barrier
	v_mfma_f32_32x32x16_bf16 v[18:33], v[238:241], v[218:221], v[18:33]
	v_mfma_f32_32x32x16_bf16 v[18:33], v[234:237], v[222:225], v[18:33]
	v_mfma_f32_32x32x16_bf16 v[18:33], v[230:233], v[226:229], v[18:33]
	s_and_saveexec_b64 s[16:17], s[40:41]
	s_xor_b64 s[16:17], exec, s[16:17]
	s_movk_i32 s10, 0xff80
	v_mad_i64_i32 v[36:37], s[46:47], v38, s35, v[116:117]
	s_mov_b32 s11, -1
	v_lshl_add_u64 v[36:37], v[36:37], 0, s[10:11]
	s_andn2_saveexec_b64 s[16:17], s[16:17]
	v_lshlrev_b64 v[36:37], 11, v[38:39]
	v_lshl_add_u64 v[36:37], v[142:143], 0, v[36:37]
	s_or_b64 exec, exec, s[16:17]
	global_load_dwordx4 v[90:93], v[36:37], off
	v_add_u32_e32 v38, s14, v153
	v_ashrrev_i32_e32 v39, 31, v38
	s_and_saveexec_b64 s[16:17], s[42:43]
	s_xor_b64 s[16:17], exec, s[16:17]
	s_movk_i32 s10, 0xff80
	v_mad_i64_i32 v[36:37], s[46:47], v38, s35, v[120:121]
	s_mov_b32 s11, -1
	v_lshl_add_u64 v[36:37], v[36:37], 0, s[10:11]
	s_andn2_saveexec_b64 s[16:17], s[16:17]
	v_lshlrev_b64 v[36:37], 11, v[38:39]
	v_lshl_add_u64 v[36:37], v[144:145], 0, v[36:37]
	s_or_b64 exec, exec, s[16:17]
	global_load_dwordx4 v[94:97], v[36:37], off
	v_add_u32_e32 v38, s14, v154
	v_ashrrev_i32_e32 v39, 31, v38
	s_and_saveexec_b64 s[16:17], s[44:45]
	s_xor_b64 s[16:17], exec, s[16:17]
	s_movk_i32 s10, 0xff80
	v_mad_i64_i32 v[36:37], s[46:47], v38, s35, v[126:127]
	s_mov_b32 s11, -1
	v_lshl_add_u64 v[36:37], v[36:37], 0, s[10:11]
	s_andn2_saveexec_b64 s[16:17], s[16:17]
	v_lshlrev_b64 v[36:37], 11, v[38:39]
	v_lshl_add_u64 v[36:37], v[146:147], 0, v[36:37]
	s_or_b64 exec, exec, s[16:17]
	v_add_f32_e32 v35, 0, v98
	v_add_f32_e32 v35, v99, v35
	v_add_f32_e32 v35, v100, v35
	v_add_f32_e32 v35, v101, v35
	v_add_f32_e32 v35, v102, v35
	v_add_f32_e32 v35, v103, v35
	v_add_f32_e32 v35, v104, v35
	v_add_f32_e32 v35, v105, v35
	v_add_f32_e32 v35, v106, v35
	v_add_f32_e32 v35, v107, v35
	v_add_f32_e32 v35, v108, v35
	v_add_f32_e32 v35, v109, v35
	v_add_f32_e32 v35, v113, v35
	v_add_f32_e32 v35, v148, v35
	v_add_f32_e32 v35, v150, v35
	v_add_f32_e32 v35, v151, v35
	v_add_f32_e32 v35, v175, v35
	v_add_f32_e32 v35, v176, v35
	v_add_f32_e32 v35, v177, v35
	v_add_f32_e32 v35, v178, v35
	v_add_f32_e32 v35, v179, v35
	v_add_f32_e32 v35, v180, v35
	v_add_f32_e32 v35, v181, v35
	v_add_f32_e32 v35, v182, v35
	v_add_f32_e32 v35, v183, v35
	v_add_f32_e32 v35, v184, v35
	v_add_f32_e32 v35, v185, v35
	v_add_f32_e32 v35, v189, v35
	v_add_f32_e32 v35, v192, v35
	s_ashr_i32 s15, s14, 31
	v_add_f32_e32 v35, v193, v35
	s_lshl_b64 s[14:15], s[14:15], 11
	v_add_f32_e32 v35, v194, v35
	s_add_u32 s14, s12, s14
	v_add_f32_e32 v35, v195, v35
	s_addc_u32 s15, s13, s15
	v_add_f32_e32 v113, v35, v34
	v_lshl_add_u64 v[34:35], s[14:15], 0, v[138:139]
	global_load_dwordx4 v[102:105], v[34:35], off offset:128
	v_lshl_add_u64 v[34:35], s[14:15], 0, v[140:141]
	global_load_dwordx4 v[98:101], v[36:37], off
	global_load_dwordx4 v[106:109], v[34:35], off offset:128
	ds_read_b128 v[38:41], v174 offset:25600
	ds_read_b128 v[42:45], v174 offset:25632
	ds_read_b128 v[34:37], v174 offset:32256
	ds_read_b128 v[176:179], v174 offset:32288
	ds_read_b128 v[46:49], v174 offset:25664
	ds_read_b128 v[180:183], v174 offset:32320
	ds_read_b128 v[192:195], v174 offset:25696
	ds_read_b128 v[218:221], v174 offset:32352
	ds_read_b128 v[222:225], v174 offset:25728
	ds_read_b128 v[226:229], v174 offset:32384
	ds_read_b128 v[230:233], v174 offset:25760
	ds_read_b128 v[234:237], v174 offset:32416
	s_waitcnt lgkmcnt(11)
	v_mfma_f32_32x32x16_bf16 v[50:65], v[38:41], v[66:69], 0
	s_waitcnt lgkmcnt(10)
	v_mfma_f32_32x32x16_bf16 v[50:65], v[42:45], v[70:73], v[50:65]
	s_waitcnt lgkmcnt(7)
	v_mfma_f32_32x32x16_bf16 v[50:65], v[46:49], v[74:77], v[50:65]
	v_mfma_f32_32x32x16_bf16 v[34:49], v[34:37], v[66:69], 0
	v_mfma_f32_32x32x16_bf16 v[34:49], v[176:179], v[70:73], v[34:49]
	s_waitcnt lgkmcnt(5)
	v_mfma_f32_32x32x16_bf16 v[50:65], v[192:195], v[78:81], v[50:65]
	v_mfma_f32_32x32x16_bf16 v[34:49], v[180:183], v[74:77], v[34:49]
	s_waitcnt lgkmcnt(3)
	v_mfma_f32_32x32x16_bf16 v[50:65], v[222:225], v[82:85], v[50:65]
	v_mfma_f32_32x32x16_bf16 v[34:49], v[218:221], v[78:81], v[34:49]
	s_waitcnt lgkmcnt(1)
	v_mfma_f32_32x32x16_bf16 v[50:65], v[230:233], v[86:89], v[50:65]
	v_mfma_f32_32x32x16_bf16 v[34:49], v[226:229], v[82:85], v[34:49]
	s_nop 10
	v_max_f32_e32 v148, v51, v51
	v_max_f32_e32 v150, v50, v50
	v_max_f32_e32 v148, v150, v148
	v_max3_f32 v148, v148, v52, v53
	v_max3_f32 v148, v148, v54, v55
	v_max3_f32 v148, v148, v56, v57
	v_max3_f32 v148, v148, v58, v59
	s_waitcnt lgkmcnt(0)
	v_mfma_f32_32x32x16_bf16 v[34:49], v[234:237], v[86:89], v[34:49]
	v_max3_f32 v148, v148, v60, v61
	v_max3_f32 v148, v148, v62, v63
	v_max3_f32 v148, v148, v64, v65
	s_nop 8
	v_max3_f32 v148, v148, v34, v35
	v_max3_f32 v148, v148, v36, v37
	v_max3_f32 v148, v148, v38, v39
	v_max3_f32 v148, v148, v40, v41
	v_max3_f32 v148, v148, v42, v43
	v_max3_f32 v148, v148, v44, v45
	v_max3_f32 v148, v148, v46, v47
	v_max3_f32 v148, v148, v48, v49
	ds_bpermute_b32 v150, v166, v148
	s_waitcnt lgkmcnt(0)
	v_max_f32_e32 v150, v150, v150
	v_max_f32_e32 v150, v148, v150
	v_max_f32_e32 v148, v149, v149
	v_max_f32_e32 v148, v148, v150
	v_cmp_gt_f32_e32 vcc, v150, v149
	s_cbranch_vccz .LBB0_105
; DI unsigned pk2(float a, float b) { f32x2 v = {a, b}; bf2_t r = __builtin_convertvector(v, bf2_t); return __builtin_bit_cast(unsigned, r); }
; #define PV_TILE64_(T) do { TRV8_192_T##T(R, vaddr); \
;           _Pragma("unroll") for (int st = 0; st < 2; ++st) _Pragma("unroll") for (int s = 0; s < 2; ++s) { const int ix = (st * 2 + s) * 2; \
;             const bf16x8 va = __builtin_shufflevector(R[ix], R[ix + 1], 0, 1, 2, 3, 4, 5, 6, 7); O[T] = mfma32(va, pf[st][s], O[T]); } } while (0)
; template <int DQK, int DV, int KW0, int MODE> ...
;     ...
;     for (int e = 0; e < 16; ++e) { S0[e] = __builtin_amdgcn_exp2f(S0[e] * c - mc); ps += S0[e]; }
; #pragma unroll
;     for (int e = 0; e < 16; ++e) { S1[e] = __builtin_amdgcn_exp2f(S1[e] * c - mc); ps += S1[e]; }
;     if (grow) {
;       l *= alpha;
; #pragma unroll
;       for (int t = 0; t < DV / 32; ++t)
; #pragma unroll
;         for (int e = 0; e < 16; ++e) O[t][e] *= alpha;
;     }
;     l += ps;
;     bf16x8 pf[2][2];
; #pragma unroll
;     for (int s = 0; s < 2; ++s) {
;       u32x4 w0, w1;
;       w0.x = pk2(S0[8 * s + 0], S0[8 * s + 1]); w0.y = pk2(S0[8 * s + 2], S0[8 * s + 3]); w0.z = pk2(S0[8 * s + 4], S0[8 * s + 5]); w0.w = pk2(S0[8 * s + 6], S0[8 * s + 7]);
;       w1.x = pk2(S1[8 * s + 0], S1[8 * s + 1]); w1.y = pk2(S1[8 * s + 2], S1[8 * s + 3]); w1.z = pk2(S1[8 * s + 4], S1[8 * s + 5]); w1.w = pk2(S1[8 * s + 6], S1[8 * s + 7]);
;       pf[0][s] = __builtin_bit_cast(bf16x8, w0); pf[1][s] = __builtin_bit_cast(bf16x8, w1);
;     }
;     {
;       const unsigned vaddr = (unsigned)(size_t)(cur + KB) + (unsigned)((4 * h + ((lane & 15) >> 2)) * VSB + ((lane >> 4) & 1) * 32 + (lane & 3) * 8);
;       if (DV == 64) {
;         s16x4 R[8];
;     ...
;         PV_TILE64_(0); PV_TILE64_(1);
;     ...
;       } else {
;         s16x4 R[8];
;     ...
;         PV_TILE_(0); PV_TILE_(1); PV_TILE_(2); PV_TILE_(3);
;     ...
;       }
;     }
;     if (DV > 64) { __builtin_amdgcn_sched_barrier(0); if (more) attn_gload<DQK, DV, KW0, 3>(kreg, vreg, k0p, ldk0, k1p, ldk1, vp, ldv, key_tile_row<MODE>(it + 1, b, qn, wlo), tid); }
;     if (more) attn_sstore<DQK, DV>(kreg, vreg, smem + ((it + 1) & 1) * STG, tid);
	v_sub_f32_e32 v149, v149, v148
	v_mul_f32_e32 v149, 0x3e16c740, v149
	v_exp_f32_e32 v150, v149
	s_nop 0
	v_mul_f32_e32 v32, v32, v150
	v_mul_f32_e32 v33, v33, v150
	v_mul_f32_e32 v30, v30, v150
	v_mul_f32_e32 v31, v31, v150
	v_mul_f32_e32 v28, v28, v150
	v_mul_f32_e32 v29, v29, v150
	v_mul_f32_e32 v26, v26, v150
	v_mul_f32_e32 v27, v27, v150
	v_mul_f32_e32 v24, v24, v150
	v_mul_f32_e32 v25, v25, v150
	v_mul_f32_e32 v22, v22, v150
	v_mul_f32_e32 v23, v23, v150
	v_mul_f32_e32 v20, v20, v150
	v_mul_f32_e32 v21, v21, v150
	v_mul_f32_e32 v18, v18, v150
	v_mul_f32_e32 v19, v19, v150
	v_mul_f32_e32 v16, v16, v150
	v_mul_f32_e32 v17, v17, v150
	v_mul_f32_e32 v14, v14, v150
	v_mul_f32_e32 v15, v15, v150
	v_mul_f32_e32 v12, v12, v150
	v_mul_f32_e32 v13, v13, v150
	v_mul_f32_e32 v10, v10, v150
	v_mul_f32_e32 v11, v11, v150
	v_mul_f32_e32 v8, v8, v150
	v_mul_f32_e32 v9, v9, v150
	v_mul_f32_e32 v6, v6, v150
	v_mul_f32_e32 v7, v7, v150
	v_mul_f32_e32 v4, v4, v150
	v_mul_f32_e32 v5, v5, v150
	v_mul_f32_e32 v2, v2, v150
	v_mul_f32_e32 v3, v3, v150
	v_mul_f32_e32 v113, v113, v150
.LBB0_105:
	v_mul_f32_e32 v176, 0x3e16c740, v148
	v_fma_f32 v34, v34, s30, -v176
	v_exp_f32_e32 v149, v34
	v_fma_f32 v34, v35, s30, -v176
	v_exp_f32_e32 v150, v34
	v_fma_f32 v34, v36, s30, -v176
	v_exp_f32_e32 v151, v34
	v_fma_f32 v34, v37, s30, -v176
	v_exp_f32_e32 v175, v34
	v_fma_f32 v34, v38, s30, -v176
	v_exp_f32_e32 v38, v34
	v_fma_f32 v34, v39, s30, -v176
	v_exp_f32_e32 v39, v34
	v_fma_f32 v34, v40, s30, -v176
	v_exp_f32_e32 v40, v34
	v_fma_f32 v34, v41, s30, -v176
	v_exp_f32_e32 v41, v34
	v_fma_f32 v34, v42, s30, -v176
	v_exp_f32_e32 v42, v34
	v_fma_f32 v34, v43, s30, -v176
	v_exp_f32_e32 v43, v34
	v_fma_f32 v34, v44, s30, -v176
	v_fma_f32 v50, v50, s30, -v176
	v_fma_f32 v51, v51, s30, -v176
	v_fma_f32 v52, v52, s30, -v176
	v_fma_f32 v53, v53, s30, -v176
	v_fma_f32 v54, v54, s30, -v176
	v_fma_f32 v55, v55, s30, -v176
	v_fma_f32 v56, v56, s30, -v176
	v_fma_f32 v57, v57, s30, -v176
	v_exp_f32_e32 v44, v34
	v_fma_f32 v34, v45, s30, -v176
	v_exp_f32_e32 v50, v50
	v_exp_f32_e32 v51, v51
	v_exp_f32_e32 v52, v52
	v_exp_f32_e32 v53, v53
	v_exp_f32_e32 v54, v54
	v_exp_f32_e32 v55, v55
	v_exp_f32_e32 v56, v56
	v_exp_f32_e32 v57, v57
	v_exp_f32_e32 v45, v34
	v_fma_f32 v34, v46, s30, -v176
	v_exp_f32_e32 v46, v34
	v_fma_f32 v34, v47, s30, -v176
	v_exp_f32_e32 v47, v34
	v_fma_f32 v34, v48, s30, -v176
	v_exp_f32_e32 v48, v34
	v_fma_f32 v34, v49, s30, -v176
	v_exp_f32_e32 v49, v34
	v_cvt_pk_bf16_f32 v34, v50, v51
	v_cvt_pk_bf16_f32 v35, v52, v53
	v_cvt_pk_bf16_f32 v36, v54, v55
	v_cvt_pk_bf16_f32 v37, v56, v57
	ds_read_b64_tr_b16 v[230:231], v169 offset:0
	ds_read_b64_tr_b16 v[232:233], v169 offset:1536
	ds_read_b64_tr_b16 v[226:227], v169 offset:3072
	ds_read_b64_tr_b16 v[228:229], v169 offset:4608
	ds_read_b64_tr_b16 v[222:223], v169 offset:6144
	ds_read_b64_tr_b16 v[224:225], v169 offset:7680
	ds_read_b64_tr_b16 v[218:219], v169 offset:9216
	ds_read_b64_tr_b16 v[220:221], v169 offset:10752
	s_waitcnt lgkmcnt(0)
	v_fma_f32 v58, v58, s30, -v176
	v_fma_f32 v59, v59, s30, -v176
	v_mfma_f32_32x32x16_bf16 v[2:17], v[230:233], v[34:37], v[2:17]
	v_fma_f32 v60, v60, s30, -v176
	v_fma_f32 v61, v61, s30, -v176
	v_fma_f32 v62, v62, s30, -v176
	v_fma_f32 v63, v63, s30, -v176
	v_fma_f32 v64, v64, s30, -v176
	v_fma_f32 v65, v65, s30, -v176
	v_exp_f32_e32 v58, v58
	v_exp_f32_e32 v59, v59
	v_exp_f32_e32 v60, v60
	v_exp_f32_e32 v61, v61
	v_exp_f32_e32 v62, v62
	v_exp_f32_e32 v63, v63
	v_exp_f32_e32 v64, v64
	v_exp_f32_e32 v65, v65
	v_cvt_pk_bf16_f32 v180, v58, v59
	v_cvt_pk_bf16_f32 v181, v60, v61
	v_cvt_pk_bf16_f32 v182, v62, v63
	v_cvt_pk_bf16_f32 v183, v64, v65
	v_cvt_pk_bf16_f32 v176, v149, v150
	v_cvt_pk_bf16_f32 v177, v151, v175
	v_mfma_f32_32x32x16_bf16 v[2:17], v[226:229], v[180:183], v[2:17]
	v_cvt_pk_bf16_f32 v178, v38, v39
	v_cvt_pk_bf16_f32 v179, v40, v41
	v_cvt_pk_bf16_f32 v192, v42, v43
	v_cvt_pk_bf16_f32 v193, v44, v45
	v_cvt_pk_bf16_f32 v194, v46, v47
	v_cvt_pk_bf16_f32 v195, v48, v49
	s_add_i32 s14, s19, 0x100c0
	v_mfma_f32_32x32x16_bf16 v[2:17], v[222:225], v[176:179], v[2:17]
	v_mfma_f32_32x32x16_bf16 v[2:17], v[218:221], v[192:195], v[2:17]
	ds_read_b64_tr_b16 v[230:231], v169 offset:64
	ds_read_b64_tr_b16 v[232:233], v169 offset:1600
	ds_read_b64_tr_b16 v[226:227], v169 offset:3136
	ds_read_b64_tr_b16 v[228:229], v169 offset:4672
	ds_read_b64_tr_b16 v[222:223], v169 offset:6208
	ds_read_b64_tr_b16 v[224:225], v169 offset:7744
	ds_read_b64_tr_b16 v[218:219], v169 offset:9280
	ds_read_b64_tr_b16 v[220:221], v169 offset:10816
	s_waitcnt lgkmcnt(0)
	s_waitcnt vmcnt(4)
	ds_write_b128 v170, v[90:93]
	s_waitcnt vmcnt(3)
	ds_write_b128 v171, v[94:97]
	s_waitcnt vmcnt(1)
	ds_write_b128 v172, v[98:101]
	ds_write_b128 v173, v[102:105] offset:13312
	s_waitcnt vmcnt(0)
	ds_write_b128 v173, v[106:109] offset:13504
	s_waitcnt lgkmcnt(0)
	s_barrier
; template <int DQK, int DV, int KW0, int MODE> ...
;     ...
;   for (int it = 0; it < nkt; ++it) {
;     const char* cur = smem + (it & 1) * STG;
;     const bool more = (it + 1 < nkt);
;     if (DV <= 64) { if (more) attn_gload<DQK, DV, KW0, 3>(kreg, vreg, k0p, ldk0, k1p, ldk1, vp, ldv, key_tile_row<MODE>(it + 1, b, qn, wlo), tid); __builtin_amdgcn_sched_barrier(0); }
;     f32x16 S0, S1;
; #pragma unroll
;     for (int e = 0; e < 16; ++e) { S0[e] = 0.f; S1[e] = 0.f; }
;     {
;       bf16x8 kfa[DQK / 16], kfb[DQK / 16], qv[DQK / 16];
; #pragma unroll
;       for (int kk = 0; kk < DQK / 16; ++kk) {
;         kfa[kk] = *(const bf16x8*)(cur + r * (KS * 2) + kk * 32 + h * 16);
;         kfb[kk] = *(const bf16x8*)(cur + (32 + r) * (KS * 2) + kk * 32 + h * 16);
;         qv[kk] = QLDS ? *(const bf16x8*)(qbase + kk * 1024) : qf[kk];
;       }
; #pragma unroll
;       for (int kk = 0; kk < DQK / 16; ++kk) {
;         S0 = mfma32(kfa[kk], qv[kk], S0);
;         S1 = mfma32(kfb[kk], qv[kk], S1);
;       }
;       __builtin_amdgcn_sched_group_barrier(0x100, (QLDS ? 3 : 2) * (DQK / 16), 0);
;       __builtin_amdgcn_sched_group_barrier(0x008, 2 * (DQK / 16), 0);
;     }
;     if (MODE == 2) {
;       if (it >= 4) {
;         const int w = wlo + it - 4;
;         if (w < 2 || w > 3) {
;           const int kpos0 = (qn - 1) * 128 + 64 * w, qpos = qn * 128 + wid * 32 + r;
; #pragma unroll
;           for (int e = 0; e < 16; ++e) {
;             const int d0 = qpos - (kpos0 + crow(e, h)), d1 = d0 - 32;
;             if (d0 > 128 || d0 < -128) S0[e] = -1e30f;
;             if (d1 > 128 || d1 < -128) S1[e] = -1e30f;
;           }
;         }
;       }
;     }
;     float mx = S0[0];
; #pragma unroll
;     for (int e = 1; e < 16; ++e) mx = fmaxf(mx, S0[e]);
; #pragma unroll
;     for (int e = 0; e < 16; ++e) mx = fmaxf(mx, S1[e]);
;     mx = fmaxf(mx, __shfl_xor(mx, 32));
;     const float mn = fmaxf(m, mx);
;     const bool grow = __builtin_amdgcn_ballot_w64(mx > m) != 0ull;
;     const float alpha = __builtin_amdgcn_exp2f((m - mn) * c);
;     m = mn;
;     const float mc = mn * c;
;     float ps = 0.f;
; #pragma unroll
;     for (int e = 0; e < 16; ++e) { S0[e] = __builtin_amdgcn_exp2f(S0[e] * c - mc); ps += S0[e]; }
; #pragma unroll
;     for (int e = 0; e < 16; ++e) { S1[e] = __builtin_amdgcn_exp2f(S1[e] * c - mc); ps += S1[e]; }
;     if (grow) {
;       l *= alpha;
	v_mfma_f32_32x32x16_bf16 v[18:33], v[230:233], v[34:37], v[18:33]
	v_add_u32_e32 v36, s14, v152
	v_ashrrev_i32_e32 v37, 31, v36
	v_mfma_f32_32x32x16_bf16 v[18:33], v[226:229], v[180:183], v[18:33]
	v_mfma_f32_32x32x16_bf16 v[18:33], v[222:225], v[176:179], v[18:33]
	v_mfma_f32_32x32x16_bf16 v[18:33], v[218:221], v[192:195], v[18:33]
	s_and_saveexec_b64 s[16:17], s[40:41]
	s_xor_b64 s[16:17], exec, s[16:17]
	s_movk_i32 s10, 0xff80
	v_mad_i64_i32 v[34:35], s[46:47], v36, s35, v[116:117]
	s_mov_b32 s11, -1
	v_lshl_add_u64 v[34:35], v[34:35], 0, s[10:11]
	s_andn2_saveexec_b64 s[16:17], s[16:17]
	v_lshlrev_b64 v[34:35], 11, v[36:37]
	v_lshl_add_u64 v[34:35], v[142:143], 0, v[34:35]
	s_or_b64 exec, exec, s[16:17]
	global_load_dwordx4 v[90:93], v[34:35], off
	v_add_u32_e32 v36, s14, v153
	v_ashrrev_i32_e32 v37, 31, v36
	s_and_saveexec_b64 s[16:17], s[42:43]
	s_xor_b64 s[16:17], exec, s[16:17]
	s_movk_i32 s10, 0xff80
	v_mad_i64_i32 v[34:35], s[46:47], v36, s35, v[120:121]
	s_mov_b32 s11, -1
	v_lshl_add_u64 v[34:35], v[34:35], 0, s[10:11]
	s_andn2_saveexec_b64 s[16:17], s[16:17]
	v_lshlrev_b64 v[34:35], 11, v[36:37]
	v_lshl_add_u64 v[34:35], v[144:145], 0, v[34:35]
	s_or_b64 exec, exec, s[16:17]
	global_load_dwordx4 v[94:97], v[34:35], off
	v_add_u32_e32 v36, s14, v154
	v_ashrrev_i32_e32 v37, 31, v36
	s_and_saveexec_b64 s[16:17], s[44:45]
	s_xor_b64 s[16:17], exec, s[16:17]
	s_movk_i32 s10, 0xff80
	v_mad_i64_i32 v[34:35], s[46:47], v36, s35, v[126:127]
	s_mov_b32 s11, -1
	v_lshl_add_u64 v[34:35], v[34:35], 0, s[10:11]
	s_andn2_saveexec_b64 s[16:17], s[16:17]
	v_lshlrev_b64 v[34:35], 11, v[36:37]
	v_lshl_add_u64 v[34:35], v[146:147], 0, v[34:35]
	s_or_b64 exec, exec, s[16:17]
	s_ashr_i32 s15, s14, 31
	s_lshl_b64 s[14:15], s[14:15], 11
	s_add_u32 s14, s12, s14
	s_addc_u32 s15, s13, s15
	global_load_dwordx4 v[98:101], v[34:35], off
	v_lshl_add_u64 v[34:35], s[14:15], 0, v[138:139]
	global_load_dwordx4 v[102:105], v[34:35], off offset:128
	v_lshl_add_u64 v[34:35], s[14:15], 0, v[140:141]
	global_load_dwordx4 v[106:109], v[34:35], off offset:128
	v_add_f32_e32 v36, 0, v50
	v_add_f32_e32 v36, v51, v36
	v_add_f32_e32 v36, v52, v36
	v_add_f32_e32 v36, v53, v36
	v_add_f32_e32 v36, v54, v36
	v_add_f32_e32 v36, v55, v36
	v_add_f32_e32 v36, v56, v36
	v_add_f32_e32 v36, v57, v36
	v_add_f32_e32 v36, v58, v36
	v_add_f32_e32 v36, v59, v36
	v_add_f32_e32 v36, v60, v36
	v_add_f32_e32 v36, v61, v36
	v_add_f32_e32 v36, v62, v36
	v_add_f32_e32 v36, v63, v36
	v_add_f32_e32 v36, v64, v36
	v_add_f32_e32 v36, v65, v36
	v_add_f32_e32 v36, v149, v36
	v_add_f32_e32 v36, v150, v36
	v_add_f32_e32 v36, v151, v36
	v_add_f32_e32 v36, v175, v36
	v_add_f32_e32 v36, v38, v36
	v_add_f32_e32 v36, v39, v36
	v_add_f32_e32 v36, v40, v36
	v_add_f32_e32 v36, v41, v36
	v_add_f32_e32 v36, v42, v36
	v_add_f32_e32 v36, v43, v36
	v_add_f32_e32 v36, v44, v36
	v_add_f32_e32 v36, v45, v36
	v_add_f32_e32 v36, v46, v36
	v_add_f32_e32 v36, v47, v36
	v_add_f32_e32 v36, v48, v36
	v_add_f32_e32 v36, v49, v36
	v_add_f32_e32 v113, v36, v113
	ds_read_b128 v[38:41], v174
	ds_read_b128 v[42:45], v174 offset:32
	ds_read_b128 v[34:37], v174 offset:6656
	ds_read_b128 v[176:179], v174 offset:6688
	ds_read_b128 v[46:49], v174 offset:64
	ds_read_b128 v[180:183], v174 offset:6720
	ds_read_b128 v[192:195], v174 offset:96
	ds_read_b128 v[218:221], v174 offset:6752
	ds_read_b128 v[222:225], v174 offset:128
	ds_read_b128 v[226:229], v174 offset:6784
	ds_read_b128 v[230:233], v174 offset:160
	ds_read_b128 v[234:237], v174 offset:6816
	s_waitcnt lgkmcnt(11)
	v_mfma_f32_32x32x16_bf16 v[50:65], v[38:41], v[66:69], 0
	s_waitcnt lgkmcnt(10)
	v_mfma_f32_32x32x16_bf16 v[50:65], v[42:45], v[70:73], v[50:65]
	s_waitcnt lgkmcnt(7)
	v_mfma_f32_32x32x16_bf16 v[50:65], v[46:49], v[74:77], v[50:65]
	v_mfma_f32_32x32x16_bf16 v[34:49], v[34:37], v[66:69], 0
	v_mfma_f32_32x32x16_bf16 v[34:49], v[176:179], v[70:73], v[34:49]
	s_waitcnt lgkmcnt(5)
	v_mfma_f32_32x32x16_bf16 v[50:65], v[192:195], v[78:81], v[50:65]
	v_mfma_f32_32x32x16_bf16 v[34:49], v[180:183], v[74:77], v[34:49]
	s_waitcnt lgkmcnt(3)
	v_mfma_f32_32x32x16_bf16 v[50:65], v[222:225], v[82:85], v[50:65]
	v_mfma_f32_32x32x16_bf16 v[34:49], v[218:221], v[78:81], v[34:49]
	s_waitcnt lgkmcnt(1)
	v_mfma_f32_32x32x16_bf16 v[50:65], v[230:233], v[86:89], v[50:65]
	v_mfma_f32_32x32x16_bf16 v[34:49], v[226:229], v[82:85], v[34:49]
	s_nop 10
	v_max_f32_e32 v149, v51, v51
	v_max_f32_e32 v150, v50, v50
	v_max_f32_e32 v149, v150, v149
	v_max3_f32 v149, v149, v52, v53
	v_max3_f32 v149, v149, v54, v55
	v_max3_f32 v149, v149, v56, v57
	v_max3_f32 v149, v149, v58, v59
	s_waitcnt lgkmcnt(0)
	v_mfma_f32_32x32x16_bf16 v[34:49], v[234:237], v[86:89], v[34:49]
	v_max3_f32 v149, v149, v60, v61
	v_max3_f32 v149, v149, v62, v63
	v_max3_f32 v149, v149, v64, v65
	s_nop 8
	v_max3_f32 v149, v149, v34, v35
	v_max3_f32 v149, v149, v36, v37
	v_max3_f32 v149, v149, v38, v39
	v_max3_f32 v149, v149, v40, v41
	v_max3_f32 v149, v149, v42, v43
	v_max3_f32 v149, v149, v44, v45
	v_max3_f32 v149, v149, v46, v47
	v_max3_f32 v149, v149, v48, v49
	ds_bpermute_b32 v150, v166, v149
	s_waitcnt lgkmcnt(0)
	v_max_f32_e32 v150, v150, v150
	v_max_f32_e32 v150, v149, v150
	v_max_f32_e32 v149, v148, v148
	v_max_f32_e32 v149, v149, v150
	v_cmp_gt_f32_e32 vcc, v150, v148
	s_cbranch_vccz .LBB0_119
	v_sub_f32_e32 v148, v148, v149
	v_mul_f32_e32 v148, 0x3e16c740, v148
	v_exp_f32_e32 v148, v148
	s_nop 0
	v_mul_f32_e32 v32, v32, v148
	v_mul_f32_e32 v33, v33, v148
	v_mul_f32_e32 v30, v30, v148
	v_mul_f32_e32 v31, v31, v148
	v_mul_f32_e32 v28, v28, v148
	v_mul_f32_e32 v29, v29, v148
	v_mul_f32_e32 v26, v26, v148
	v_mul_f32_e32 v27, v27, v148
	v_mul_f32_e32 v24, v24, v148
	v_mul_f32_e32 v25, v25, v148
	v_mul_f32_e32 v22, v22, v148
	v_mul_f32_e32 v23, v23, v148
	v_mul_f32_e32 v20, v20, v148
	v_mul_f32_e32 v21, v21, v148
	v_mul_f32_e32 v18, v18, v148
	v_mul_f32_e32 v19, v19, v148
	v_mul_f32_e32 v16, v16, v148
	v_mul_f32_e32 v17, v17, v148
	v_mul_f32_e32 v14, v14, v148
	v_mul_f32_e32 v15, v15, v148
	v_mul_f32_e32 v12, v12, v148
	v_mul_f32_e32 v13, v13, v148
	v_mul_f32_e32 v10, v10, v148
	v_mul_f32_e32 v11, v11, v148
	v_mul_f32_e32 v8, v8, v148
	v_mul_f32_e32 v9, v9, v148
	v_mul_f32_e32 v6, v6, v148
	v_mul_f32_e32 v7, v7, v148
	v_mul_f32_e32 v4, v4, v148
	v_mul_f32_e32 v5, v5, v148
	v_mul_f32_e32 v2, v2, v148
	v_mul_f32_e32 v3, v3, v148
	v_mul_f32_e32 v113, v113, v148
; DI unsigned pk2(float a, float b) { f32x2 v = {a, b}; bf2_t r = __builtin_convertvector(v, bf2_t); return __builtin_bit_cast(unsigned, r); }
; #define PV_TILE64_(T) do { TRV8_192_T##T(R, vaddr); \
;           _Pragma("unroll") for (int st = 0; st < 2; ++st) _Pragma("unroll") for (int s = 0; s < 2; ++s) { const int ix = (st * 2 + s) * 2; \
;             const bf16x8 va = __builtin_shufflevector(R[ix], R[ix + 1], 0, 1, 2, 3, 4, 5, 6, 7); O[T] = mfma32(va, pf[st][s], O[T]); } } while (0)
; template <int DQK, int DV, int KW0, int MODE> ...
;     ...
;     const float mn = fmaxf(m, mx);
;     const bool grow = __builtin_amdgcn_ballot_w64(mx > m) != 0ull;
;     const float alpha = __builtin_amdgcn_exp2f((m - mn) * c);
;     m = mn;
;     const float mc = mn * c;
;     float ps = 0.f;
; #pragma unroll
;     for (int e = 0; e < 16; ++e) { S0[e] = __builtin_amdgcn_exp2f(S0[e] * c - mc); ps += S0[e]; }
; #pragma unroll
;     for (int e = 0; e < 16; ++e) { S1[e] = __builtin_amdgcn_exp2f(S1[e] * c - mc); ps += S1[e]; }
;     if (grow) {
;       l *= alpha;
; #pragma unroll
;       for (int t = 0; t < DV / 32; ++t)
; #pragma unroll
;         for (int e = 0; e < 16; ++e) O[t][e] *= alpha;
;     }
;     l += ps;
;     bf16x8 pf[2][2];
; #pragma unroll
;     for (int s = 0; s < 2; ++s) {
;       u32x4 w0, w1;
;       w0.x = pk2(S0[8 * s + 0], S0[8 * s + 1]); w0.y = pk2(S0[8 * s + 2], S0[8 * s + 3]); w0.z = pk2(S0[8 * s + 4], S0[8 * s + 5]); w0.w = pk2(S0[8 * s + 6], S0[8 * s + 7]);
;       w1.x = pk2(S1[8 * s + 0], S1[8 * s + 1]); w1.y = pk2(S1[8 * s + 2], S1[8 * s + 3]); w1.z = pk2(S1[8 * s + 4], S1[8 * s + 5]); w1.w = pk2(S1[8 * s + 6], S1[8 * s + 7]);
;       pf[0][s] = __builtin_bit_cast(bf16x8, w0); pf[1][s] = __builtin_bit_cast(bf16x8, w1);
;     }
;     {
;       const unsigned vaddr = (unsigned)(size_t)(cur + KB) + (unsigned)((4 * h + ((lane & 15) >> 2)) * VSB + ((lane >> 4) & 1) * 32 + (lane & 3) * 8);
;       if (DV == 64) {
;         s16x4 R[8];
;     ...
;         PV_TILE64_(0); PV_TILE64_(1);
;     ...
;       } else {
;         s16x4 R[8];
;     ...
;         PV_TILE_(0); PV_TILE_(1); PV_TILE_(2); PV_TILE_(3);
;     ...
;       }
;     }
;     if (DV > 64) { __builtin_amdgcn_sched_barrier(0); if (more) attn_gload<DQK, DV, KW0, 3>(kreg, vreg, k0p, ldk0, k1p, ldk1, vp, ldv, key_tile_row<MODE>(it + 1, b, qn, wlo), tid); }
;     if (more) attn_sstore<DQK, DV>(kreg, vreg, smem + ((it + 1) & 1) * STG, tid);
.LBB0_119:
	v_mov_b32_e32 v148, v65
	v_mul_f32_e64 v150, v148, s30
	v_mul_f32_e64 v151, v149, s30
	s_lshl_b32 s14, s18, 11
	v_fma_f32 v50, v50, s30, -v151
	v_exp_f32_e32 v50, v50
	v_fma_f32 v51, v51, s30, -v151
	v_exp_f32_e32 v51, v51
	v_fma_f32 v52, v52, s30, -v151
	v_exp_f32_e32 v52, v52
	v_fma_f32 v53, v53, s30, -v151
	v_exp_f32_e32 v53, v53
	v_fma_f32 v54, v54, s30, -v151
	v_exp_f32_e32 v54, v54
	v_fma_f32 v55, v55, s30, -v151
	v_add_f32_e32 v148, 0, v50
	v_exp_f32_e32 v55, v55
	v_fma_f32 v56, v56, s30, -v151
	v_add_f32_e32 v148, v51, v148
	v_exp_f32_e32 v56, v56
	v_fma_f32 v57, v57, s30, -v151
	v_add_f32_e32 v148, v52, v148
	v_exp_f32_e32 v57, v57
	v_fma_f32 v58, v58, s30, -v151
	v_add_f32_e32 v148, v53, v148
	v_exp_f32_e32 v58, v58
	v_fma_f32 v59, v59, s30, -v151
	v_add_f32_e32 v148, v54, v148
	v_exp_f32_e32 v59, v59
	v_fma_f32 v60, v60, s30, -v151
	v_add_f32_e32 v148, v55, v148
	v_exp_f32_e32 v60, v60
	v_fma_f32 v61, v61, s30, -v151
	v_add_f32_e32 v148, v56, v148
	v_exp_f32_e32 v61, v61
	v_fma_f32 v62, v62, s30, -v151
	v_add_f32_e32 v148, v57, v148
	v_exp_f32_e32 v62, v62
	v_fma_f32 v63, v63, s30, -v151
	v_add_f32_e32 v148, v58, v148
	v_exp_f32_e32 v63, v63
	v_fma_f32 v64, v64, s30, -v151
	v_add_f32_e32 v148, v59, v148
	v_exp_f32_e32 v64, v64
	v_sub_f32_e32 v65, v150, v151
	v_add_f32_e32 v148, v60, v148
	v_exp_f32_e32 v65, v65
	v_add_f32_e32 v148, v61, v148
	v_fma_f32 v34, v34, s30, -v151
	v_add_f32_e32 v148, v62, v148
	v_exp_f32_e32 v34, v34
	v_fma_f32 v35, v35, s30, -v151
	v_add_f32_e32 v148, v63, v148
	v_exp_f32_e32 v35, v35
	v_fma_f32 v36, v36, s30, -v151
	v_add_f32_e32 v148, v64, v148
	v_exp_f32_e32 v36, v36
	v_fma_f32 v37, v37, s30, -v151
	v_add_f32_e32 v148, v65, v148
	v_exp_f32_e32 v37, v37
	v_fma_f32 v38, v38, s30, -v151
	v_add_f32_e32 v148, v34, v148
	v_exp_f32_e32 v150, v38
	v_add_f32_e32 v148, v35, v148
	v_add_f32_e32 v148, v36, v148
	v_add_f32_e32 v148, v37, v148
	v_fma_f32 v39, v39, s30, -v151
	v_add_f32_e32 v38, v150, v148
	v_exp_f32_e32 v148, v39
	v_fma_f32 v39, v40, s30, -v151
	v_exp_f32_e32 v175, v39
	v_fma_f32 v39, v41, s30, -v151
	v_exp_f32_e32 v41, v39
	v_fma_f32 v39, v42, s30, -v151
	v_exp_f32_e32 v176, v39
	v_fma_f32 v39, v43, s30, -v151
	v_exp_f32_e32 v177, v39
	v_fma_f32 v39, v44, s30, -v151
	v_exp_f32_e32 v178, v39
	v_fma_f32 v39, v45, s30, -v151
	v_exp_f32_e32 v179, v39
	v_fma_f32 v39, v46, s30, -v151
	v_exp_f32_e32 v180, v39
	v_fma_f32 v39, v47, s30, -v151
	v_exp_f32_e32 v181, v39
	v_fma_f32 v39, v48, s30, -v151
	v_exp_f32_e32 v182, v39
	v_fma_f32 v39, v49, s30, -v151
	v_cvt_pk_bf16_f32 v46, v50, v51
	v_cvt_pk_bf16_f32 v47, v52, v53
	v_cvt_pk_bf16_f32 v48, v54, v55
	v_cvt_pk_bf16_f32 v49, v56, v57
	v_cvt_pk_bf16_f32 v42, v58, v59
	v_cvt_pk_bf16_f32 v43, v60, v61
	v_cvt_pk_bf16_f32 v44, v62, v63
	v_cvt_pk_bf16_f32 v45, v64, v65
	ds_read_b64_tr_b16 v[62:63], v168 offset:0
	ds_read_b64_tr_b16 v[64:65], v168 offset:1536
	ds_read_b64_tr_b16 v[58:59], v168 offset:3072
	ds_read_b64_tr_b16 v[60:61], v168 offset:4608
	ds_read_b64_tr_b16 v[54:55], v168 offset:6144
	ds_read_b64_tr_b16 v[56:57], v168 offset:7680
	ds_read_b64_tr_b16 v[50:51], v168 offset:9216
	ds_read_b64_tr_b16 v[52:53], v168 offset:10752
	s_waitcnt lgkmcnt(0)
	v_add_f32_e32 v38, v148, v38
	v_mfma_f32_32x32x16_bf16 v[2:17], v[62:65], v[46:49], v[2:17]
	v_add_f32_e32 v38, v175, v38
	v_add_f32_e32 v38, v41, v38
	v_add_f32_e32 v38, v176, v38
	v_add_f32_e32 v38, v177, v38
	v_add_f32_e32 v38, v178, v38
	v_add_f32_e32 v38, v179, v38
	v_exp_f32_e32 v151, v39
	v_mfma_f32_32x32x16_bf16 v[2:17], v[58:61], v[42:45], v[2:17]
	v_add_f32_e32 v38, v180, v38
	v_add_f32_e32 v38, v181, v38
	v_add_f32_e32 v38, v182, v38
	v_add_f32_e32 v183, v151, v38
	v_cvt_pk_bf16_f32 v38, v34, v35
	v_cvt_pk_bf16_f32 v39, v36, v37
	v_cvt_pk_bf16_f32 v40, v150, v148
	v_cvt_pk_bf16_f32 v41, v175, v41
	v_cvt_pk_bf16_f32 v34, v176, v177
	v_cvt_pk_bf16_f32 v35, v178, v179
	v_mfma_f32_32x32x16_bf16 v[2:17], v[54:57], v[38:41], v[2:17]
	v_cvt_pk_bf16_f32 v36, v180, v181
	v_cvt_pk_bf16_f32 v37, v182, v151
	v_add_f32_e32 v113, v183, v113
	s_mov_b32 s46, 3
	v_mfma_f32_32x32x16_bf16 v[2:17], v[50:53], v[34:37], v[2:17]
	ds_read_b64_tr_b16 v[62:63], v168 offset:64
	ds_read_b64_tr_b16 v[64:65], v168 offset:1600
	ds_read_b64_tr_b16 v[58:59], v168 offset:3136
	ds_read_b64_tr_b16 v[60:61], v168 offset:4672
	ds_read_b64_tr_b16 v[54:55], v168 offset:6208
	ds_read_b64_tr_b16 v[56:57], v168 offset:7744
	ds_read_b64_tr_b16 v[50:51], v168 offset:9280
	ds_read_b64_tr_b16 v[52:53], v168 offset:10816
	s_waitcnt lgkmcnt(0)
	s_waitcnt vmcnt(4)
	ds_write_b128 v170, v[90:93] offset:25600
	s_waitcnt vmcnt(3)
	ds_write_b128 v171, v[94:97] offset:25600
	s_waitcnt vmcnt(2)
	ds_write_b128 v172, v[98:101] offset:25600
	s_waitcnt vmcnt(1)
	ds_write_b128 v173, v[102:105] offset:38912
	s_waitcnt vmcnt(0)
	ds_write_b128 v173, v[106:109] offset:39104
	s_waitcnt lgkmcnt(0)
	s_barrier
	v_mfma_f32_32x32x16_bf16 v[18:33], v[62:65], v[46:49], v[18:33]
	v_mfma_f32_32x32x16_bf16 v[18:33], v[58:61], v[42:45], v[18:33]
	v_mfma_f32_32x32x16_bf16 v[18:33], v[54:57], v[38:41], v[18:33]
	v_mfma_f32_32x32x16_bf16 v[18:33], v[50:53], v[34:37], v[18:33]

; DI f32x16 mfma32(bf16x8 a, bf16x8 b, f32x16 c) { return __builtin_amdgcn_mfma_f32_32x32x16_bf16(a, b, c, 0, 0, 0); }
; DI int crow(int reg, int h) { return (reg & 3) + 8 * (reg >> 2) + 4 * h; }
; template <int DQK, int DV, int KW0, int MODE> ...
;     ...
;       bf16x8 kfa[DQK / 16], kfb[DQK / 16], qv[DQK / 16];
; #pragma unroll
;       for (int kk = 0; kk < DQK / 16; ++kk) {
;         kfa[kk] = *(const bf16x8*)(cur + r * (KS * 2) + kk * 32 + h * 16);
;         kfb[kk] = *(const bf16x8*)(cur + (32 + r) * (KS * 2) + kk * 32 + h * 16);
;         qv[kk] = QLDS ? *(const bf16x8*)(qbase + kk * 1024) : qf[kk];
;       }
; #pragma unroll
;       for (int kk = 0; kk < DQK / 16; ++kk) {
;         S0 = mfma32(kfa[kk], qv[kk], S0);
;         S1 = mfma32(kfb[kk], qv[kk], S1);
;       }
;       __builtin_amdgcn_sched_group_barrier(0x100, (QLDS ? 3 : 2) * (DQK / 16), 0);
;       __builtin_amdgcn_sched_group_barrier(0x008, 2 * (DQK / 16), 0);
;     }
;     if (MODE == 2) {
;       if (it >= 4) {
;         const int w = wlo + it - 4;
;         if (w < 2 || w > 3) {
;           const int kpos0 = (qn - 1) * 128 + 64 * w, qpos = qn * 128 + wid * 32 + r;
; #pragma unroll
;           for (int e = 0; e < 16; ++e) {
;             const int d0 = qpos - (kpos0 + crow(e, h)), d1 = d0 - 32;
;             if (d0 > 128 || d0 < -128) S0[e] = -1e30f;
;             if (d1 > 128 || d1 < -128) S1[e] = -1e30f;
;           }
;         }
;       }
;     }
;     float mx = S0[0];
; #pragma unroll
;     for (int e = 1; e < 16; ++e) mx = fmaxf(mx, S0[e]);
; #pragma unroll
;     for (int e = 0; e < 16; ++e) mx = fmaxf(mx, S1[e]);
;     mx = fmaxf(mx, __shfl_xor(mx, 32));
;     const float mn = fmaxf(m, mx);
;     const bool grow = __builtin_amdgcn_ballot_w64(mx > m) != 0ull;
;     const float alpha = __builtin_amdgcn_exp2f((m - mn) * c);
;     m = mn;
;     const float mc = mn * c;
;     float ps = 0.f;
; #pragma unroll
;     for (int e = 0; e < 16; ++e) { S0[e] = __builtin_amdgcn_exp2f(S0[e] * c - mc); ps += S0[e]; }
; #pragma unroll
;     for (int e = 0; e < 16; ++e) { S1[e] = __builtin_amdgcn_exp2f(S1[e] * c - mc); ps += S1[e]; }
;     if (grow) {
;       l *= alpha;
; #pragma unroll
;       for (int t = 0; t < DV / 32; ++t)
; #pragma unroll
;         for (int e = 0; e < 16; ++e) O[t][e] *= alpha;
.LBB0_134:
	s_bitcmp1_b32 s46, 0
	s_cselect_b32 s10, 0x6400, 0
	s_add_i32 s15, s10, 16
	v_add3_u32 v50, s15, v164, v165
	ds_read_b128 v[38:41], v50
	ds_read_b128 v[42:45], v50 offset:32
	ds_read_b128 v[34:37], v50 offset:6656
	ds_read_b128 v[176:179], v50 offset:6688
	ds_read_b128 v[46:49], v50 offset:64
	ds_read_b128 v[180:183], v50 offset:6720
	ds_read_b128 v[192:195], v50 offset:96
	ds_read_b128 v[218:221], v50 offset:6752
	ds_read_b128 v[222:225], v50 offset:128
	ds_read_b128 v[226:229], v50 offset:6784
	ds_read_b128 v[230:233], v50 offset:160
	ds_read_b128 v[234:237], v50 offset:6816
	s_setprio 1
	s_waitcnt lgkmcnt(11)
	v_mfma_f32_32x32x16_bf16 v[50:65], v[38:41], v[66:69], 0
	s_waitcnt lgkmcnt(10)
	v_mfma_f32_32x32x16_bf16 v[50:65], v[42:45], v[70:73], v[50:65]
	s_waitcnt lgkmcnt(7)
	v_mfma_f32_32x32x16_bf16 v[50:65], v[46:49], v[74:77], v[50:65]
	v_mfma_f32_32x32x16_bf16 v[34:49], v[34:37], v[66:69], 0
	v_mfma_f32_32x32x16_bf16 v[34:49], v[176:179], v[70:73], v[34:49]
	s_waitcnt lgkmcnt(5)
	v_mfma_f32_32x32x16_bf16 v[50:65], v[192:195], v[78:81], v[50:65]
	v_mfma_f32_32x32x16_bf16 v[34:49], v[180:183], v[74:77], v[34:49]
	s_waitcnt lgkmcnt(3)
	v_mfma_f32_32x32x16_bf16 v[50:65], v[222:225], v[82:85], v[50:65]
	v_mfma_f32_32x32x16_bf16 v[34:49], v[218:221], v[78:81], v[34:49]
	s_waitcnt lgkmcnt(1)
	v_mfma_f32_32x32x16_bf16 v[50:65], v[230:233], v[86:89], v[50:65]
	v_mfma_f32_32x32x16_bf16 v[34:49], v[226:229], v[82:85], v[34:49]
	s_nop 10
	v_max_f32_e32 v148, v51, v51
	v_max_f32_e32 v150, v50, v50
	v_max_f32_e32 v148, v150, v148
	v_max3_f32 v148, v148, v52, v53
	v_max3_f32 v148, v148, v54, v55
	v_max3_f32 v148, v148, v56, v57
	v_max3_f32 v148, v148, v58, v59
	s_waitcnt lgkmcnt(0)
	v_mfma_f32_32x32x16_bf16 v[34:49], v[234:237], v[86:89], v[34:49]
	s_setprio 0
	v_max3_f32 v148, v148, v60, v61
	v_max3_f32 v148, v148, v62, v63
	v_max3_f32 v148, v148, v64, v65
	s_nop 8
	v_max3_f32 v148, v148, v34, v35
	v_max3_f32 v148, v148, v36, v37
	v_max3_f32 v148, v148, v38, v39
	v_max3_f32 v148, v148, v40, v41
	v_max3_f32 v148, v148, v42, v43
	v_max3_f32 v148, v148, v44, v45
	v_max3_f32 v148, v148, v46, v47
	v_max3_f32 v148, v148, v48, v49
	ds_bpermute_b32 v150, v166, v148
	s_waitcnt lgkmcnt(0)
	v_max_f32_e32 v150, v150, v150
	v_max_f32_e32 v148, v148, v150
	v_max_f32_e32 v150, v149, v149
	v_max_f32_e32 v151, v150, v148
	v_cmp_gt_f32_e32 vcc, v148, v149
	s_cbranch_vccz .LBB0_136
	v_sub_f32_e32 v148, v149, v151
	v_mul_f32_e32 v148, 0x3e16c740, v148
	v_exp_f32_e32 v148, v148
	s_nop 0
	v_mul_f32_e32 v32, v32, v148
	v_mul_f32_e32 v33, v33, v148
	v_mul_f32_e32 v30, v30, v148
	v_mul_f32_e32 v31, v31, v148
	v_mul_f32_e32 v28, v28, v148
	v_mul_f32_e32 v29, v29, v148
	v_mul_f32_e32 v26, v26, v148
	v_mul_f32_e32 v27, v27, v148
	v_mul_f32_e32 v24, v24, v148
	v_mul_f32_e32 v25, v25, v148
	v_mul_f32_e32 v22, v22, v148
	v_mul_f32_e32 v23, v23, v148
	v_mul_f32_e32 v20, v20, v148
	v_mul_f32_e32 v21, v21, v148
	v_mul_f32_e32 v18, v18, v148
	v_mul_f32_e32 v19, v19, v148
	v_mul_f32_e32 v16, v16, v148
	v_mul_f32_e32 v17, v17, v148
	v_mul_f32_e32 v14, v14, v148
	v_mul_f32_e32 v15, v15, v148
	v_mul_f32_e32 v12, v12, v148
	v_mul_f32_e32 v13, v13, v148
	v_mul_f32_e32 v10, v10, v148
	v_mul_f32_e32 v11, v11, v148
	v_mul_f32_e32 v8, v8, v148
	v_mul_f32_e32 v9, v9, v148
	v_mul_f32_e32 v6, v6, v148
	v_mul_f32_e32 v7, v7, v148
	v_mul_f32_e32 v4, v4, v148
	v_mul_f32_e32 v5, v5, v148
	v_mul_f32_e32 v2, v2, v148
	v_mul_f32_e32 v3, v3, v148
	v_mul_f32_e32 v113, v113, v148
; DI unsigned pk2(float a, float b) { f32x2 v = {a, b}; bf2_t r = __builtin_convertvector(v, bf2_t); return __builtin_bit_cast(unsigned, r); }
; #define PV_TILE64_(T) do { TRV8_192_T##T(R, vaddr); \
;           _Pragma("unroll") for (int st = 0; st < 2; ++st) _Pragma("unroll") for (int s = 0; s < 2; ++s) { const int ix = (st * 2 + s) * 2; \
;             const bf16x8 va = __builtin_shufflevector(R[ix], R[ix + 1], 0, 1, 2, 3, 4, 5, 6, 7); O[T] = mfma32(va, pf[st][s], O[T]); } } while (0)
; template <int DQK, int DV, int KW0, int MODE> ...
;     ...
;     const float mn = fmaxf(m, mx);
;     const bool grow = __builtin_amdgcn_ballot_w64(mx > m) != 0ull;
;     const float alpha = __builtin_amdgcn_exp2f((m - mn) * c);
;     m = mn;
;     const float mc = mn * c;
;     float ps = 0.f;
; #pragma unroll
;     for (int e = 0; e < 16; ++e) { S0[e] = __builtin_amdgcn_exp2f(S0[e] * c - mc); ps += S0[e]; }
; #pragma unroll
;     for (int e = 0; e < 16; ++e) { S1[e] = __builtin_amdgcn_exp2f(S1[e] * c - mc); ps += S1[e]; }
;     if (grow) {
;       l *= alpha;
; #pragma unroll
;       for (int t = 0; t < DV / 32; ++t)
; #pragma unroll
;         for (int e = 0; e < 16; ++e) O[t][e] *= alpha;
;     }
;     l += ps;
;     bf16x8 pf[2][2];
; #pragma unroll
;     for (int s = 0; s < 2; ++s) {
;       u32x4 w0, w1;
;       w0.x = pk2(S0[8 * s + 0], S0[8 * s + 1]); w0.y = pk2(S0[8 * s + 2], S0[8 * s + 3]); w0.z = pk2(S0[8 * s + 4], S0[8 * s + 5]); w0.w = pk2(S0[8 * s + 6], S0[8 * s + 7]);
;       w1.x = pk2(S1[8 * s + 0], S1[8 * s + 1]); w1.y = pk2(S1[8 * s + 2], S1[8 * s + 3]); w1.z = pk2(S1[8 * s + 4], S1[8 * s + 5]); w1.w = pk2(S1[8 * s + 6], S1[8 * s + 7]);
;       pf[0][s] = __builtin_bit_cast(bf16x8, w0); pf[1][s] = __builtin_bit_cast(bf16x8, w1);
;     }
;     {
;       const unsigned vaddr = (unsigned)(size_t)(cur + KB) + (unsigned)((4 * h + ((lane & 15) >> 2)) * VSB + ((lane >> 4) & 1) * 32 + (lane & 3) * 8);
;       if (DV == 64) {
;         s16x4 R[8];
;     ...
;         PV_TILE64_(0); PV_TILE64_(1);
;     ...
;       } else {
;         s16x4 R[8];
;     ...
;         PV_TILE_(0); PV_TILE_(1); PV_TILE_(2); PV_TILE_(3);
;     ...
;       }
;     }
;     if (DV > 64) { __builtin_amdgcn_sched_barrier(0); if (more) attn_gload<DQK, DV, KW0, 3>(kreg, vreg, k0p, ldk0, k1p, ldk1, vp, ldv, key_tile_row<MODE>(it + 1, b, qn, wlo), tid); }
;     if (more) attn_sstore<DQK, DV>(kreg, vreg, smem + ((it + 1) & 1) * STG, tid);
.LBB0_136:
	v_mov_b32_e32 v150, v65
	v_mul_f32_e64 v148, v150, s30
	v_mul_f32_e64 v149, v151, s30
	s_addk_i32 s15, 0x3400
	v_fma_f32 v50, v50, s30, -v149
	v_fma_f32 v51, v51, s30, -v149
	v_fma_f32 v52, v52, s30, -v149
	v_fma_f32 v53, v53, s30, -v149
	v_fma_f32 v54, v54, s30, -v149
	v_fma_f32 v55, v55, s30, -v149
	v_fma_f32 v56, v56, s30, -v149
	v_fma_f32 v57, v57, s30, -v149
	v_exp_f32_e32 v50, v50
	v_exp_f32_e32 v51, v51
	v_exp_f32_e32 v52, v52
	v_exp_f32_e32 v53, v53
	v_exp_f32_e32 v54, v54
	v_exp_f32_e32 v55, v55
	v_exp_f32_e32 v56, v56
	v_exp_f32_e32 v57, v57
	v_cvt_pk_bf16_f32 v176, v50, v51
	v_cvt_pk_bf16_f32 v177, v52, v53
	v_cvt_pk_bf16_f32 v178, v54, v55
	v_cvt_pk_bf16_f32 v179, v56, v57
	v_sub_f32_e32 v65, v148, v149
	v_add_u32_e32 v148, s15, v167
	s_setprio 1
	ds_read_b64_tr_b16 v[234:235], v148 offset:0
	ds_read_b64_tr_b16 v[236:237], v148 offset:1536
	ds_read_b64_tr_b16 v[230:231], v148 offset:3072
	ds_read_b64_tr_b16 v[232:233], v148 offset:4608
	ds_read_b64_tr_b16 v[226:227], v148 offset:6144
	ds_read_b64_tr_b16 v[228:229], v148 offset:7680
	ds_read_b64_tr_b16 v[222:223], v148 offset:9216
	ds_read_b64_tr_b16 v[224:225], v148 offset:10752
	s_waitcnt lgkmcnt(0)
	v_fma_f32 v58, v58, s30, -v149
	v_mfma_f32_32x32x16_bf16 v[2:17], v[234:237], v[176:179], v[2:17]
	v_fma_f32 v59, v59, s30, -v149
	v_fma_f32 v60, v60, s30, -v149
	v_fma_f32 v61, v61, s30, -v149
	v_fma_f32 v62, v62, s30, -v149
	v_fma_f32 v63, v63, s30, -v149
	v_fma_f32 v64, v64, s30, -v149
	v_exp_f32_e32 v58, v58
	v_exp_f32_e32 v59, v59
	v_exp_f32_e32 v60, v60
	v_exp_f32_e32 v61, v61
	v_exp_f32_e32 v62, v62
	v_exp_f32_e32 v63, v63
	v_exp_f32_e32 v64, v64
	v_exp_f32_e32 v65, v65
	v_cvt_pk_bf16_f32 v192, v58, v59
	v_cvt_pk_bf16_f32 v193, v60, v61
	v_cvt_pk_bf16_f32 v194, v62, v63
	v_cvt_pk_bf16_f32 v195, v64, v65
	v_fma_f32 v34, v34, s30, -v149
	v_fma_f32 v35, v35, s30, -v149
	v_mfma_f32_32x32x16_bf16 v[2:17], v[230:233], v[192:195], v[2:17]
	v_fma_f32 v36, v36, s30, -v149
	v_fma_f32 v37, v37, s30, -v149
	v_fma_f32 v38, v38, s30, -v149
	v_fma_f32 v39, v39, s30, -v149
	v_fma_f32 v40, v40, s30, -v149
	v_fma_f32 v41, v41, s30, -v149
	v_exp_f32_e32 v34, v34
	v_exp_f32_e32 v35, v35
	v_exp_f32_e32 v36, v36
	v_exp_f32_e32 v37, v37
	v_exp_f32_e32 v38, v38
	v_exp_f32_e32 v39, v39
	v_exp_f32_e32 v40, v40
	v_exp_f32_e32 v41, v41
	v_cvt_pk_bf16_f32 v180, v34, v35
	v_cvt_pk_bf16_f32 v181, v36, v37
	v_cvt_pk_bf16_f32 v182, v38, v39
	v_cvt_pk_bf16_f32 v183, v40, v41
	v_fma_f32 v42, v42, s30, -v149
	v_fma_f32 v43, v43, s30, -v149
	v_mfma_f32_32x32x16_bf16 v[2:17], v[226:229], v[180:183], v[2:17]
	v_fma_f32 v44, v44, s30, -v149
	v_fma_f32 v45, v45, s30, -v149
	v_fma_f32 v46, v46, s30, -v149
	v_fma_f32 v47, v47, s30, -v149
	v_fma_f32 v48, v48, s30, -v149
	v_fma_f32 v49, v49, s30, -v149
	v_exp_f32_e32 v42, v42
	v_exp_f32_e32 v43, v43
	v_exp_f32_e32 v44, v44
	v_exp_f32_e32 v45, v45
	v_exp_f32_e32 v46, v46
	v_exp_f32_e32 v47, v47
	v_exp_f32_e32 v48, v48
	v_exp_f32_e32 v49, v49
	v_cvt_pk_bf16_f32 v218, v42, v43
	v_cvt_pk_bf16_f32 v219, v44, v45
	v_cvt_pk_bf16_f32 v220, v46, v47
	v_cvt_pk_bf16_f32 v221, v48, v49
	s_andn2_b64 vcc, exec, s[16:17]
	s_nop 0
	v_mfma_f32_32x32x16_bf16 v[2:17], v[222:225], v[218:221], v[2:17]
	ds_read_b64_tr_b16 v[234:235], v148 offset:64
	ds_read_b64_tr_b16 v[236:237], v148 offset:1600
	ds_read_b64_tr_b16 v[230:231], v148 offset:3136
	ds_read_b64_tr_b16 v[232:233], v148 offset:4672
	ds_read_b64_tr_b16 v[226:227], v148 offset:6208
	ds_read_b64_tr_b16 v[228:229], v148 offset:7744
	ds_read_b64_tr_b16 v[222:223], v148 offset:9280
	ds_read_b64_tr_b16 v[224:225], v148 offset:10816
	s_waitcnt lgkmcnt(0)
	s_nop 0
	v_mfma_f32_32x32x16_bf16 v[18:33], v[234:237], v[176:179], v[18:33]
	v_mfma_f32_32x32x16_bf16 v[18:33], v[230:233], v[192:195], v[18:33]
	v_mfma_f32_32x32x16_bf16 v[18:33], v[226:229], v[180:183], v[18:33]
	v_mfma_f32_32x32x16_bf16 v[18:33], v[222:225], v[218:221], v[18:33]
	s_setprio 0
	s_cbranch_vccnz .LBB0_138
	s_bitcmp1_b32 s29, 0
	s_cselect_b32 s10, 0x6400, 0
	s_add_i32 s10, s10, 16
	v_add3_u32 v148, s10, v156, v157
	s_waitcnt vmcnt(4)
	ds_write_b128 v148, v[90:93]
	v_add3_u32 v148, s10, v158, v159
	s_waitcnt vmcnt(3)
	ds_write_b128 v148, v[94:97]
	v_add3_u32 v148, s10, v160, v161
	s_waitcnt vmcnt(2)
	ds_write_b128 v148, v[98:101]
	v_add3_u32 v148, s10, v163, v155
	s_waitcnt vmcnt(1)
	ds_write_b128 v148, v[102:105] offset:13312
	s_waitcnt vmcnt(0)
	ds_write_b128 v148, v[106:109] offset:13504

; #define GAS __attribute__((address_space(1)))
; DI unsigned pk2(float a, float b) { f32x2 v = {a, b}; bf2_t r = __builtin_convertvector(v, bf2_t); return __builtin_bit_cast(unsigned, r); }
; DI float bflo(unsigned w) { return __uint_as_float(w << 16); }
; DI float bfhi(unsigned w) { return __uint_as_float(w & 0xffff0000u); }
; DI float siluf(float v) { return v * __builtin_amdgcn_rcpf(1.f + __builtin_amdgcn_exp2f(-1.4426950408889634f * v)); }
;     ...
;         const char* base = smem + r * 528 + (p * 128 + j8) * 2;
;         const u32x4 zz = {0u, 0u, 0u, 0u};
;         const u32x4 pa = top ? zz : *(const u32x4*)(base - 528), ca = *(const u32x4*)base, na = bot ? zz : *(const u32x4*)(base + 528);
;         const u32x4 pg = top ? zz : *(const u32x4*)(base - 528 + 128), cg = *(const u32x4*)(base + 128), ng = bot ? zz : *(const u32x4*)(base + 528 + 128);
;         unsigned resw[4];
; #pragma unroll
;         for (int q = 0; q < 4; ++q) {
;           const int hh = q >> 1, e0 = (q & 1) * 2;
;           const float ua0 = wa[0][hh][e0] * bflo(pa[q]) + wa[1][hh][e0] * bflo(ca[q]) + wa[2][hh][e0] * bflo(na[q]) + wa[3][hh][e0];
;           const float ua1 = wa[0][hh][e0 + 1] * bfhi(pa[q]) + wa[1][hh][e0 + 1] * bfhi(ca[q]) + wa[2][hh][e0 + 1] * bfhi(na[q]) + wa[3][hh][e0 + 1];
;           const float ug0 = wg[0][hh][e0] * bflo(pg[q]) + wg[1][hh][e0] * bflo(cg[q]) + wg[2][hh][e0] * bflo(ng[q]) + wg[3][hh][e0];
;           const float ug1 = wg[0][hh][e0 + 1] * bfhi(pg[q]) + wg[1][hh][e0 + 1] * bfhi(cg[q]) + wg[2][hh][e0 + 1] * bfhi(ng[q]) + wg[3][hh][e0 + 1];
;           resw[q] = pk2(siluf(ug0) * ua0, siluf(ug1) * ua1);
;         }
;         u32x4 w; w.x = resw[0]; w.y = resw[1]; w.z = resw[2]; w.w = resw[3];
;         __builtin_nontemporal_store(w, (GAS u32x4*)(ea.out + (size_t)(m0 + r) * 2816 + ja0 + j8));
.LBB0_276:
	s_or_b64 exec, exec, s[40:41]
	s_waitcnt lgkmcnt(1)
	v_lshlrev_b32_e32 v100, 16, v78
	v_and_b32_e32 v101, 0xffff0000, v78
	v_lshlrev_b32_e32 v78, 16, v79
	v_and_b32_e32 v79, 0xffff0000, v79
	v_lshlrev_b32_e32 v94, 16, v70
	v_and_b32_e32 v95, 0xffff0000, v70
	v_mul_f32_e32 v100, v10, v100
	v_mul_f32_e32 v101, v11, v101
	v_lshlrev_b32_e32 v70, 16, v71
	v_and_b32_e32 v71, 0xffff0000, v71
	v_mul_f32_e32 v78, v12, v78
	v_mul_f32_e32 v79, v13, v79
	v_fma_f32 v94, v2, v94, v100
	v_fma_f32 v95, v3, v95, v101
	v_lshlrev_b32_e32 v100, 16, v66
	v_and_b32_e32 v101, 0xffff0000, v66
	v_fma_f32 v70, v4, v70, v78
	v_fma_f32 v71, v5, v71, v79
	v_lshlrev_b32_e32 v78, 16, v67
	v_and_b32_e32 v79, 0xffff0000, v67
	v_fma_f32 v94, v18, v100, v94
	v_fma_f32 v95, v19, v101, v95
	v_lshlrev_b32_e32 v100, 16, v82
	v_and_b32_e32 v101, 0xffff0000, v82
	s_waitcnt lgkmcnt(0)
	v_lshlrev_b32_e32 v102, 16, v86
	v_and_b32_e32 v103, 0xffff0000, v86
	v_fma_f32 v70, v20, v78, v70
	v_fma_f32 v71, v21, v79, v71
	v_lshlrev_b32_e32 v78, 16, v83
	v_and_b32_e32 v79, 0xffff0000, v83
	v_lshlrev_b32_e32 v82, 16, v87
	v_and_b32_e32 v83, 0xffff0000, v87
	v_mul_f32_e32 v102, v42, v102
	v_mul_f32_e32 v103, v43, v103
	v_mul_f32_e32 v82, v44, v82
	v_mul_f32_e32 v83, v45, v83
	v_fma_f32 v100, v34, v100, v102
	v_fma_f32 v101, v35, v101, v103
	v_lshlrev_b32_e32 v102, 16, v74
	v_and_b32_e32 v103, 0xffff0000, v74
	v_fma_f32 v78, v36, v78, v82
	v_fma_f32 v79, v37, v79, v83
	v_lshlrev_b32_e32 v74, 16, v75
	v_and_b32_e32 v75, 0xffff0000, v75
	v_fma_f32 v74, v52, v74, v78
	v_fma_f32 v75, v53, v75, v79
	v_add_f32_e32 v70, v28, v70
	v_add_f32_e32 v71, v29, v71
	v_add_f32_e32 v74, v60, v74
	v_add_f32_e32 v75, v61, v75
	v_fma_f32 v100, v50, v102, v100
	v_fma_f32 v101, v51, v103, v101
	v_mul_f32_e32 v67, 0xbfb8aa3b, v74
	v_exp_f32_e32 v67, v67
	v_add_f32_e32 v100, v58, v100
	v_add_f32_e32 v101, v59, v101
	v_add_f32_e32 v94, v26, v94
	v_add_f32_e32 v95, v27, v95
	v_mul_f32_e32 v66, 0xbfb8aa3b, v100
	v_add_f32_e32 v67, 1.0, v67
	v_rcp_f32_e32 v78, v67
	v_mul_f32_e32 v67, 0xbfb8aa3b, v75
	v_exp_f32_e32 v67, v67
	v_exp_f32_e32 v66, v66
	s_movk_i32 s10, 0x1600
	v_add_f32_e32 v67, 1.0, v67
	v_rcp_f32_e32 v79, v67
	v_add_f32_e32 v66, 1.0, v66
	v_rcp_f32_e32 v102, v66
	v_mul_f32_e32 v66, 0xbfb8aa3b, v101
	v_mul_f32_e32 v74, v74, v78
	v_mul_f32_e32 v75, v75, v79
	v_lshlrev_b32_e32 v78, 16, v88
	v_mul_f32_e32 v70, v70, v74
	v_mul_f32_e32 v71, v71, v75
	v_lshlrev_b32_e32 v74, 16, v80
	v_and_b32_e32 v75, 0xffff0000, v80
	v_cvt_pk_bf16_f32 v67, v70, v71
	v_lshlrev_b32_e32 v70, 16, v72
	v_and_b32_e32 v71, 0xffff0000, v72
	v_mul_f32_e32 v74, v14, v74
	v_mul_f32_e32 v75, v15, v75
	v_and_b32_e32 v79, 0xffff0000, v88
	v_fma_f32 v70, v6, v70, v74
	v_fma_f32 v71, v7, v71, v75
	v_lshlrev_b32_e32 v74, 16, v68
	v_and_b32_e32 v75, 0xffff0000, v68
	v_fma_f32 v70, v22, v74, v70
	v_fma_f32 v71, v23, v75, v71
	v_lshlrev_b32_e32 v74, 16, v84
	v_and_b32_e32 v75, 0xffff0000, v84
	v_mul_f32_e32 v78, v46, v78
	v_mul_f32_e32 v79, v47, v79
	v_add_f32_e32 v70, v30, v70
	v_add_f32_e32 v71, v31, v71
	v_fma_f32 v74, v38, v74, v78
	v_fma_f32 v75, v39, v75, v79
	v_lshlrev_b32_e32 v78, 16, v76
	v_and_b32_e32 v79, 0xffff0000, v76
	v_fma_f32 v74, v54, v78, v74
	v_fma_f32 v75, v55, v79, v75
	v_lshlrev_b32_e32 v72, 16, v81
	v_add_f32_e32 v74, v62, v74
	v_add_f32_e32 v75, v63, v75
	v_exp_f32_e32 v66, v66
	v_mul_f32_e32 v68, 0xbfb8aa3b, v74
	v_exp_f32_e32 v68, v68
	v_add_f32_e32 v66, 1.0, v66
	v_rcp_f32_e32 v103, v66
	v_add_f32_e32 v68, 1.0, v68
	v_rcp_f32_e32 v78, v68
	v_mul_f32_e32 v68, 0xbfb8aa3b, v75
	v_exp_f32_e32 v68, v68
	v_mul_f32_e32 v100, v100, v102
	v_mul_f32_e32 v101, v101, v103
	v_add_f32_e32 v68, 1.0, v68
	v_rcp_f32_e32 v79, v68
	v_mul_f32_e32 v94, v94, v100
	v_mul_f32_e32 v95, v95, v101
	v_mul_f32_e32 v74, v74, v78
	v_mul_f32_e32 v75, v75, v79
	s_nop 0
	v_mul_f32_e32 v70, v70, v74
	v_mul_f32_e32 v71, v71, v75
	v_lshlrev_b32_e32 v74, 16, v89
	v_cvt_pk_bf16_f32 v68, v70, v71
	v_lshlrev_b32_e32 v70, 16, v73
	v_and_b32_e32 v71, 0xffff0000, v73
	v_and_b32_e32 v73, 0xffff0000, v81
	v_mul_f32_e32 v72, v16, v72
	v_mul_f32_e32 v73, v17, v73
	v_and_b32_e32 v75, 0xffff0000, v89
	v_fma_f32 v70, v8, v70, v72
	v_fma_f32 v71, v9, v71, v73
	v_lshlrev_b32_e32 v72, 16, v69
	v_and_b32_e32 v73, 0xffff0000, v69
	v_fma_f32 v70, v24, v72, v70
	v_fma_f32 v71, v25, v73, v71
	v_lshlrev_b32_e32 v72, 16, v85
	v_and_b32_e32 v73, 0xffff0000, v85
	v_mul_f32_e32 v74, v48, v74
	v_mul_f32_e32 v75, v49, v75
	v_add_f32_e32 v70, v32, v70
	v_add_f32_e32 v71, v33, v71
	v_fma_f32 v72, v40, v72, v74
	v_fma_f32 v73, v41, v73, v75
	v_lshlrev_b32_e32 v74, 16, v77
	v_and_b32_e32 v75, 0xffff0000, v77
	v_fma_f32 v72, v56, v74, v72
	v_fma_f32 v73, v57, v75, v73
	v_cvt_pk_bf16_f32 v66, v94, v95
	v_add_f32_e32 v72, v64, v72
	v_add_f32_e32 v73, v65, v73
	s_nop 0
	v_mul_f32_e32 v69, 0xbfb8aa3b, v72
	v_exp_f32_e32 v69, v69
	s_nop 0
	v_add_f32_e32 v69, 1.0, v69
	v_rcp_f32_e32 v74, v69
	v_mul_f32_e32 v69, 0xbfb8aa3b, v73
	v_exp_f32_e32 v69, v69
	s_nop 0
	v_add_f32_e32 v69, 1.0, v69
	v_rcp_f32_e32 v75, v69
	s_nop 0
	v_mul_f32_e32 v72, v72, v74
	v_mul_f32_e32 v73, v73, v75
	s_nop 0
	v_mul_f32_e32 v70, v70, v72
	v_mul_f32_e32 v71, v71, v73
	s_nop 0
	v_cvt_pk_bf16_f32 v69, v70, v71
	v_add_u32_e32 v70, s46, v98
	v_mad_i64_i32 v[70:71], s[10:11], v70, s10, v[92:93]
	global_store_dwordx4 v[70:71], v[66:69], off nt
